# ssd_out decay blocks: wave-uniform fast paths for blocks entirely below/above the diagonal (no selects, half the LDS reads) + previous
# speedup vs baseline: 1.0096x; 1.0045x over previous
.LBB0_740:
	s_or_b64 exec, exec, s[66:67]
	v_lshlrev_b32_e32 v54, 3, v168
	v_mov_b32_e32 v2, s46
	v_mov_b32_e32 v3, s45
	v_cndmask_b32_e32 v1, v5, v4, vcc
	v_cndmask_b32_e32 v2, v2, v3, vcc
	v_lshl_add_u32 v57, v54, 1, s23
	v_lshl_add_u32 v1, v1, 2, v2
	v_mad_u32_u24 v8, v52, s71, v57
	ds_write_b32 v1, v0
	s_waitcnt lgkmcnt(0)
	s_barrier
	ds_read_b128 v[0:3], v8 offset:17408
	ds_read_b128 v[4:7], v8 offset:17440
	s_waitcnt lgkmcnt(1)
	v_mfma_f32_32x32x16_bf16 v[24:39], v[0:3], v[48:51], 0
	v_lshlrev_b32_e32 v110, 2, v168
	v_cmp_ge_u32_e32 vcc, v110, v53
	s_waitcnt lgkmcnt(0)
	v_mfma_f32_32x32x16_bf16 v[24:39], v[4:7], v[102:105], v[24:39]
	ds_read_b128 v[0:3], v8 offset:17472
	ds_read_b128 v[4:7], v8 offset:17504
	s_waitcnt lgkmcnt(1)
	v_mfma_f32_32x32x16_bf16 v[24:39], v[0:3], v[98:101], v[24:39]
	v_lshl_add_u32 v0, v53, 2, s23
	ds_read2st64_b32 v[126:127], v0 offset0:140 offset1:142
	s_waitcnt lgkmcnt(1)
	v_mfma_f32_32x32x16_bf16 v[24:39], v[4:7], v[94:97], v[24:39]
	v_lshl_add_u32 v236, v110, 2, s23
	v_lshrrev_b32_e32 v239, 5, v53
	s_nop 0
	v_readfirstlane_b32 s0, v239
	s_cmp_gt_u32 s0, 0
	s_cbranch_scc1 .Lssdb0_lt
	s_cmp_lt_u32 s0, 0
	s_cbranch_scc1 .Lssdb0_gt
	v_sub_u32_e32 v237, v53, v110
	ds_read_b128 v[170:173], v236 offset:35840
	ds_read_b128 v[174:177], v236 offset:36352
	ds_read_b128 v[178:181], v236 offset:36864
	ds_read_b128 v[182:185], v236 offset:37376
	ds_read_b128 v[186:189], v236 offset:35872
	ds_read_b128 v[190:193], v236 offset:36384
	ds_read_b128 v[194:197], v236 offset:36896
	ds_read_b128 v[198:201], v236 offset:37408
	ds_read_b128 v[202:205], v236 offset:35904
	ds_read_b128 v[206:209], v236 offset:36416
	ds_read_b128 v[210:213], v236 offset:36928
	ds_read_b128 v[214:217], v236 offset:37440
	s_waitcnt lgkmcnt(8)
	ds_read_b128 v[218:221], v236 offset:35936
	ds_read_b128 v[222:225], v236 offset:36448
	ds_read_b128 v[226:229], v236 offset:36960
	ds_read_b128 v[230:233], v236 offset:37472
	v_mov_b32_e32 v238, v237
	v_cmp_lt_i32_e32 vcc, 0, v238
	v_cmp_lt_i32_e64 s[0:1], 1, v238
	v_cmp_lt_i32_e64 s[4:5], 2, v238
	v_cmp_lt_i32_e64 s[66:67], 3, v238
	v_sub_f32_e32 v170, v126, v170
	v_sub_f32_e32 v171, v126, v171
	v_sub_f32_e32 v172, v126, v172
	v_sub_f32_e32 v173, v126, v173
	v_sub_f32_e32 v174, v127, v174
	v_sub_f32_e32 v175, v127, v175
	v_sub_f32_e32 v176, v127, v176
	v_sub_f32_e32 v177, v127, v177
	v_cndmask_b32_e64 v170, v174, v170, vcc
	v_cndmask_b32_e64 v171, v175, v171, s[0:1]
	v_cndmask_b32_e64 v172, v176, v172, s[4:5]
	v_cndmask_b32_e64 v173, v177, v173, s[66:67]
	v_add_f32_e32 v174, v178, v182
	v_add_f32_e32 v175, v179, v183
	v_add_f32_e32 v176, v180, v184
	v_add_f32_e32 v177, v181, v185
	v_cndmask_b32_e64 v178, v182, v178, vcc
	v_cndmask_b32_e64 v179, v183, v179, s[0:1]
	v_cndmask_b32_e64 v180, v184, v180, s[4:5]
	v_cndmask_b32_e64 v181, v185, v181, s[66:67]
	v_cmp_eq_u32_e32 vcc, 0, v238
	v_cmp_eq_u32_e64 s[0:1], 1, v238
	v_cmp_eq_u32_e64 s[4:5], 2, v238
	v_cmp_eq_u32_e64 s[66:67], 3, v238
	v_mul_f32_e32 v170, 0x3fb8aa3b, v170
	v_mul_f32_e32 v171, 0x3fb8aa3b, v171
	v_mul_f32_e32 v172, 0x3fb8aa3b, v172
	v_mul_f32_e32 v173, 0x3fb8aa3b, v173
	v_exp_f32_e32 v170, v170
	v_exp_f32_e32 v171, v171
	v_exp_f32_e32 v172, v172
	v_exp_f32_e32 v173, v173
	v_mul_f32_e32 v178, v178, v170
	v_mul_f32_e32 v179, v179, v171
	v_mul_f32_e32 v180, v180, v172
	v_mul_f32_e32 v181, v181, v173
	v_cndmask_b32_e64 v0, v178, v174, vcc
	v_cndmask_b32_e64 v1, v179, v175, s[0:1]
	v_cndmask_b32_e64 v2, v180, v176, s[4:5]
	v_cndmask_b32_e64 v3, v181, v177, s[66:67]
	s_waitcnt lgkmcnt(8)
	v_add_u32_e32 v238, -8, v237
	v_cmp_lt_i32_e32 vcc, 0, v238
	v_cmp_lt_i32_e64 s[0:1], 1, v238
	v_cmp_lt_i32_e64 s[4:5], 2, v238
	v_cmp_lt_i32_e64 s[66:67], 3, v238
	v_sub_f32_e32 v186, v126, v186
	v_sub_f32_e32 v187, v126, v187
	v_sub_f32_e32 v188, v126, v188
	v_sub_f32_e32 v189, v126, v189
	v_sub_f32_e32 v190, v127, v190
	v_sub_f32_e32 v191, v127, v191
	v_sub_f32_e32 v192, v127, v192
	v_sub_f32_e32 v193, v127, v193
	v_cndmask_b32_e64 v186, v190, v186, vcc
	v_cndmask_b32_e64 v187, v191, v187, s[0:1]
	v_cndmask_b32_e64 v188, v192, v188, s[4:5]
	v_cndmask_b32_e64 v189, v193, v189, s[66:67]
	v_add_f32_e32 v190, v194, v198
	v_add_f32_e32 v191, v195, v199
	v_add_f32_e32 v192, v196, v200
	v_add_f32_e32 v193, v197, v201
	v_cndmask_b32_e64 v194, v198, v194, vcc
	v_cndmask_b32_e64 v195, v199, v195, s[0:1]
	v_cndmask_b32_e64 v196, v200, v196, s[4:5]
	v_cndmask_b32_e64 v197, v201, v197, s[66:67]
	v_cmp_eq_u32_e32 vcc, 0, v238
	v_cmp_eq_u32_e64 s[0:1], 1, v238
	v_cmp_eq_u32_e64 s[4:5], 2, v238
	v_cmp_eq_u32_e64 s[66:67], 3, v238
	v_mul_f32_e32 v186, 0x3fb8aa3b, v186
	v_mul_f32_e32 v187, 0x3fb8aa3b, v187
	v_mul_f32_e32 v188, 0x3fb8aa3b, v188
	v_mul_f32_e32 v189, 0x3fb8aa3b, v189
	v_exp_f32_e32 v186, v186
	v_exp_f32_e32 v187, v187
	v_exp_f32_e32 v188, v188
	v_exp_f32_e32 v189, v189
	v_mul_f32_e32 v194, v194, v186
	v_mul_f32_e32 v195, v195, v187
	v_mul_f32_e32 v196, v196, v188
	v_mul_f32_e32 v197, v197, v189
	v_cndmask_b32_e64 v4, v194, v190, vcc
	v_cndmask_b32_e64 v5, v195, v191, s[0:1]
	v_cndmask_b32_e64 v6, v196, v192, s[4:5]
	v_cndmask_b32_e64 v7, v197, v193, s[66:67]
	s_waitcnt lgkmcnt(4)
	v_add_u32_e32 v238, -16, v237
	v_cmp_lt_i32_e32 vcc, 0, v238
	v_cmp_lt_i32_e64 s[0:1], 1, v238
	v_cmp_lt_i32_e64 s[4:5], 2, v238
	v_cmp_lt_i32_e64 s[66:67], 3, v238
	v_sub_f32_e32 v202, v126, v202
	v_sub_f32_e32 v203, v126, v203
	v_sub_f32_e32 v204, v126, v204
	v_sub_f32_e32 v205, v126, v205
	v_sub_f32_e32 v206, v127, v206
	v_sub_f32_e32 v207, v127, v207
	v_sub_f32_e32 v208, v127, v208
	v_sub_f32_e32 v209, v127, v209
	v_cndmask_b32_e64 v202, v206, v202, vcc
	v_cndmask_b32_e64 v203, v207, v203, s[0:1]
	v_cndmask_b32_e64 v204, v208, v204, s[4:5]
	v_cndmask_b32_e64 v205, v209, v205, s[66:67]
	v_add_f32_e32 v206, v210, v214
	v_add_f32_e32 v207, v211, v215
	v_add_f32_e32 v208, v212, v216
	v_add_f32_e32 v209, v213, v217
	v_cndmask_b32_e64 v210, v214, v210, vcc
	v_cndmask_b32_e64 v211, v215, v211, s[0:1]
	v_cndmask_b32_e64 v212, v216, v212, s[4:5]
	v_cndmask_b32_e64 v213, v217, v213, s[66:67]
	v_cmp_eq_u32_e32 vcc, 0, v238
	v_cmp_eq_u32_e64 s[0:1], 1, v238
	v_cmp_eq_u32_e64 s[4:5], 2, v238
	v_cmp_eq_u32_e64 s[66:67], 3, v238
	v_mul_f32_e32 v202, 0x3fb8aa3b, v202
	v_mul_f32_e32 v203, 0x3fb8aa3b, v203
	v_mul_f32_e32 v204, 0x3fb8aa3b, v204
	v_mul_f32_e32 v205, 0x3fb8aa3b, v205
	v_exp_f32_e32 v202, v202
	v_exp_f32_e32 v203, v203
	v_exp_f32_e32 v204, v204
	v_exp_f32_e32 v205, v205
	v_mul_f32_e32 v210, v210, v202
	v_mul_f32_e32 v211, v211, v203
	v_mul_f32_e32 v212, v212, v204
	v_mul_f32_e32 v213, v213, v205
	v_cndmask_b32_e64 v40, v210, v206, vcc
	v_cndmask_b32_e64 v41, v211, v207, s[0:1]
	v_cndmask_b32_e64 v8, v212, v208, s[4:5]
	v_cndmask_b32_e64 v9, v213, v209, s[66:67]
	s_waitcnt lgkmcnt(0)
	v_add_u32_e32 v238, 0xffffffe8, v237
	v_cmp_lt_i32_e32 vcc, 0, v238
	v_cmp_lt_i32_e64 s[0:1], 1, v238
	v_cmp_lt_i32_e64 s[4:5], 2, v238
	v_cmp_lt_i32_e64 s[66:67], 3, v238
	v_sub_f32_e32 v218, v126, v218
	v_sub_f32_e32 v219, v126, v219
	v_sub_f32_e32 v220, v126, v220
	v_sub_f32_e32 v221, v126, v221
	v_sub_f32_e32 v222, v127, v222
	v_sub_f32_e32 v223, v127, v223
	v_sub_f32_e32 v224, v127, v224
	v_sub_f32_e32 v225, v127, v225
	v_cndmask_b32_e64 v218, v222, v218, vcc
	v_cndmask_b32_e64 v219, v223, v219, s[0:1]
	v_cndmask_b32_e64 v220, v224, v220, s[4:5]
	v_cndmask_b32_e64 v221, v225, v221, s[66:67]
	v_add_f32_e32 v222, v226, v230
	v_add_f32_e32 v223, v227, v231
	v_add_f32_e32 v224, v228, v232
	v_add_f32_e32 v225, v229, v233
	v_cndmask_b32_e64 v226, v230, v226, vcc
	v_cndmask_b32_e64 v227, v231, v227, s[0:1]
	v_cndmask_b32_e64 v228, v232, v228, s[4:5]
	v_cndmask_b32_e64 v229, v233, v229, s[66:67]
	v_cmp_eq_u32_e32 vcc, 0, v238
	v_cmp_eq_u32_e64 s[0:1], 1, v238
	v_cmp_eq_u32_e64 s[4:5], 2, v238
	v_cmp_eq_u32_e64 s[66:67], 3, v238
	v_mul_f32_e32 v218, 0x3fb8aa3b, v218
	v_mul_f32_e32 v219, 0x3fb8aa3b, v219
	v_mul_f32_e32 v220, 0x3fb8aa3b, v220
	v_mul_f32_e32 v221, 0x3fb8aa3b, v221
	v_exp_f32_e32 v218, v218
	v_exp_f32_e32 v219, v219
	v_exp_f32_e32 v220, v220
	v_exp_f32_e32 v221, v221
	v_mul_f32_e32 v226, v226, v218
	v_mul_f32_e32 v227, v227, v219
	v_mul_f32_e32 v228, v228, v220
	v_mul_f32_e32 v229, v229, v221
	v_cndmask_b32_e64 v10, v226, v222, vcc
	v_cndmask_b32_e64 v11, v227, v223, s[0:1]
	v_cndmask_b32_e64 v12, v228, v224, s[4:5]
	v_cndmask_b32_e64 v42, v229, v225, s[66:67]
	s_branch .Lssdb0_done
.Lssdb0_lt:
	ds_read_b128 v[170:173], v236 offset:35840
	ds_read_b128 v[178:181], v236 offset:36864
	ds_read_b128 v[186:189], v236 offset:35872
	ds_read_b128 v[194:197], v236 offset:36896
	ds_read_b128 v[202:205], v236 offset:35904
	ds_read_b128 v[210:213], v236 offset:36928
	ds_read_b128 v[218:221], v236 offset:35936
	ds_read_b128 v[226:229], v236 offset:36960
	s_waitcnt lgkmcnt(6)
	v_sub_f32_e32 v170, v126, v170
	v_sub_f32_e32 v171, v126, v171
	v_sub_f32_e32 v172, v126, v172
	v_sub_f32_e32 v173, v126, v173
	v_mul_f32_e32 v170, 0x3fb8aa3b, v170
	v_mul_f32_e32 v171, 0x3fb8aa3b, v171
	v_mul_f32_e32 v172, 0x3fb8aa3b, v172
	v_mul_f32_e32 v173, 0x3fb8aa3b, v173
	v_exp_f32_e32 v170, v170
	v_exp_f32_e32 v171, v171
	v_exp_f32_e32 v172, v172
	v_exp_f32_e32 v173, v173
	v_mul_f32_e32 v0, v178, v170
	v_mul_f32_e32 v1, v179, v171
	v_mul_f32_e32 v2, v180, v172
	v_mul_f32_e32 v3, v181, v173
	s_waitcnt lgkmcnt(4)
	v_sub_f32_e32 v186, v126, v186
	v_sub_f32_e32 v187, v126, v187
	v_sub_f32_e32 v188, v126, v188
	v_sub_f32_e32 v189, v126, v189
	v_mul_f32_e32 v186, 0x3fb8aa3b, v186
	v_mul_f32_e32 v187, 0x3fb8aa3b, v187
	v_mul_f32_e32 v188, 0x3fb8aa3b, v188
	v_mul_f32_e32 v189, 0x3fb8aa3b, v189
	v_exp_f32_e32 v186, v186
	v_exp_f32_e32 v187, v187
	v_exp_f32_e32 v188, v188
	v_exp_f32_e32 v189, v189
	v_mul_f32_e32 v4, v194, v186
	v_mul_f32_e32 v5, v195, v187
	v_mul_f32_e32 v6, v196, v188
	v_mul_f32_e32 v7, v197, v189
	s_waitcnt lgkmcnt(2)
	v_sub_f32_e32 v202, v126, v202
	v_sub_f32_e32 v203, v126, v203
	v_sub_f32_e32 v204, v126, v204
	v_sub_f32_e32 v205, v126, v205
	v_mul_f32_e32 v202, 0x3fb8aa3b, v202
	v_mul_f32_e32 v203, 0x3fb8aa3b, v203
	v_mul_f32_e32 v204, 0x3fb8aa3b, v204
	v_mul_f32_e32 v205, 0x3fb8aa3b, v205
	v_exp_f32_e32 v202, v202
	v_exp_f32_e32 v203, v203
	v_exp_f32_e32 v204, v204
	v_exp_f32_e32 v205, v205
	v_mul_f32_e32 v40, v210, v202
	v_mul_f32_e32 v41, v211, v203
	v_mul_f32_e32 v8, v212, v204
	v_mul_f32_e32 v9, v213, v205
	s_waitcnt lgkmcnt(0)
	v_sub_f32_e32 v218, v126, v218
	v_sub_f32_e32 v219, v126, v219
	v_sub_f32_e32 v220, v126, v220
	v_sub_f32_e32 v221, v126, v221
	v_mul_f32_e32 v218, 0x3fb8aa3b, v218
	v_mul_f32_e32 v219, 0x3fb8aa3b, v219
	v_mul_f32_e32 v220, 0x3fb8aa3b, v220
	v_mul_f32_e32 v221, 0x3fb8aa3b, v221
	v_exp_f32_e32 v218, v218
	v_exp_f32_e32 v219, v219
	v_exp_f32_e32 v220, v220
	v_exp_f32_e32 v221, v221
	v_mul_f32_e32 v10, v226, v218
	v_mul_f32_e32 v11, v227, v219
	v_mul_f32_e32 v12, v228, v220
	v_mul_f32_e32 v42, v229, v221
	s_branch .Lssdb0_done
.Lssdb0_gt:
	ds_read_b128 v[170:173], v236 offset:36352
	ds_read_b128 v[178:181], v236 offset:37376
	ds_read_b128 v[186:189], v236 offset:36384
	ds_read_b128 v[194:197], v236 offset:37408
	ds_read_b128 v[202:205], v236 offset:36416
	ds_read_b128 v[210:213], v236 offset:37440
	ds_read_b128 v[218:221], v236 offset:36448
	ds_read_b128 v[226:229], v236 offset:37472
	s_waitcnt lgkmcnt(6)
	v_sub_f32_e32 v170, v127, v170
	v_sub_f32_e32 v171, v127, v171
	v_sub_f32_e32 v172, v127, v172
	v_sub_f32_e32 v173, v127, v173
	v_mul_f32_e32 v170, 0x3fb8aa3b, v170
	v_mul_f32_e32 v171, 0x3fb8aa3b, v171
	v_mul_f32_e32 v172, 0x3fb8aa3b, v172
	v_mul_f32_e32 v173, 0x3fb8aa3b, v173
	v_exp_f32_e32 v170, v170
	v_exp_f32_e32 v171, v171
	v_exp_f32_e32 v172, v172
	v_exp_f32_e32 v173, v173
	v_mul_f32_e32 v0, v178, v170
	v_mul_f32_e32 v1, v179, v171
	v_mul_f32_e32 v2, v180, v172
	v_mul_f32_e32 v3, v181, v173
	s_waitcnt lgkmcnt(4)
	v_sub_f32_e32 v186, v127, v186
	v_sub_f32_e32 v187, v127, v187
	v_sub_f32_e32 v188, v127, v188
	v_sub_f32_e32 v189, v127, v189
	v_mul_f32_e32 v186, 0x3fb8aa3b, v186
	v_mul_f32_e32 v187, 0x3fb8aa3b, v187
	v_mul_f32_e32 v188, 0x3fb8aa3b, v188
	v_mul_f32_e32 v189, 0x3fb8aa3b, v189
	v_exp_f32_e32 v186, v186
	v_exp_f32_e32 v187, v187
	v_exp_f32_e32 v188, v188
	v_exp_f32_e32 v189, v189
	v_mul_f32_e32 v4, v194, v186
	v_mul_f32_e32 v5, v195, v187
	v_mul_f32_e32 v6, v196, v188
	v_mul_f32_e32 v7, v197, v189
	s_waitcnt lgkmcnt(2)
	v_sub_f32_e32 v202, v127, v202
	v_sub_f32_e32 v203, v127, v203
	v_sub_f32_e32 v204, v127, v204
	v_sub_f32_e32 v205, v127, v205
	v_mul_f32_e32 v202, 0x3fb8aa3b, v202
	v_mul_f32_e32 v203, 0x3fb8aa3b, v203
	v_mul_f32_e32 v204, 0x3fb8aa3b, v204
	v_mul_f32_e32 v205, 0x3fb8aa3b, v205
	v_exp_f32_e32 v202, v202
	v_exp_f32_e32 v203, v203
	v_exp_f32_e32 v204, v204
	v_exp_f32_e32 v205, v205
	v_mul_f32_e32 v40, v210, v202
	v_mul_f32_e32 v41, v211, v203
	v_mul_f32_e32 v8, v212, v204
	v_mul_f32_e32 v9, v213, v205
	s_waitcnt lgkmcnt(0)
	v_sub_f32_e32 v218, v127, v218
	v_sub_f32_e32 v219, v127, v219
	v_sub_f32_e32 v220, v127, v220
	v_sub_f32_e32 v221, v127, v221
	v_mul_f32_e32 v218, 0x3fb8aa3b, v218
	v_mul_f32_e32 v219, 0x3fb8aa3b, v219
	v_mul_f32_e32 v220, 0x3fb8aa3b, v220
	v_mul_f32_e32 v221, 0x3fb8aa3b, v221
	v_exp_f32_e32 v218, v218
	v_exp_f32_e32 v219, v219
	v_exp_f32_e32 v220, v220
	v_exp_f32_e32 v221, v221
	v_mul_f32_e32 v10, v226, v218
	v_mul_f32_e32 v11, v227, v219
	v_mul_f32_e32 v12, v228, v220
	v_mul_f32_e32 v42, v229, v221
.Lssdb0_done:
	v_mul_f32_e32 v16, v28, v4
	v_mul_u32_u24_e32 v4, 0x88, v52
	v_lshl_add_u32 v56, v110, 1, s23
	v_lshl_add_u32 v62, v4, 1, v56
	v_mul_f32_e32 v13, v31, v7
	v_mul_f32_e32 v14, v30, v6
	v_mul_f32_e32 v15, v29, v5
	ds_read2_b64 v[4:7], v62 offset1:2
	v_mul_f32_e32 v3, v27, v3
	v_mul_f32_e32 v2, v26, v2
	v_mul_f32_e32 v1, v25, v1
	v_mul_f32_e32 v0, v24, v0
	v_cvt_pk_bf16_f32 v0, v0, v1
	v_cvt_pk_bf16_f32 v1, v2, v3
	v_cvt_pk_bf16_f32 v2, v16, v15
	v_cvt_pk_bf16_f32 v3, v14, v13
	v_add_u32_e32 v63, 0x2000, v62
	v_mul_f32_e32 v44, v37, v11
	v_mul_f32_e32 v45, v36, v10
	v_mul_f32_e32 v46, v35, v9
	v_mul_f32_e32 v47, v34, v8
	ds_read2_b64 v[34:37], v62 offset0:4 offset1:6
	s_waitcnt lgkmcnt(1)
	v_mfma_f32_32x32x16_bf16 v[16:31], v[4:7], v[0:3], 0
	ds_read2_b64 v[4:7], v63 offset0:64 offset1:66
	v_mul_f32_e32 v43, v38, v12
	v_mul_f32_e32 v33, v33, v41
	v_mul_f32_e32 v32, v32, v40
	v_mul_f32_e32 v41, v39, v42
	v_cvt_pk_bf16_f32 v38, v32, v33
	v_cvt_pk_bf16_f32 v39, v47, v46
	v_cvt_pk_bf16_f32 v40, v45, v44
	v_cvt_pk_bf16_f32 v41, v43, v41
	s_waitcnt lgkmcnt(0)
	v_mfma_f32_32x32x16_bf16 v[0:15], v[4:7], v[0:3], 0
	v_or_b32_e32 v59, 32, v110
	v_cmp_ge_u32_e32 vcc, v59, v53
	v_mfma_f32_32x32x16_bf16 v[16:31], v[34:37], v[38:41], v[16:31]
	ds_read2_b64 v[32:35], v63 offset0:68 offset1:70
	v_or_b32_e32 v36, 32, v52
	v_mad_u32_u24 v58, v36, s71, v57
	s_waitcnt lgkmcnt(0)
	v_mfma_f32_32x32x16_bf16 v[0:15], v[32:35], v[38:41], v[0:15]
	ds_read_b128 v[32:35], v58 offset:17408
	ds_read_b128 v[64:67], v58 offset:17440
	s_waitcnt lgkmcnt(1)
	v_mfma_f32_32x32x16_bf16 v[32:47], v[32:35], v[48:51], 0
	s_waitcnt lgkmcnt(0)
	v_mfma_f32_32x32x16_bf16 v[32:47], v[64:67], v[102:105], v[32:47]
	ds_read_b128 v[64:67], v58 offset:17472
	ds_read_b128 v[68:71], v58 offset:17504
	s_waitcnt lgkmcnt(1)
	v_mfma_f32_32x32x16_bf16 v[32:47], v[64:67], v[98:101], v[32:47]
	s_waitcnt lgkmcnt(0)
	v_mfma_f32_32x32x16_bf16 v[32:47], v[68:71], v[94:97], v[32:47]
	v_lshl_add_u32 v236, v110, 2, s23
	v_lshrrev_b32_e32 v239, 5, v53
	s_nop 0
	v_readfirstlane_b32 s0, v239
	s_cmp_gt_u32 s0, 1
	s_cbranch_scc1 .Lssdb1_lt
	s_cmp_lt_u32 s0, 1
	s_cbranch_scc1 .Lssdb1_gt
	v_sub_u32_e32 v237, v53, v110
	ds_read_b128 v[170:173], v236 offset:35968
	ds_read_b128 v[174:177], v236 offset:36480
	ds_read_b128 v[178:181], v236 offset:36992
	ds_read_b128 v[182:185], v236 offset:37504
	ds_read_b128 v[186:189], v236 offset:36000
	ds_read_b128 v[190:193], v236 offset:36512
	ds_read_b128 v[194:197], v236 offset:37024
	ds_read_b128 v[198:201], v236 offset:37536
	ds_read_b128 v[202:205], v236 offset:36032
	ds_read_b128 v[206:209], v236 offset:36544
	ds_read_b128 v[210:213], v236 offset:37056
	ds_read_b128 v[214:217], v236 offset:37568
	s_waitcnt lgkmcnt(8)
	ds_read_b128 v[218:221], v236 offset:36064
	ds_read_b128 v[222:225], v236 offset:36576
	ds_read_b128 v[226:229], v236 offset:37088
	ds_read_b128 v[230:233], v236 offset:37600
	v_add_u32_e32 v238, 0xffffffe0, v237
	v_cmp_lt_i32_e32 vcc, 0, v238
	v_cmp_lt_i32_e64 s[0:1], 1, v238
	v_cmp_lt_i32_e64 s[4:5], 2, v238
	v_cmp_lt_i32_e64 s[66:67], 3, v238
	v_sub_f32_e32 v170, v126, v170
	v_sub_f32_e32 v171, v126, v171
	v_sub_f32_e32 v172, v126, v172
	v_sub_f32_e32 v173, v126, v173
	v_sub_f32_e32 v174, v127, v174
	v_sub_f32_e32 v175, v127, v175
	v_sub_f32_e32 v176, v127, v176
	v_sub_f32_e32 v177, v127, v177
	v_cndmask_b32_e64 v170, v174, v170, vcc
	v_cndmask_b32_e64 v171, v175, v171, s[0:1]
	v_cndmask_b32_e64 v172, v176, v172, s[4:5]
	v_cndmask_b32_e64 v173, v177, v173, s[66:67]
	v_add_f32_e32 v174, v178, v182
	v_add_f32_e32 v175, v179, v183
	v_add_f32_e32 v176, v180, v184
	v_add_f32_e32 v177, v181, v185
	v_cndmask_b32_e64 v178, v182, v178, vcc
	v_cndmask_b32_e64 v179, v183, v179, s[0:1]
	v_cndmask_b32_e64 v180, v184, v180, s[4:5]
	v_cndmask_b32_e64 v181, v185, v181, s[66:67]
	v_cmp_eq_u32_e32 vcc, 0, v238
	v_cmp_eq_u32_e64 s[0:1], 1, v238
	v_cmp_eq_u32_e64 s[4:5], 2, v238
	v_cmp_eq_u32_e64 s[66:67], 3, v238
	v_mul_f32_e32 v170, 0x3fb8aa3b, v170
	v_mul_f32_e32 v171, 0x3fb8aa3b, v171
	v_mul_f32_e32 v172, 0x3fb8aa3b, v172
	v_mul_f32_e32 v173, 0x3fb8aa3b, v173
	v_exp_f32_e32 v170, v170
	v_exp_f32_e32 v171, v171
	v_exp_f32_e32 v172, v172
	v_exp_f32_e32 v173, v173
	v_mul_f32_e32 v178, v178, v170
	v_mul_f32_e32 v179, v179, v171
	v_mul_f32_e32 v180, v180, v172
	v_mul_f32_e32 v181, v181, v173
	v_cndmask_b32_e64 v58, v178, v174, vcc
	v_cndmask_b32_e64 v59, v179, v175, s[0:1]
	v_cndmask_b32_e64 v64, v180, v176, s[4:5]
	v_cndmask_b32_e64 v65, v181, v177, s[66:67]
	s_waitcnt lgkmcnt(8)
	v_add_u32_e32 v238, 0xffffffd8, v237
	v_cmp_lt_i32_e32 vcc, 0, v238
	v_cmp_lt_i32_e64 s[0:1], 1, v238
	v_cmp_lt_i32_e64 s[4:5], 2, v238
	v_cmp_lt_i32_e64 s[66:67], 3, v238
	v_sub_f32_e32 v186, v126, v186
	v_sub_f32_e32 v187, v126, v187
	v_sub_f32_e32 v188, v126, v188
	v_sub_f32_e32 v189, v126, v189
	v_sub_f32_e32 v190, v127, v190
	v_sub_f32_e32 v191, v127, v191
	v_sub_f32_e32 v192, v127, v192
	v_sub_f32_e32 v193, v127, v193
	v_cndmask_b32_e64 v186, v190, v186, vcc
	v_cndmask_b32_e64 v187, v191, v187, s[0:1]
	v_cndmask_b32_e64 v188, v192, v188, s[4:5]
	v_cndmask_b32_e64 v189, v193, v189, s[66:67]
	v_add_f32_e32 v190, v194, v198
	v_add_f32_e32 v191, v195, v199
	v_add_f32_e32 v192, v196, v200
	v_add_f32_e32 v193, v197, v201
	v_cndmask_b32_e64 v194, v198, v194, vcc
	v_cndmask_b32_e64 v195, v199, v195, s[0:1]
	v_cndmask_b32_e64 v196, v200, v196, s[4:5]
	v_cndmask_b32_e64 v197, v201, v197, s[66:67]
	v_cmp_eq_u32_e32 vcc, 0, v238
	v_cmp_eq_u32_e64 s[0:1], 1, v238
	v_cmp_eq_u32_e64 s[4:5], 2, v238
	v_cmp_eq_u32_e64 s[66:67], 3, v238
	v_mul_f32_e32 v186, 0x3fb8aa3b, v186
	v_mul_f32_e32 v187, 0x3fb8aa3b, v187
	v_mul_f32_e32 v188, 0x3fb8aa3b, v188
	v_mul_f32_e32 v189, 0x3fb8aa3b, v189
	v_exp_f32_e32 v186, v186
	v_exp_f32_e32 v187, v187
	v_exp_f32_e32 v188, v188
	v_exp_f32_e32 v189, v189
	v_mul_f32_e32 v194, v194, v186
	v_mul_f32_e32 v195, v195, v187
	v_mul_f32_e32 v196, v196, v188
	v_mul_f32_e32 v197, v197, v189
	v_cndmask_b32_e64 v66, v194, v190, vcc
	v_cndmask_b32_e64 v67, v195, v191, s[0:1]
	v_cndmask_b32_e64 v68, v196, v192, s[4:5]
	v_cndmask_b32_e64 v70, v197, v193, s[66:67]
	s_waitcnt lgkmcnt(4)
	v_add_u32_e32 v238, 0xffffffd0, v237
	v_cmp_lt_i32_e32 vcc, 0, v238
	v_cmp_lt_i32_e64 s[0:1], 1, v238
	v_cmp_lt_i32_e64 s[4:5], 2, v238
	v_cmp_lt_i32_e64 s[66:67], 3, v238
	v_sub_f32_e32 v202, v126, v202
	v_sub_f32_e32 v203, v126, v203
	v_sub_f32_e32 v204, v126, v204
	v_sub_f32_e32 v205, v126, v205
	v_sub_f32_e32 v206, v127, v206
	v_sub_f32_e32 v207, v127, v207
	v_sub_f32_e32 v208, v127, v208
	v_sub_f32_e32 v209, v127, v209
	v_cndmask_b32_e64 v202, v206, v202, vcc
	v_cndmask_b32_e64 v203, v207, v203, s[0:1]
	v_cndmask_b32_e64 v204, v208, v204, s[4:5]
	v_cndmask_b32_e64 v205, v209, v205, s[66:67]
	v_add_f32_e32 v206, v210, v214
	v_add_f32_e32 v207, v211, v215
	v_add_f32_e32 v208, v212, v216
	v_add_f32_e32 v209, v213, v217
	v_cndmask_b32_e64 v210, v214, v210, vcc
	v_cndmask_b32_e64 v211, v215, v211, s[0:1]
	v_cndmask_b32_e64 v212, v216, v212, s[4:5]
	v_cndmask_b32_e64 v213, v217, v213, s[66:67]
	v_cmp_eq_u32_e32 vcc, 0, v238
	v_cmp_eq_u32_e64 s[0:1], 1, v238
	v_cmp_eq_u32_e64 s[4:5], 2, v238
	v_cmp_eq_u32_e64 s[66:67], 3, v238
	v_mul_f32_e32 v202, 0x3fb8aa3b, v202
	v_mul_f32_e32 v203, 0x3fb8aa3b, v203
	v_mul_f32_e32 v204, 0x3fb8aa3b, v204
	v_mul_f32_e32 v205, 0x3fb8aa3b, v205
	v_exp_f32_e32 v202, v202
	v_exp_f32_e32 v203, v203
	v_exp_f32_e32 v204, v204
	v_exp_f32_e32 v205, v205
	v_mul_f32_e32 v210, v210, v202
	v_mul_f32_e32 v211, v211, v203
	v_mul_f32_e32 v212, v212, v204
	v_mul_f32_e32 v213, v213, v205
	v_cndmask_b32_e64 v69, v210, v206, vcc
	v_cndmask_b32_e64 v71, v211, v207, s[0:1]
	v_cndmask_b32_e64 v72, v212, v208, s[4:5]
	v_cndmask_b32_e64 v73, v213, v209, s[66:67]
	s_waitcnt lgkmcnt(0)
	v_add_u32_e32 v238, 0xffffffc8, v237
	v_cmp_lt_i32_e32 vcc, 0, v238
	v_cmp_lt_i32_e64 s[0:1], 1, v238
	v_cmp_lt_i32_e64 s[4:5], 2, v238
	v_cmp_lt_i32_e64 s[66:67], 3, v238
	v_sub_f32_e32 v218, v126, v218
	v_sub_f32_e32 v219, v126, v219
	v_sub_f32_e32 v220, v126, v220
	v_sub_f32_e32 v221, v126, v221
	v_sub_f32_e32 v222, v127, v222
	v_sub_f32_e32 v223, v127, v223
	v_sub_f32_e32 v224, v127, v224
	v_sub_f32_e32 v225, v127, v225
	v_cndmask_b32_e64 v218, v222, v218, vcc
	v_cndmask_b32_e64 v219, v223, v219, s[0:1]
	v_cndmask_b32_e64 v220, v224, v220, s[4:5]
	v_cndmask_b32_e64 v221, v225, v221, s[66:67]
	v_add_f32_e32 v222, v226, v230
	v_add_f32_e32 v223, v227, v231
	v_add_f32_e32 v224, v228, v232
	v_add_f32_e32 v225, v229, v233
	v_cndmask_b32_e64 v226, v230, v226, vcc
	v_cndmask_b32_e64 v227, v231, v227, s[0:1]
	v_cndmask_b32_e64 v228, v232, v228, s[4:5]
	v_cndmask_b32_e64 v229, v233, v229, s[66:67]
	v_cmp_eq_u32_e32 vcc, 0, v238
	v_cmp_eq_u32_e64 s[0:1], 1, v238
	v_cmp_eq_u32_e64 s[4:5], 2, v238
	v_cmp_eq_u32_e64 s[66:67], 3, v238
	v_mul_f32_e32 v218, 0x3fb8aa3b, v218
	v_mul_f32_e32 v219, 0x3fb8aa3b, v219
	v_mul_f32_e32 v220, 0x3fb8aa3b, v220
	v_mul_f32_e32 v221, 0x3fb8aa3b, v221
	v_exp_f32_e32 v218, v218
	v_exp_f32_e32 v219, v219
	v_exp_f32_e32 v220, v220
	v_exp_f32_e32 v221, v221
	v_mul_f32_e32 v226, v226, v218
	v_mul_f32_e32 v227, v227, v219
	v_mul_f32_e32 v228, v228, v220
	v_mul_f32_e32 v229, v229, v221
	v_cndmask_b32_e64 v74, v226, v222, vcc
	v_cndmask_b32_e64 v75, v227, v223, s[0:1]
	v_cndmask_b32_e64 v76, v228, v224, s[4:5]
	v_cndmask_b32_e64 v77, v229, v225, s[66:67]
	s_branch .Lssdb1_done
.Lssdb1_lt:
	ds_read_b128 v[170:173], v236 offset:35968
	ds_read_b128 v[178:181], v236 offset:36992
	ds_read_b128 v[186:189], v236 offset:36000
	ds_read_b128 v[194:197], v236 offset:37024
	ds_read_b128 v[202:205], v236 offset:36032
	ds_read_b128 v[210:213], v236 offset:37056
	ds_read_b128 v[218:221], v236 offset:36064
	ds_read_b128 v[226:229], v236 offset:37088
	s_waitcnt lgkmcnt(6)
	v_sub_f32_e32 v170, v126, v170
	v_sub_f32_e32 v171, v126, v171
	v_sub_f32_e32 v172, v126, v172
	v_sub_f32_e32 v173, v126, v173
	v_mul_f32_e32 v170, 0x3fb8aa3b, v170
	v_mul_f32_e32 v171, 0x3fb8aa3b, v171
	v_mul_f32_e32 v172, 0x3fb8aa3b, v172
	v_mul_f32_e32 v173, 0x3fb8aa3b, v173
	v_exp_f32_e32 v170, v170
	v_exp_f32_e32 v171, v171
	v_exp_f32_e32 v172, v172
	v_exp_f32_e32 v173, v173
	v_mul_f32_e32 v58, v178, v170
	v_mul_f32_e32 v59, v179, v171
	v_mul_f32_e32 v64, v180, v172
	v_mul_f32_e32 v65, v181, v173
	s_waitcnt lgkmcnt(4)
	v_sub_f32_e32 v186, v126, v186
	v_sub_f32_e32 v187, v126, v187
	v_sub_f32_e32 v188, v126, v188
	v_sub_f32_e32 v189, v126, v189
	v_mul_f32_e32 v186, 0x3fb8aa3b, v186
	v_mul_f32_e32 v187, 0x3fb8aa3b, v187
	v_mul_f32_e32 v188, 0x3fb8aa3b, v188
	v_mul_f32_e32 v189, 0x3fb8aa3b, v189
	v_exp_f32_e32 v186, v186
	v_exp_f32_e32 v187, v187
	v_exp_f32_e32 v188, v188
	v_exp_f32_e32 v189, v189
	v_mul_f32_e32 v66, v194, v186
	v_mul_f32_e32 v67, v195, v187
	v_mul_f32_e32 v68, v196, v188
	v_mul_f32_e32 v70, v197, v189
	s_waitcnt lgkmcnt(2)
	v_sub_f32_e32 v202, v126, v202
	v_sub_f32_e32 v203, v126, v203
	v_sub_f32_e32 v204, v126, v204
	v_sub_f32_e32 v205, v126, v205
	v_mul_f32_e32 v202, 0x3fb8aa3b, v202
	v_mul_f32_e32 v203, 0x3fb8aa3b, v203
	v_mul_f32_e32 v204, 0x3fb8aa3b, v204
	v_mul_f32_e32 v205, 0x3fb8aa3b, v205
	v_exp_f32_e32 v202, v202
	v_exp_f32_e32 v203, v203
	v_exp_f32_e32 v204, v204
	v_exp_f32_e32 v205, v205
	v_mul_f32_e32 v69, v210, v202
	v_mul_f32_e32 v71, v211, v203
	v_mul_f32_e32 v72, v212, v204
	v_mul_f32_e32 v73, v213, v205
	s_waitcnt lgkmcnt(0)
	v_sub_f32_e32 v218, v126, v218
	v_sub_f32_e32 v219, v126, v219
	v_sub_f32_e32 v220, v126, v220
	v_sub_f32_e32 v221, v126, v221
	v_mul_f32_e32 v218, 0x3fb8aa3b, v218
	v_mul_f32_e32 v219, 0x3fb8aa3b, v219
	v_mul_f32_e32 v220, 0x3fb8aa3b, v220
	v_mul_f32_e32 v221, 0x3fb8aa3b, v221
	v_exp_f32_e32 v218, v218
	v_exp_f32_e32 v219, v219
	v_exp_f32_e32 v220, v220
	v_exp_f32_e32 v221, v221
	v_mul_f32_e32 v74, v226, v218
	v_mul_f32_e32 v75, v227, v219
	v_mul_f32_e32 v76, v228, v220
	v_mul_f32_e32 v77, v229, v221
	s_branch .Lssdb1_done
.Lssdb1_gt:
	ds_read_b128 v[170:173], v236 offset:36480
	ds_read_b128 v[178:181], v236 offset:37504
	ds_read_b128 v[186:189], v236 offset:36512
	ds_read_b128 v[194:197], v236 offset:37536
	ds_read_b128 v[202:205], v236 offset:36544
	ds_read_b128 v[210:213], v236 offset:37568
	ds_read_b128 v[218:221], v236 offset:36576
	ds_read_b128 v[226:229], v236 offset:37600
	s_waitcnt lgkmcnt(6)
	v_sub_f32_e32 v170, v127, v170
	v_sub_f32_e32 v171, v127, v171
	v_sub_f32_e32 v172, v127, v172
	v_sub_f32_e32 v173, v127, v173
	v_mul_f32_e32 v170, 0x3fb8aa3b, v170
	v_mul_f32_e32 v171, 0x3fb8aa3b, v171
	v_mul_f32_e32 v172, 0x3fb8aa3b, v172
	v_mul_f32_e32 v173, 0x3fb8aa3b, v173
	v_exp_f32_e32 v170, v170
	v_exp_f32_e32 v171, v171
	v_exp_f32_e32 v172, v172
	v_exp_f32_e32 v173, v173
	v_mul_f32_e32 v58, v178, v170
	v_mul_f32_e32 v59, v179, v171
	v_mul_f32_e32 v64, v180, v172
	v_mul_f32_e32 v65, v181, v173
	s_waitcnt lgkmcnt(4)
	v_sub_f32_e32 v186, v127, v186
	v_sub_f32_e32 v187, v127, v187
	v_sub_f32_e32 v188, v127, v188
	v_sub_f32_e32 v189, v127, v189
	v_mul_f32_e32 v186, 0x3fb8aa3b, v186
	v_mul_f32_e32 v187, 0x3fb8aa3b, v187
	v_mul_f32_e32 v188, 0x3fb8aa3b, v188
	v_mul_f32_e32 v189, 0x3fb8aa3b, v189
	v_exp_f32_e32 v186, v186
	v_exp_f32_e32 v187, v187
	v_exp_f32_e32 v188, v188
	v_exp_f32_e32 v189, v189
	v_mul_f32_e32 v66, v194, v186
	v_mul_f32_e32 v67, v195, v187
	v_mul_f32_e32 v68, v196, v188
	v_mul_f32_e32 v70, v197, v189
	s_waitcnt lgkmcnt(2)
	v_sub_f32_e32 v202, v127, v202
	v_sub_f32_e32 v203, v127, v203
	v_sub_f32_e32 v204, v127, v204
	v_sub_f32_e32 v205, v127, v205
	v_mul_f32_e32 v202, 0x3fb8aa3b, v202
	v_mul_f32_e32 v203, 0x3fb8aa3b, v203
	v_mul_f32_e32 v204, 0x3fb8aa3b, v204
	v_mul_f32_e32 v205, 0x3fb8aa3b, v205
	v_exp_f32_e32 v202, v202
	v_exp_f32_e32 v203, v203
	v_exp_f32_e32 v204, v204
	v_exp_f32_e32 v205, v205
	v_mul_f32_e32 v69, v210, v202
	v_mul_f32_e32 v71, v211, v203
	v_mul_f32_e32 v72, v212, v204
	v_mul_f32_e32 v73, v213, v205
	s_waitcnt lgkmcnt(0)
	v_sub_f32_e32 v218, v127, v218
	v_sub_f32_e32 v219, v127, v219
	v_sub_f32_e32 v220, v127, v220
	v_sub_f32_e32 v221, v127, v221
	v_mul_f32_e32 v218, 0x3fb8aa3b, v218
	v_mul_f32_e32 v219, 0x3fb8aa3b, v219
	v_mul_f32_e32 v220, 0x3fb8aa3b, v220
	v_mul_f32_e32 v221, 0x3fb8aa3b, v221
	v_exp_f32_e32 v218, v218
	v_exp_f32_e32 v219, v219
	v_exp_f32_e32 v220, v220
	v_exp_f32_e32 v221, v221
	v_mul_f32_e32 v74, v226, v218
	v_mul_f32_e32 v75, v227, v219
	v_mul_f32_e32 v76, v228, v220
	v_mul_f32_e32 v77, v229, v221
.Lssdb1_done:
	v_mul_f32_e32 v70, v39, v70
	v_mul_f32_e32 v68, v38, v68
	v_mul_f32_e32 v67, v37, v67
	v_mul_f32_e32 v66, v36, v66
	ds_read2_b64 v[36:39], v62 offset0:8 offset1:10
	v_mul_f32_e32 v35, v35, v65
	v_mul_f32_e32 v34, v34, v64
	v_mul_f32_e32 v33, v33, v59
	v_mul_f32_e32 v32, v32, v58
	v_cvt_pk_bf16_f32 v32, v32, v33
	v_cvt_pk_bf16_f32 v33, v34, v35
	v_cvt_pk_bf16_f32 v34, v66, v67
	v_cvt_pk_bf16_f32 v35, v68, v70
	v_mul_f32_e32 v58, v45, v75
	v_mul_f32_e32 v59, v44, v74
	s_waitcnt lgkmcnt(0)
	v_mfma_f32_32x32x16_bf16 v[16:31], v[36:39], v[32:35], v[16:31]
	ds_read2_b64 v[36:39], v63 offset0:72 offset1:74
	v_mul_f32_e32 v64, v43, v73
	v_mul_f32_e32 v65, v42, v72
	ds_read2_b64 v[42:45], v62 offset0:12 offset1:14
	v_mul_f32_e32 v46, v46, v76
	s_waitcnt lgkmcnt(1)
	v_mfma_f32_32x32x16_bf16 v[0:15], v[36:39], v[32:35], v[0:15]
	ds_read2_b64 v[36:39], v63 offset0:76 offset1:78
	v_mul_f32_e32 v32, v41, v71
	v_mul_f32_e32 v33, v40, v69
	v_mul_f32_e32 v35, v47, v77
	v_mul_u32_u24_e32 v40, 0x90, v52
	v_cvt_pk_bf16_f32 v32, v33, v32
	v_cvt_pk_bf16_f32 v33, v65, v64
	v_cvt_pk_bf16_f32 v34, v59, v58
	v_cvt_pk_bf16_f32 v35, v46, v35
	v_add_u32_e32 v57, v57, v40
	v_or_b32_e32 v59, 64, v110
	s_waitcnt lgkmcnt(1)
	v_mfma_f32_32x32x16_bf16 v[16:31], v[42:45], v[32:35], v[16:31]
	v_cmp_ge_u32_e32 vcc, v59, v53
	s_waitcnt lgkmcnt(0)
	v_mfma_f32_32x32x16_bf16 v[0:15], v[36:39], v[32:35], v[0:15]
	ds_read_b128 v[32:35], v57 offset:26624
	ds_read_b128 v[64:67], v57 offset:26656
	s_waitcnt lgkmcnt(1)
	v_mfma_f32_32x32x16_bf16 v[32:47], v[32:35], v[48:51], 0
	s_waitcnt lgkmcnt(0)
	v_mfma_f32_32x32x16_bf16 v[32:47], v[64:67], v[102:105], v[32:47]
	ds_read_b128 v[64:67], v57 offset:26688
	ds_read_b128 v[68:71], v57 offset:26720
	s_waitcnt lgkmcnt(1)
	v_mfma_f32_32x32x16_bf16 v[32:47], v[64:67], v[98:101], v[32:47]
	s_waitcnt lgkmcnt(0)
	v_mfma_f32_32x32x16_bf16 v[32:47], v[68:71], v[94:97], v[32:47]
	v_lshl_add_u32 v236, v110, 2, s23
	v_lshrrev_b32_e32 v239, 5, v53
	s_nop 0
	v_readfirstlane_b32 s0, v239
	s_cmp_gt_u32 s0, 2
	s_cbranch_scc1 .Lssdb2_lt
	s_cmp_lt_u32 s0, 2
	s_cbranch_scc1 .Lssdb2_gt
	v_sub_u32_e32 v237, v53, v110
	ds_read_b128 v[170:173], v236 offset:36096
	ds_read_b128 v[174:177], v236 offset:36608
	ds_read_b128 v[178:181], v236 offset:37120
	ds_read_b128 v[182:185], v236 offset:37632
	ds_read_b128 v[186:189], v236 offset:36128
	ds_read_b128 v[190:193], v236 offset:36640
	ds_read_b128 v[194:197], v236 offset:37152
	ds_read_b128 v[198:201], v236 offset:37664
	ds_read_b128 v[202:205], v236 offset:36160
	ds_read_b128 v[206:209], v236 offset:36672
	ds_read_b128 v[210:213], v236 offset:37184
	ds_read_b128 v[214:217], v236 offset:37696
	s_waitcnt lgkmcnt(8)
	ds_read_b128 v[218:221], v236 offset:36192
	ds_read_b128 v[222:225], v236 offset:36704
	ds_read_b128 v[226:229], v236 offset:37216
	ds_read_b128 v[230:233], v236 offset:37728
	v_add_u32_e32 v238, 0xffffffc0, v237
	v_cmp_lt_i32_e32 vcc, 0, v238
	v_cmp_lt_i32_e64 s[0:1], 1, v238
	v_cmp_lt_i32_e64 s[4:5], 2, v238
	v_cmp_lt_i32_e64 s[66:67], 3, v238
	v_sub_f32_e32 v170, v126, v170
	v_sub_f32_e32 v171, v126, v171
	v_sub_f32_e32 v172, v126, v172
	v_sub_f32_e32 v173, v126, v173
	v_sub_f32_e32 v174, v127, v174
	v_sub_f32_e32 v175, v127, v175
	v_sub_f32_e32 v176, v127, v176
	v_sub_f32_e32 v177, v127, v177
	v_cndmask_b32_e64 v170, v174, v170, vcc
	v_cndmask_b32_e64 v171, v175, v171, s[0:1]
	v_cndmask_b32_e64 v172, v176, v172, s[4:5]
	v_cndmask_b32_e64 v173, v177, v173, s[66:67]
	v_add_f32_e32 v174, v178, v182
	v_add_f32_e32 v175, v179, v183
	v_add_f32_e32 v176, v180, v184
	v_add_f32_e32 v177, v181, v185
	v_cndmask_b32_e64 v178, v182, v178, vcc
	v_cndmask_b32_e64 v179, v183, v179, s[0:1]
	v_cndmask_b32_e64 v180, v184, v180, s[4:5]
	v_cndmask_b32_e64 v181, v185, v181, s[66:67]
	v_cmp_eq_u32_e32 vcc, 0, v238
	v_cmp_eq_u32_e64 s[0:1], 1, v238
	v_cmp_eq_u32_e64 s[4:5], 2, v238
	v_cmp_eq_u32_e64 s[66:67], 3, v238
	v_mul_f32_e32 v170, 0x3fb8aa3b, v170
	v_mul_f32_e32 v171, 0x3fb8aa3b, v171
	v_mul_f32_e32 v172, 0x3fb8aa3b, v172
	v_mul_f32_e32 v173, 0x3fb8aa3b, v173
	v_exp_f32_e32 v170, v170
	v_exp_f32_e32 v171, v171
	v_exp_f32_e32 v172, v172
	v_exp_f32_e32 v173, v173
	v_mul_f32_e32 v178, v178, v170
	v_mul_f32_e32 v179, v179, v171
	v_mul_f32_e32 v180, v180, v172
	v_mul_f32_e32 v181, v181, v173
	v_cndmask_b32_e64 v58, v178, v174, vcc
	v_cndmask_b32_e64 v59, v179, v175, s[0:1]
	v_cndmask_b32_e64 v64, v180, v176, s[4:5]
	v_cndmask_b32_e64 v65, v181, v177, s[66:67]
	s_waitcnt lgkmcnt(8)
	v_add_u32_e32 v238, 0xffffffb8, v237
	v_cmp_lt_i32_e32 vcc, 0, v238
	v_cmp_lt_i32_e64 s[0:1], 1, v238
	v_cmp_lt_i32_e64 s[4:5], 2, v238
	v_cmp_lt_i32_e64 s[66:67], 3, v238
	v_sub_f32_e32 v186, v126, v186
	v_sub_f32_e32 v187, v126, v187
	v_sub_f32_e32 v188, v126, v188
	v_sub_f32_e32 v189, v126, v189
	v_sub_f32_e32 v190, v127, v190
	v_sub_f32_e32 v191, v127, v191
	v_sub_f32_e32 v192, v127, v192
	v_sub_f32_e32 v193, v127, v193
	v_cndmask_b32_e64 v186, v190, v186, vcc
	v_cndmask_b32_e64 v187, v191, v187, s[0:1]
	v_cndmask_b32_e64 v188, v192, v188, s[4:5]
	v_cndmask_b32_e64 v189, v193, v189, s[66:67]
	v_add_f32_e32 v190, v194, v198
	v_add_f32_e32 v191, v195, v199
	v_add_f32_e32 v192, v196, v200
	v_add_f32_e32 v193, v197, v201
	v_cndmask_b32_e64 v194, v198, v194, vcc
	v_cndmask_b32_e64 v195, v199, v195, s[0:1]
	v_cndmask_b32_e64 v196, v200, v196, s[4:5]
	v_cndmask_b32_e64 v197, v201, v197, s[66:67]
	v_cmp_eq_u32_e32 vcc, 0, v238
	v_cmp_eq_u32_e64 s[0:1], 1, v238
	v_cmp_eq_u32_e64 s[4:5], 2, v238
	v_cmp_eq_u32_e64 s[66:67], 3, v238
	v_mul_f32_e32 v186, 0x3fb8aa3b, v186
	v_mul_f32_e32 v187, 0x3fb8aa3b, v187
	v_mul_f32_e32 v188, 0x3fb8aa3b, v188
	v_mul_f32_e32 v189, 0x3fb8aa3b, v189
	v_exp_f32_e32 v186, v186
	v_exp_f32_e32 v187, v187
	v_exp_f32_e32 v188, v188
	v_exp_f32_e32 v189, v189
	v_mul_f32_e32 v194, v194, v186
	v_mul_f32_e32 v195, v195, v187
	v_mul_f32_e32 v196, v196, v188
	v_mul_f32_e32 v197, v197, v189
	v_cndmask_b32_e64 v66, v194, v190, vcc
	v_cndmask_b32_e64 v67, v195, v191, s[0:1]
	v_cndmask_b32_e64 v68, v196, v192, s[4:5]
	v_cndmask_b32_e64 v70, v197, v193, s[66:67]
	s_waitcnt lgkmcnt(4)
	v_add_u32_e32 v238, 0xffffffb0, v237
	v_cmp_lt_i32_e32 vcc, 0, v238
	v_cmp_lt_i32_e64 s[0:1], 1, v238
	v_cmp_lt_i32_e64 s[4:5], 2, v238
	v_cmp_lt_i32_e64 s[66:67], 3, v238
	v_sub_f32_e32 v202, v126, v202
	v_sub_f32_e32 v203, v126, v203
	v_sub_f32_e32 v204, v126, v204
	v_sub_f32_e32 v205, v126, v205
	v_sub_f32_e32 v206, v127, v206
	v_sub_f32_e32 v207, v127, v207
	v_sub_f32_e32 v208, v127, v208
	v_sub_f32_e32 v209, v127, v209
	v_cndmask_b32_e64 v202, v206, v202, vcc
	v_cndmask_b32_e64 v203, v207, v203, s[0:1]
	v_cndmask_b32_e64 v204, v208, v204, s[4:5]
	v_cndmask_b32_e64 v205, v209, v205, s[66:67]
	v_add_f32_e32 v206, v210, v214
	v_add_f32_e32 v207, v211, v215
	v_add_f32_e32 v208, v212, v216
	v_add_f32_e32 v209, v213, v217
	v_cndmask_b32_e64 v210, v214, v210, vcc
	v_cndmask_b32_e64 v211, v215, v211, s[0:1]
	v_cndmask_b32_e64 v212, v216, v212, s[4:5]
	v_cndmask_b32_e64 v213, v217, v213, s[66:67]
	v_cmp_eq_u32_e32 vcc, 0, v238
	v_cmp_eq_u32_e64 s[0:1], 1, v238
	v_cmp_eq_u32_e64 s[4:5], 2, v238
	v_cmp_eq_u32_e64 s[66:67], 3, v238
	v_mul_f32_e32 v202, 0x3fb8aa3b, v202
	v_mul_f32_e32 v203, 0x3fb8aa3b, v203
	v_mul_f32_e32 v204, 0x3fb8aa3b, v204
	v_mul_f32_e32 v205, 0x3fb8aa3b, v205
	v_exp_f32_e32 v202, v202
	v_exp_f32_e32 v203, v203
	v_exp_f32_e32 v204, v204
	v_exp_f32_e32 v205, v205
	v_mul_f32_e32 v210, v210, v202
	v_mul_f32_e32 v211, v211, v203
	v_mul_f32_e32 v212, v212, v204
	v_mul_f32_e32 v213, v213, v205
	v_cndmask_b32_e64 v69, v210, v206, vcc
	v_cndmask_b32_e64 v71, v211, v207, s[0:1]
	v_cndmask_b32_e64 v72, v212, v208, s[4:5]
	v_cndmask_b32_e64 v73, v213, v209, s[66:67]
	s_waitcnt lgkmcnt(0)
	v_add_u32_e32 v238, 0xffffffa8, v237
	v_cmp_lt_i32_e32 vcc, 0, v238
	v_cmp_lt_i32_e64 s[0:1], 1, v238
	v_cmp_lt_i32_e64 s[4:5], 2, v238
	v_cmp_lt_i32_e64 s[66:67], 3, v238
	v_sub_f32_e32 v218, v126, v218
	v_sub_f32_e32 v219, v126, v219
	v_sub_f32_e32 v220, v126, v220
	v_sub_f32_e32 v221, v126, v221
	v_sub_f32_e32 v222, v127, v222
	v_sub_f32_e32 v223, v127, v223
	v_sub_f32_e32 v224, v127, v224
	v_sub_f32_e32 v225, v127, v225
	v_cndmask_b32_e64 v218, v222, v218, vcc
	v_cndmask_b32_e64 v219, v223, v219, s[0:1]
	v_cndmask_b32_e64 v220, v224, v220, s[4:5]
	v_cndmask_b32_e64 v221, v225, v221, s[66:67]
	v_add_f32_e32 v222, v226, v230
	v_add_f32_e32 v223, v227, v231
	v_add_f32_e32 v224, v228, v232
	v_add_f32_e32 v225, v229, v233
	v_cndmask_b32_e64 v226, v230, v226, vcc
	v_cndmask_b32_e64 v227, v231, v227, s[0:1]
	v_cndmask_b32_e64 v228, v232, v228, s[4:5]
	v_cndmask_b32_e64 v229, v233, v229, s[66:67]
	v_cmp_eq_u32_e32 vcc, 0, v238
	v_cmp_eq_u32_e64 s[0:1], 1, v238
	v_cmp_eq_u32_e64 s[4:5], 2, v238
	v_cmp_eq_u32_e64 s[66:67], 3, v238
	v_mul_f32_e32 v218, 0x3fb8aa3b, v218
	v_mul_f32_e32 v219, 0x3fb8aa3b, v219
	v_mul_f32_e32 v220, 0x3fb8aa3b, v220
	v_mul_f32_e32 v221, 0x3fb8aa3b, v221
	v_exp_f32_e32 v218, v218
	v_exp_f32_e32 v219, v219
	v_exp_f32_e32 v220, v220
	v_exp_f32_e32 v221, v221
	v_mul_f32_e32 v226, v226, v218
	v_mul_f32_e32 v227, v227, v219
	v_mul_f32_e32 v228, v228, v220
	v_mul_f32_e32 v229, v229, v221
	v_cndmask_b32_e64 v74, v226, v222, vcc
	v_cndmask_b32_e64 v75, v227, v223, s[0:1]
	v_cndmask_b32_e64 v76, v228, v224, s[4:5]
	v_cndmask_b32_e64 v77, v229, v225, s[66:67]
	s_branch .Lssdb2_done
.Lssdb2_lt:
	ds_read_b128 v[170:173], v236 offset:36096
	ds_read_b128 v[178:181], v236 offset:37120
	ds_read_b128 v[186:189], v236 offset:36128
	ds_read_b128 v[194:197], v236 offset:37152
	ds_read_b128 v[202:205], v236 offset:36160
	ds_read_b128 v[210:213], v236 offset:37184
	ds_read_b128 v[218:221], v236 offset:36192
	ds_read_b128 v[226:229], v236 offset:37216
	s_waitcnt lgkmcnt(6)
	v_sub_f32_e32 v170, v126, v170
	v_sub_f32_e32 v171, v126, v171
	v_sub_f32_e32 v172, v126, v172
	v_sub_f32_e32 v173, v126, v173
	v_mul_f32_e32 v170, 0x3fb8aa3b, v170
	v_mul_f32_e32 v171, 0x3fb8aa3b, v171
	v_mul_f32_e32 v172, 0x3fb8aa3b, v172
	v_mul_f32_e32 v173, 0x3fb8aa3b, v173
	v_exp_f32_e32 v170, v170
	v_exp_f32_e32 v171, v171
	v_exp_f32_e32 v172, v172
	v_exp_f32_e32 v173, v173
	v_mul_f32_e32 v58, v178, v170
	v_mul_f32_e32 v59, v179, v171
	v_mul_f32_e32 v64, v180, v172
	v_mul_f32_e32 v65, v181, v173
	s_waitcnt lgkmcnt(4)
	v_sub_f32_e32 v186, v126, v186
	v_sub_f32_e32 v187, v126, v187
	v_sub_f32_e32 v188, v126, v188
	v_sub_f32_e32 v189, v126, v189
	v_mul_f32_e32 v186, 0x3fb8aa3b, v186
	v_mul_f32_e32 v187, 0x3fb8aa3b, v187
	v_mul_f32_e32 v188, 0x3fb8aa3b, v188
	v_mul_f32_e32 v189, 0x3fb8aa3b, v189
	v_exp_f32_e32 v186, v186
	v_exp_f32_e32 v187, v187
	v_exp_f32_e32 v188, v188
	v_exp_f32_e32 v189, v189
	v_mul_f32_e32 v66, v194, v186
	v_mul_f32_e32 v67, v195, v187
	v_mul_f32_e32 v68, v196, v188
	v_mul_f32_e32 v70, v197, v189
	s_waitcnt lgkmcnt(2)
	v_sub_f32_e32 v202, v126, v202
	v_sub_f32_e32 v203, v126, v203
	v_sub_f32_e32 v204, v126, v204
	v_sub_f32_e32 v205, v126, v205
	v_mul_f32_e32 v202, 0x3fb8aa3b, v202
	v_mul_f32_e32 v203, 0x3fb8aa3b, v203
	v_mul_f32_e32 v204, 0x3fb8aa3b, v204
	v_mul_f32_e32 v205, 0x3fb8aa3b, v205
	v_exp_f32_e32 v202, v202
	v_exp_f32_e32 v203, v203
	v_exp_f32_e32 v204, v204
	v_exp_f32_e32 v205, v205
	v_mul_f32_e32 v69, v210, v202
	v_mul_f32_e32 v71, v211, v203
	v_mul_f32_e32 v72, v212, v204
	v_mul_f32_e32 v73, v213, v205
	s_waitcnt lgkmcnt(0)
	v_sub_f32_e32 v218, v126, v218
	v_sub_f32_e32 v219, v126, v219
	v_sub_f32_e32 v220, v126, v220
	v_sub_f32_e32 v221, v126, v221
	v_mul_f32_e32 v218, 0x3fb8aa3b, v218
	v_mul_f32_e32 v219, 0x3fb8aa3b, v219
	v_mul_f32_e32 v220, 0x3fb8aa3b, v220
	v_mul_f32_e32 v221, 0x3fb8aa3b, v221
	v_exp_f32_e32 v218, v218
	v_exp_f32_e32 v219, v219
	v_exp_f32_e32 v220, v220
	v_exp_f32_e32 v221, v221
	v_mul_f32_e32 v74, v226, v218
	v_mul_f32_e32 v75, v227, v219
	v_mul_f32_e32 v76, v228, v220
	v_mul_f32_e32 v77, v229, v221
	s_branch .Lssdb2_done
.Lssdb2_gt:
	ds_read_b128 v[170:173], v236 offset:36608
	ds_read_b128 v[178:181], v236 offset:37632
	ds_read_b128 v[186:189], v236 offset:36640
	ds_read_b128 v[194:197], v236 offset:37664
	ds_read_b128 v[202:205], v236 offset:36672
	ds_read_b128 v[210:213], v236 offset:37696
	ds_read_b128 v[218:221], v236 offset:36704
	ds_read_b128 v[226:229], v236 offset:37728
	s_waitcnt lgkmcnt(6)
	v_sub_f32_e32 v170, v127, v170
	v_sub_f32_e32 v171, v127, v171
	v_sub_f32_e32 v172, v127, v172
	v_sub_f32_e32 v173, v127, v173
	v_mul_f32_e32 v170, 0x3fb8aa3b, v170
	v_mul_f32_e32 v171, 0x3fb8aa3b, v171
	v_mul_f32_e32 v172, 0x3fb8aa3b, v172
	v_mul_f32_e32 v173, 0x3fb8aa3b, v173
	v_exp_f32_e32 v170, v170
	v_exp_f32_e32 v171, v171
	v_exp_f32_e32 v172, v172
	v_exp_f32_e32 v173, v173
	v_mul_f32_e32 v58, v178, v170
	v_mul_f32_e32 v59, v179, v171
	v_mul_f32_e32 v64, v180, v172
	v_mul_f32_e32 v65, v181, v173
	s_waitcnt lgkmcnt(4)
	v_sub_f32_e32 v186, v127, v186
	v_sub_f32_e32 v187, v127, v187
	v_sub_f32_e32 v188, v127, v188
	v_sub_f32_e32 v189, v127, v189
	v_mul_f32_e32 v186, 0x3fb8aa3b, v186
	v_mul_f32_e32 v187, 0x3fb8aa3b, v187
	v_mul_f32_e32 v188, 0x3fb8aa3b, v188
	v_mul_f32_e32 v189, 0x3fb8aa3b, v189
	v_exp_f32_e32 v186, v186
	v_exp_f32_e32 v187, v187
	v_exp_f32_e32 v188, v188
	v_exp_f32_e32 v189, v189
	v_mul_f32_e32 v66, v194, v186
	v_mul_f32_e32 v67, v195, v187
	v_mul_f32_e32 v68, v196, v188
	v_mul_f32_e32 v70, v197, v189
	s_waitcnt lgkmcnt(2)
	v_sub_f32_e32 v202, v127, v202
	v_sub_f32_e32 v203, v127, v203
	v_sub_f32_e32 v204, v127, v204
	v_sub_f32_e32 v205, v127, v205
	v_mul_f32_e32 v202, 0x3fb8aa3b, v202
	v_mul_f32_e32 v203, 0x3fb8aa3b, v203
	v_mul_f32_e32 v204, 0x3fb8aa3b, v204
	v_mul_f32_e32 v205, 0x3fb8aa3b, v205
	v_exp_f32_e32 v202, v202
	v_exp_f32_e32 v203, v203
	v_exp_f32_e32 v204, v204
	v_exp_f32_e32 v205, v205
	v_mul_f32_e32 v69, v210, v202
	v_mul_f32_e32 v71, v211, v203
	v_mul_f32_e32 v72, v212, v204
	v_mul_f32_e32 v73, v213, v205
	s_waitcnt lgkmcnt(0)
	v_sub_f32_e32 v218, v127, v218
	v_sub_f32_e32 v219, v127, v219
	v_sub_f32_e32 v220, v127, v220
	v_sub_f32_e32 v221, v127, v221
	v_mul_f32_e32 v218, 0x3fb8aa3b, v218
	v_mul_f32_e32 v219, 0x3fb8aa3b, v219
	v_mul_f32_e32 v220, 0x3fb8aa3b, v220
	v_mul_f32_e32 v221, 0x3fb8aa3b, v221
	v_exp_f32_e32 v218, v218
	v_exp_f32_e32 v219, v219
	v_exp_f32_e32 v220, v220
	v_exp_f32_e32 v221, v221
	v_mul_f32_e32 v74, v226, v218
	v_mul_f32_e32 v75, v227, v219
	v_mul_f32_e32 v76, v228, v220
	v_mul_f32_e32 v77, v229, v221
.Lssdb2_done:
	v_mul_f32_e32 v70, v39, v70
	v_mul_f32_e32 v68, v38, v68
	v_mul_f32_e32 v67, v37, v67
	v_mul_f32_e32 v66, v36, v66
	ds_read2_b64 v[36:39], v62 offset0:16 offset1:18
	v_mul_f32_e32 v35, v35, v65
	v_mul_f32_e32 v34, v34, v64
	v_mul_f32_e32 v33, v33, v59
	v_mul_f32_e32 v32, v32, v58
	v_cvt_pk_bf16_f32 v32, v32, v33
	v_cvt_pk_bf16_f32 v33, v34, v35
	v_cvt_pk_bf16_f32 v34, v66, v67
	v_cvt_pk_bf16_f32 v35, v68, v70
	v_mul_f32_e32 v58, v45, v75
	v_mul_f32_e32 v59, v44, v74
	s_waitcnt lgkmcnt(0)
	v_mfma_f32_32x32x16_bf16 v[16:31], v[36:39], v[32:35], v[16:31]
	ds_read2_b64 v[36:39], v63 offset0:80 offset1:82
	v_mul_f32_e32 v64, v43, v73
	v_mul_f32_e32 v65, v42, v72
	ds_read2_b64 v[42:45], v62 offset0:20 offset1:22
	v_mul_f32_e32 v46, v46, v76
	s_waitcnt lgkmcnt(1)
	v_mfma_f32_32x32x16_bf16 v[0:15], v[36:39], v[32:35], v[0:15]
	ds_read2_b64 v[36:39], v63 offset0:84 offset1:86
	v_mul_f32_e32 v32, v41, v71
	v_mul_f32_e32 v33, v40, v69
	v_mul_f32_e32 v35, v47, v77
	v_cvt_pk_bf16_f32 v32, v33, v32
	v_cvt_pk_bf16_f32 v33, v65, v64
	v_cvt_pk_bf16_f32 v34, v59, v58
	v_cvt_pk_bf16_f32 v35, v46, v35
	v_or_b32_e32 v58, 0x60, v110
	v_cmp_ge_u32_e32 vcc, v58, v53
	s_waitcnt lgkmcnt(1)
	v_mfma_f32_32x32x16_bf16 v[16:31], v[42:45], v[32:35], v[16:31]
	s_waitcnt lgkmcnt(0)
	v_mfma_f32_32x32x16_bf16 v[0:15], v[36:39], v[32:35], v[0:15]
	ds_read_b128 v[32:35], v57 offset:31232
	ds_read_b128 v[64:67], v57 offset:31264
	s_waitcnt lgkmcnt(1)
	v_mfma_f32_32x32x16_bf16 v[32:47], v[32:35], v[48:51], 0
	s_waitcnt lgkmcnt(0)
	v_mfma_f32_32x32x16_bf16 v[32:47], v[64:67], v[102:105], v[32:47]
	ds_read_b128 v[64:67], v57 offset:31296
	ds_read_b128 v[68:71], v57 offset:31328
	s_waitcnt lgkmcnt(1)
	v_mfma_f32_32x32x16_bf16 v[32:47], v[64:67], v[98:101], v[32:47]
	s_waitcnt lgkmcnt(0)
	v_mfma_f32_32x32x16_bf16 v[32:47], v[68:71], v[94:97], v[32:47]
	v_lshl_add_u32 v236, v110, 2, s23
	v_lshrrev_b32_e32 v239, 5, v53
	s_nop 0
	v_readfirstlane_b32 s0, v239
	s_cmp_gt_u32 s0, 3
	s_cbranch_scc1 .Lssdb3_lt
	s_cmp_lt_u32 s0, 3
	s_cbranch_scc1 .Lssdb3_gt
	v_sub_u32_e32 v237, v53, v110
	ds_read_b128 v[170:173], v236 offset:36224
	ds_read_b128 v[174:177], v236 offset:36736
	ds_read_b128 v[178:181], v236 offset:37248
	ds_read_b128 v[182:185], v236 offset:37760
	ds_read_b128 v[186:189], v236 offset:36256
	ds_read_b128 v[190:193], v236 offset:36768
	ds_read_b128 v[194:197], v236 offset:37280
	ds_read_b128 v[198:201], v236 offset:37792
	ds_read_b128 v[202:205], v236 offset:36288
	ds_read_b128 v[206:209], v236 offset:36800
	ds_read_b128 v[210:213], v236 offset:37312
	ds_read_b128 v[214:217], v236 offset:37824
	s_waitcnt lgkmcnt(8)
	ds_read_b128 v[218:221], v236 offset:36320
	ds_read_b128 v[222:225], v236 offset:36832
	ds_read_b128 v[226:229], v236 offset:37344
	ds_read_b128 v[230:233], v236 offset:37856
	v_add_u32_e32 v238, 0xffffffa0, v237
	v_cmp_lt_i32_e32 vcc, 0, v238
	v_cmp_lt_i32_e64 s[0:1], 1, v238
	v_cmp_lt_i32_e64 s[4:5], 2, v238
	v_cmp_lt_i32_e64 s[66:67], 3, v238
	v_sub_f32_e32 v170, v126, v170
	v_sub_f32_e32 v171, v126, v171
	v_sub_f32_e32 v172, v126, v172
	v_sub_f32_e32 v173, v126, v173
	v_sub_f32_e32 v174, v127, v174
	v_sub_f32_e32 v175, v127, v175
	v_sub_f32_e32 v176, v127, v176
	v_sub_f32_e32 v177, v127, v177
	v_cndmask_b32_e64 v170, v174, v170, vcc
	v_cndmask_b32_e64 v171, v175, v171, s[0:1]
	v_cndmask_b32_e64 v172, v176, v172, s[4:5]
	v_cndmask_b32_e64 v173, v177, v173, s[66:67]
	v_add_f32_e32 v174, v178, v182
	v_add_f32_e32 v175, v179, v183
	v_add_f32_e32 v176, v180, v184
	v_add_f32_e32 v177, v181, v185
	v_cndmask_b32_e64 v178, v182, v178, vcc
	v_cndmask_b32_e64 v179, v183, v179, s[0:1]
	v_cndmask_b32_e64 v180, v184, v180, s[4:5]
	v_cndmask_b32_e64 v181, v185, v181, s[66:67]
	v_cmp_eq_u32_e32 vcc, 0, v238
	v_cmp_eq_u32_e64 s[0:1], 1, v238
	v_cmp_eq_u32_e64 s[4:5], 2, v238
	v_cmp_eq_u32_e64 s[66:67], 3, v238
	v_mul_f32_e32 v170, 0x3fb8aa3b, v170
	v_mul_f32_e32 v171, 0x3fb8aa3b, v171
	v_mul_f32_e32 v172, 0x3fb8aa3b, v172
	v_mul_f32_e32 v173, 0x3fb8aa3b, v173
	v_exp_f32_e32 v170, v170
	v_exp_f32_e32 v171, v171
	v_exp_f32_e32 v172, v172
	v_exp_f32_e32 v173, v173
	v_mul_f32_e32 v178, v178, v170
	v_mul_f32_e32 v179, v179, v171
	v_mul_f32_e32 v180, v180, v172
	v_mul_f32_e32 v181, v181, v173
	v_cndmask_b32_e64 v57, v178, v174, vcc
	v_cndmask_b32_e64 v58, v179, v175, s[0:1]
	v_cndmask_b32_e64 v59, v180, v176, s[4:5]
	v_cndmask_b32_e64 v64, v181, v177, s[66:67]
	s_waitcnt lgkmcnt(8)
	v_add_u32_e32 v238, 0xffffff98, v237
	v_cmp_lt_i32_e32 vcc, 0, v238
	v_cmp_lt_i32_e64 s[0:1], 1, v238
	v_cmp_lt_i32_e64 s[4:5], 2, v238
	v_cmp_lt_i32_e64 s[66:67], 3, v238
	v_sub_f32_e32 v186, v126, v186
	v_sub_f32_e32 v187, v126, v187
	v_sub_f32_e32 v188, v126, v188
	v_sub_f32_e32 v189, v126, v189
	v_sub_f32_e32 v190, v127, v190
	v_sub_f32_e32 v191, v127, v191
	v_sub_f32_e32 v192, v127, v192
	v_sub_f32_e32 v193, v127, v193
	v_cndmask_b32_e64 v186, v190, v186, vcc
	v_cndmask_b32_e64 v187, v191, v187, s[0:1]
	v_cndmask_b32_e64 v188, v192, v188, s[4:5]
	v_cndmask_b32_e64 v189, v193, v189, s[66:67]
	v_add_f32_e32 v190, v194, v198
	v_add_f32_e32 v191, v195, v199
	v_add_f32_e32 v192, v196, v200
	v_add_f32_e32 v193, v197, v201
	v_cndmask_b32_e64 v194, v198, v194, vcc
	v_cndmask_b32_e64 v195, v199, v195, s[0:1]
	v_cndmask_b32_e64 v196, v200, v196, s[4:5]
	v_cndmask_b32_e64 v197, v201, v197, s[66:67]
	v_cmp_eq_u32_e32 vcc, 0, v238
	v_cmp_eq_u32_e64 s[0:1], 1, v238
	v_cmp_eq_u32_e64 s[4:5], 2, v238
	v_cmp_eq_u32_e64 s[66:67], 3, v238
	v_mul_f32_e32 v186, 0x3fb8aa3b, v186
	v_mul_f32_e32 v187, 0x3fb8aa3b, v187
	v_mul_f32_e32 v188, 0x3fb8aa3b, v188
	v_mul_f32_e32 v189, 0x3fb8aa3b, v189
	v_exp_f32_e32 v186, v186
	v_exp_f32_e32 v187, v187
	v_exp_f32_e32 v188, v188
	v_exp_f32_e32 v189, v189
	v_mul_f32_e32 v194, v194, v186
	v_mul_f32_e32 v195, v195, v187
	v_mul_f32_e32 v196, v196, v188
	v_mul_f32_e32 v197, v197, v189
	v_cndmask_b32_e64 v56, v194, v190, vcc
	v_cndmask_b32_e64 v65, v195, v191, s[0:1]
	v_cndmask_b32_e64 v66, v196, v192, s[4:5]
	v_cndmask_b32_e64 v67, v197, v193, s[66:67]
	s_waitcnt lgkmcnt(4)
	v_add_u32_e32 v238, 0xffffff90, v237
	v_cmp_lt_i32_e32 vcc, 0, v238
	v_cmp_lt_i32_e64 s[0:1], 1, v238
	v_cmp_lt_i32_e64 s[4:5], 2, v238
	v_cmp_lt_i32_e64 s[66:67], 3, v238
	v_sub_f32_e32 v202, v126, v202
	v_sub_f32_e32 v203, v126, v203
	v_sub_f32_e32 v204, v126, v204
	v_sub_f32_e32 v205, v126, v205
	v_sub_f32_e32 v206, v127, v206
	v_sub_f32_e32 v207, v127, v207
	v_sub_f32_e32 v208, v127, v208
	v_sub_f32_e32 v209, v127, v209
	v_cndmask_b32_e64 v202, v206, v202, vcc
	v_cndmask_b32_e64 v203, v207, v203, s[0:1]
	v_cndmask_b32_e64 v204, v208, v204, s[4:5]
	v_cndmask_b32_e64 v205, v209, v205, s[66:67]
	v_add_f32_e32 v206, v210, v214
	v_add_f32_e32 v207, v211, v215
	v_add_f32_e32 v208, v212, v216
	v_add_f32_e32 v209, v213, v217
	v_cndmask_b32_e64 v210, v214, v210, vcc
	v_cndmask_b32_e64 v211, v215, v211, s[0:1]
	v_cndmask_b32_e64 v212, v216, v212, s[4:5]
	v_cndmask_b32_e64 v213, v217, v213, s[66:67]
	v_cmp_eq_u32_e32 vcc, 0, v238
	v_cmp_eq_u32_e64 s[0:1], 1, v238
	v_cmp_eq_u32_e64 s[4:5], 2, v238
	v_cmp_eq_u32_e64 s[66:67], 3, v238
	v_mul_f32_e32 v202, 0x3fb8aa3b, v202
	v_mul_f32_e32 v203, 0x3fb8aa3b, v203
	v_mul_f32_e32 v204, 0x3fb8aa3b, v204
	v_mul_f32_e32 v205, 0x3fb8aa3b, v205
	v_exp_f32_e32 v202, v202
	v_exp_f32_e32 v203, v203
	v_exp_f32_e32 v204, v204
	v_exp_f32_e32 v205, v205
	v_mul_f32_e32 v210, v210, v202
	v_mul_f32_e32 v211, v211, v203
	v_mul_f32_e32 v212, v212, v204
	v_mul_f32_e32 v213, v213, v205
	v_cndmask_b32_e64 v68, v210, v206, vcc
	v_cndmask_b32_e64 v69, v211, v207, s[0:1]
	v_cndmask_b32_e64 v70, v212, v208, s[4:5]
	v_cndmask_b32_e64 v71, v213, v209, s[66:67]
	s_waitcnt lgkmcnt(0)
	v_add_u32_e32 v238, 0xffffff88, v237
	v_cmp_lt_i32_e32 vcc, 0, v238
	v_cmp_lt_i32_e64 s[0:1], 1, v238
	v_cmp_lt_i32_e64 s[4:5], 2, v238
	v_cmp_lt_i32_e64 s[66:67], 3, v238
	v_sub_f32_e32 v218, v126, v218
	v_sub_f32_e32 v219, v126, v219
	v_sub_f32_e32 v220, v126, v220
	v_sub_f32_e32 v221, v126, v221
	v_sub_f32_e32 v222, v127, v222
	v_sub_f32_e32 v223, v127, v223
	v_sub_f32_e32 v224, v127, v224
	v_sub_f32_e32 v225, v127, v225
	v_cndmask_b32_e64 v218, v222, v218, vcc
	v_cndmask_b32_e64 v219, v223, v219, s[0:1]
	v_cndmask_b32_e64 v220, v224, v220, s[4:5]
	v_cndmask_b32_e64 v221, v225, v221, s[66:67]
	v_add_f32_e32 v222, v226, v230
	v_add_f32_e32 v223, v227, v231
	v_add_f32_e32 v224, v228, v232
	v_add_f32_e32 v225, v229, v233
	v_cndmask_b32_e64 v226, v230, v226, vcc
	v_cndmask_b32_e64 v227, v231, v227, s[0:1]
	v_cndmask_b32_e64 v228, v232, v228, s[4:5]
	v_cndmask_b32_e64 v229, v233, v229, s[66:67]
	v_cmp_eq_u32_e32 vcc, 0, v238
	v_cmp_eq_u32_e64 s[0:1], 1, v238
	v_cmp_eq_u32_e64 s[4:5], 2, v238
	v_cmp_eq_u32_e64 s[66:67], 3, v238
	v_mul_f32_e32 v218, 0x3fb8aa3b, v218
	v_mul_f32_e32 v219, 0x3fb8aa3b, v219
	v_mul_f32_e32 v220, 0x3fb8aa3b, v220
	v_mul_f32_e32 v221, 0x3fb8aa3b, v221
	v_exp_f32_e32 v218, v218
	v_exp_f32_e32 v219, v219
	v_exp_f32_e32 v220, v220
	v_exp_f32_e32 v221, v221
	v_mul_f32_e32 v226, v226, v218
	v_mul_f32_e32 v227, v227, v219
	v_mul_f32_e32 v228, v228, v220
	v_mul_f32_e32 v229, v229, v221
	v_cndmask_b32_e64 v72, v226, v222, vcc
	v_cndmask_b32_e64 v73, v227, v223, s[0:1]
	v_cndmask_b32_e64 v75, v228, v224, s[4:5]
	v_cndmask_b32_e64 v74, v229, v225, s[66:67]
	s_branch .Lssdb3_done
.Lssdb3_lt:
	ds_read_b128 v[170:173], v236 offset:36224
	ds_read_b128 v[178:181], v236 offset:37248
	ds_read_b128 v[186:189], v236 offset:36256
	ds_read_b128 v[194:197], v236 offset:37280
	ds_read_b128 v[202:205], v236 offset:36288
	ds_read_b128 v[210:213], v236 offset:37312
	ds_read_b128 v[218:221], v236 offset:36320
	ds_read_b128 v[226:229], v236 offset:37344
	s_waitcnt lgkmcnt(6)
	v_sub_f32_e32 v170, v126, v170
	v_sub_f32_e32 v171, v126, v171
	v_sub_f32_e32 v172, v126, v172
	v_sub_f32_e32 v173, v126, v173
	v_mul_f32_e32 v170, 0x3fb8aa3b, v170
	v_mul_f32_e32 v171, 0x3fb8aa3b, v171
	v_mul_f32_e32 v172, 0x3fb8aa3b, v172
	v_mul_f32_e32 v173, 0x3fb8aa3b, v173
	v_exp_f32_e32 v170, v170
	v_exp_f32_e32 v171, v171
	v_exp_f32_e32 v172, v172
	v_exp_f32_e32 v173, v173
	v_mul_f32_e32 v57, v178, v170
	v_mul_f32_e32 v58, v179, v171
	v_mul_f32_e32 v59, v180, v172
	v_mul_f32_e32 v64, v181, v173
	s_waitcnt lgkmcnt(4)
	v_sub_f32_e32 v186, v126, v186
	v_sub_f32_e32 v187, v126, v187
	v_sub_f32_e32 v188, v126, v188
	v_sub_f32_e32 v189, v126, v189
	v_mul_f32_e32 v186, 0x3fb8aa3b, v186
	v_mul_f32_e32 v187, 0x3fb8aa3b, v187
	v_mul_f32_e32 v188, 0x3fb8aa3b, v188
	v_mul_f32_e32 v189, 0x3fb8aa3b, v189
	v_exp_f32_e32 v186, v186
	v_exp_f32_e32 v187, v187
	v_exp_f32_e32 v188, v188
	v_exp_f32_e32 v189, v189
	v_mul_f32_e32 v56, v194, v186
	v_mul_f32_e32 v65, v195, v187
	v_mul_f32_e32 v66, v196, v188
	v_mul_f32_e32 v67, v197, v189
	s_waitcnt lgkmcnt(2)
	v_sub_f32_e32 v202, v126, v202
	v_sub_f32_e32 v203, v126, v203
	v_sub_f32_e32 v204, v126, v204
	v_sub_f32_e32 v205, v126, v205
	v_mul_f32_e32 v202, 0x3fb8aa3b, v202
	v_mul_f32_e32 v203, 0x3fb8aa3b, v203
	v_mul_f32_e32 v204, 0x3fb8aa3b, v204
	v_mul_f32_e32 v205, 0x3fb8aa3b, v205
	v_exp_f32_e32 v202, v202
	v_exp_f32_e32 v203, v203
	v_exp_f32_e32 v204, v204
	v_exp_f32_e32 v205, v205
	v_mul_f32_e32 v68, v210, v202
	v_mul_f32_e32 v69, v211, v203
	v_mul_f32_e32 v70, v212, v204
	v_mul_f32_e32 v71, v213, v205
	s_waitcnt lgkmcnt(0)
	v_sub_f32_e32 v218, v126, v218
	v_sub_f32_e32 v219, v126, v219
	v_sub_f32_e32 v220, v126, v220
	v_sub_f32_e32 v221, v126, v221
	v_mul_f32_e32 v218, 0x3fb8aa3b, v218
	v_mul_f32_e32 v219, 0x3fb8aa3b, v219
	v_mul_f32_e32 v220, 0x3fb8aa3b, v220
	v_mul_f32_e32 v221, 0x3fb8aa3b, v221
	v_exp_f32_e32 v218, v218
	v_exp_f32_e32 v219, v219
	v_exp_f32_e32 v220, v220
	v_exp_f32_e32 v221, v221
	v_mul_f32_e32 v72, v226, v218
	v_mul_f32_e32 v73, v227, v219
	v_mul_f32_e32 v75, v228, v220
	v_mul_f32_e32 v74, v229, v221
	s_branch .Lssdb3_done
.Lssdb3_gt:
	ds_read_b128 v[170:173], v236 offset:36736
	ds_read_b128 v[178:181], v236 offset:37760
	ds_read_b128 v[186:189], v236 offset:36768
	ds_read_b128 v[194:197], v236 offset:37792
	ds_read_b128 v[202:205], v236 offset:36800
	ds_read_b128 v[210:213], v236 offset:37824
	ds_read_b128 v[218:221], v236 offset:36832
	ds_read_b128 v[226:229], v236 offset:37856
	s_waitcnt lgkmcnt(6)
	v_sub_f32_e32 v170, v127, v170
	v_sub_f32_e32 v171, v127, v171
	v_sub_f32_e32 v172, v127, v172
	v_sub_f32_e32 v173, v127, v173
	v_mul_f32_e32 v170, 0x3fb8aa3b, v170
	v_mul_f32_e32 v171, 0x3fb8aa3b, v171
	v_mul_f32_e32 v172, 0x3fb8aa3b, v172
	v_mul_f32_e32 v173, 0x3fb8aa3b, v173
	v_exp_f32_e32 v170, v170
	v_exp_f32_e32 v171, v171
	v_exp_f32_e32 v172, v172
	v_exp_f32_e32 v173, v173
	v_mul_f32_e32 v57, v178, v170
	v_mul_f32_e32 v58, v179, v171
	v_mul_f32_e32 v59, v180, v172
	v_mul_f32_e32 v64, v181, v173
	s_waitcnt lgkmcnt(4)
	v_sub_f32_e32 v186, v127, v186
	v_sub_f32_e32 v187, v127, v187
	v_sub_f32_e32 v188, v127, v188
	v_sub_f32_e32 v189, v127, v189
	v_mul_f32_e32 v186, 0x3fb8aa3b, v186
	v_mul_f32_e32 v187, 0x3fb8aa3b, v187
	v_mul_f32_e32 v188, 0x3fb8aa3b, v188
	v_mul_f32_e32 v189, 0x3fb8aa3b, v189
	v_exp_f32_e32 v186, v186
	v_exp_f32_e32 v187, v187
	v_exp_f32_e32 v188, v188
	v_exp_f32_e32 v189, v189
	v_mul_f32_e32 v56, v194, v186
	v_mul_f32_e32 v65, v195, v187
	v_mul_f32_e32 v66, v196, v188
	v_mul_f32_e32 v67, v197, v189
	s_waitcnt lgkmcnt(2)
	v_sub_f32_e32 v202, v127, v202
	v_sub_f32_e32 v203, v127, v203
	v_sub_f32_e32 v204, v127, v204
	v_sub_f32_e32 v205, v127, v205
	v_mul_f32_e32 v202, 0x3fb8aa3b, v202
	v_mul_f32_e32 v203, 0x3fb8aa3b, v203
	v_mul_f32_e32 v204, 0x3fb8aa3b, v204
	v_mul_f32_e32 v205, 0x3fb8aa3b, v205
	v_exp_f32_e32 v202, v202
	v_exp_f32_e32 v203, v203
	v_exp_f32_e32 v204, v204
	v_exp_f32_e32 v205, v205
	v_mul_f32_e32 v68, v210, v202
	v_mul_f32_e32 v69, v211, v203
	v_mul_f32_e32 v70, v212, v204
	v_mul_f32_e32 v71, v213, v205
	s_waitcnt lgkmcnt(0)
	v_sub_f32_e32 v218, v127, v218
	v_sub_f32_e32 v219, v127, v219
	v_sub_f32_e32 v220, v127, v220
	v_sub_f32_e32 v221, v127, v221
	v_mul_f32_e32 v218, 0x3fb8aa3b, v218
	v_mul_f32_e32 v219, 0x3fb8aa3b, v219
	v_mul_f32_e32 v220, 0x3fb8aa3b, v220
	v_mul_f32_e32 v221, 0x3fb8aa3b, v221
	v_exp_f32_e32 v218, v218
	v_exp_f32_e32 v219, v219
	v_exp_f32_e32 v220, v220
	v_exp_f32_e32 v221, v221
	v_mul_f32_e32 v72, v226, v218
	v_mul_f32_e32 v73, v227, v219
	v_mul_f32_e32 v75, v228, v220
	v_mul_f32_e32 v74, v229, v221
.Lssdb3_done:
	s_lshl_b32 s0, s77, 6
	s_mul_i32 s1, s79, 34
	s_add_i32 s4, s1, s78
	s_ashr_i32 s5, s4, 31
	s_lshl_b64 s[4:5], s[4:5], 16
	s_lshl_b32 s1, s77, 13
	s_add_u32 s40, s55, s1
	s_addc_u32 s41, s63, 0
	v_lshlrev_b32_e32 v122, 1, v54
	v_lshl_add_u64 v[54:55], s[40:41], 0, v[122:123]
	v_lshl_add_u64 v[54:55], v[54:55], 0, s[4:5]
	v_lshlrev_b32_e32 v122, 7, v52
	v_lshl_add_u64 v[92:93], v[54:55], 0, v[122:123]
	global_load_dwordx4 v[76:79], v[92:93], off
	v_mov_b32_e32 v107, v123
	v_or_b32_e32 v106, 0x1000, v122
	s_mov_b64 s[4:5], 0x880000
	v_lshl_add_u64 v[112:113], v[54:55], 0, v[106:107]
	v_lshl_add_u64 v[108:109], v[54:55], 0, s[4:5]
	global_load_dwordx4 v[52:55], v[92:93], off offset:32
	global_load_dwordx4 v[80:83], v[112:113], off
	global_load_dwordx4 v[138:141], v[92:93], off offset:64
	v_mul_f32_e32 v46, v46, v75
	v_mul_f32_e32 v45, v45, v73
	v_mul_f32_e32 v73, v37, v65
	v_mul_f32_e32 v56, v36, v56
	v_mul_f32_e32 v75, v35, v64
	v_mul_f32_e32 v59, v34, v59
	v_mul_f32_e32 v33, v33, v58
	v_mul_f32_e32 v32, v32, v57
	v_cvt_pk_bf16_f32 v89, v59, v75
	v_cvt_pk_bf16_f32 v90, v56, v73
	global_load_dwordx4 v[56:59], v[112:113], off offset:32
	global_load_dwordx4 v[142:145], v[112:113], off offset:64
	v_lshl_add_u64 v[114:115], v[108:109], 0, v[122:123]
	global_load_dwordx4 v[84:87], v[114:115], off
	global_load_dwordx4 v[134:137], v[114:115], off offset:32
	ds_read2_b64 v[34:37], v62 offset0:24 offset1:26
	v_mul_f32_e32 v39, v39, v67
	v_mul_f32_e32 v38, v38, v66
	ds_read2_b64 v[64:67], v63 offset0:88 offset1:90
	v_cvt_pk_bf16_f32 v88, v32, v33
	v_cvt_pk_bf16_f32 v91, v38, v39
	v_mul_f32_e32 v44, v44, v72
	v_mul_f32_e32 v43, v43, v71
	s_waitcnt lgkmcnt(1)
	v_mfma_f32_32x32x16_bf16 v[16:31], v[34:37], v[88:91], v[16:31]
	ds_read2_b64 v[32:35], v62 offset0:28 offset1:30
	ds_read2_b64 v[36:39], v63 offset0:92 offset1:94
	global_load_dwordx4 v[146:149], v[92:93], off offset:96
	global_load_dwordx4 v[170:173], v[112:113], off offset:96
	global_load_dwordx4 v[174:177], v[114:115], off offset:64
	v_mul_f32_e32 v42, v42, v70
	v_mul_f32_e32 v41, v41, v69
	v_mul_f32_e32 v40, v40, v68
	s_waitcnt lgkmcnt(2)
	v_mfma_f32_32x32x16_bf16 v[0:15], v[64:67], v[88:91], v[0:15]
	v_mul_f32_e32 v47, v47, v74
	s_movk_i32 s1, 0x1360
	global_load_dwordx4 v[118:121], v[114:115], off offset:96
	s_lshl_b32 s60, s0, 1
	v_lshlrev_b32_e32 v122, 1, v110
	v_lshl_add_u64 v[106:107], v[108:109], 0, v[106:107]
	v_cvt_pk_bf16_f32 v40, v40, v41
	v_cvt_pk_bf16_f32 v41, v42, v43
	v_cvt_pk_bf16_f32 v42, v44, v45
	v_cvt_pk_bf16_f32 v43, v46, v47
	v_ashrrev_i32_e32 v125, 31, v124
	s_waitcnt vmcnt(11)
	v_mfma_f32_32x32x16_bf16 v[62:77], v[76:79], v[48:51], 0
	v_mov_b64_e32 v[78:79], s[6:7]
	v_mad_i64_i32 v[178:179], s[4:5], v124, s1, v[78:79]
	v_lshl_add_u64 v[112:113], v[178:179], 0, s[60:61]
	v_lshl_add_u64 v[150:151], v[112:113], 0, v[122:123]
	v_add_co_u32_e32 v110, vcc, s73, v150
	s_waitcnt vmcnt(10)
	v_mfma_f32_32x32x16_bf16 v[62:77], v[52:55], v[102:105], v[62:77]
	v_addc_co_u32_e32 v111, vcc, 0, v151, vcc
	global_load_dwordx2 v[162:163], v[110:111], off offset:2368
	global_load_dwordx4 v[52:55], v[106:107], off
	global_load_dwordx4 v[114:117], v[106:107], off offset:32
	s_lshl_b32 s4, s77, 2
	global_load_dwordx4 v[110:113], v[106:107], off offset:64
	s_waitcnt lgkmcnt(1)
	v_mfma_f32_32x32x16_bf16 v[16:31], v[32:35], v[40:43], v[16:31]
	s_mov_b64 s[0:1], 0x54dc940
	s_waitcnt vmcnt(3)
	v_lshlrev_b32_e32 v169, 16, v162
	s_waitcnt lgkmcnt(0)
	v_mfma_f32_32x32x16_bf16 v[0:15], v[36:39], v[40:43], v[0:15]
	v_and_b32_e32 v162, 0xffff0000, v162
	v_mfma_f32_32x32x16_bf16 v[32:47], v[80:83], v[48:51], 0
	v_mfma_f32_32x32x16_bf16 v[32:47], v[56:59], v[102:105], v[32:47]
	v_lshl_add_u64 v[56:57], v[60:61], 0, s[60:61]
	v_lshl_add_u64 v[56:57], v[56:57], 0, v[122:123]
	global_load_dwordx2 v[160:161], v[56:57], off
	v_mov_b32_e32 v58, s4
	global_load_dword v128, v58, s[16:17]
	v_mul_f32_e32 v58, 0x3fb8aa3b, v126
	global_load_dwordx4 v[106:109], v[106:107], off offset:96
	v_mfma_f32_32x32x16_bf16 v[78:93], v[84:87], v[48:51], 0
	v_mul_f32_e32 v59, 0x3fb8aa3b, v127
	v_exp_f32_e32 v130, v58
	v_exp_f32_e32 v132, v59
	v_lshl_add_u64 v[58:59], v[150:151], 0, s[0:1]
	v_mfma_f32_32x32x16_bf16 v[78:93], v[134:137], v[102:105], v[78:93]
	v_mfma_f32_32x32x16_bf16 v[62:77], v[138:141], v[98:101], v[62:77]
	v_mfma_f32_32x32x16_bf16 v[32:47], v[142:145], v[98:101], v[32:47]
	v_mfma_f32_32x32x16_bf16 v[62:77], v[146:149], v[94:97], v[62:77]
	global_load_dwordx2 v[156:157], v[56:57], off offset:16
	global_load_dwordx2 v[152:153], v[56:57], off offset:32
	global_load_dwordx2 v[148:149], v[56:57], off offset:48
	global_load_dwordx2 v[144:145], v[56:57], off offset:64
	global_load_dwordx2 v[140:141], v[56:57], off offset:80
	global_load_dwordx2 v[136:137], v[56:57], off offset:96
	global_load_dwordx2 v[126:127], v[56:57], off offset:112
	global_load_dwordx2 v[158:159], v[58:59], off offset:16
	global_load_dwordx2 v[154:155], v[58:59], off offset:32
	global_load_dwordx2 v[150:151], v[58:59], off offset:48
	global_load_dwordx2 v[146:147], v[58:59], off offset:64
	global_load_dwordx2 v[142:143], v[58:59], off offset:80
	global_load_dwordx2 v[138:139], v[58:59], off offset:96
	global_load_dwordx2 v[134:135], v[58:59], off offset:112
	v_mul_f32_e32 v58, 0xbfb8aa3b, v169
	v_mul_f32_e32 v59, 0xbfb8aa3b, v162
	v_exp_f32_e32 v58, v58
	v_exp_f32_e32 v59, v59
	v_mfma_f32_32x32x16_bf16 v[78:93], v[174:177], v[98:101], v[78:93]
	v_mad_i64_i32 v[56:57], s[0:1], v124, s74, v[178:179]
	v_fma_f32 v16, v130, v62, v16
	v_fma_f32 v17, v130, v63, v17
	v_fma_f32 v18, v130, v64, v18
	v_fma_f32 v19, v130, v65, v19
	v_mfma_f32_32x32x16_bf16 v[78:93], v[118:121], v[94:97], v[78:93]
	v_lshl_add_u64 v[118:119], v[56:57], 0, s[60:61]
	s_waitcnt vmcnt(16)
	v_lshlrev_b32_e32 v120, 16, v160
	s_nop 8
	v_pk_fma_f32 v[16:17], v[132:133], v[78:79], v[16:17] op_sel_hi:[0,1,1]
	v_pk_add_f32 v[78:79], v[58:59], 1.0 op_sel_hi:[1,0]
	v_mfma_f32_32x32x16_bf16 v[48:63], v[52:55], v[48:51], 0
	v_and_b32_e32 v121, 0xffff0000, v160
	s_waitcnt vmcnt(15)
	v_fma_f32 v16, v128, v120, v16
	v_fma_f32 v17, v128, v121, v17
	v_fma_f32 v18, v132, v80, v18
	v_fma_f32 v19, v132, v81, v19
	v_mfma_f32_32x32x16_bf16 v[48:63], v[114:117], v[102:105], v[48:63]
	v_div_scale_f32 v102, vcc, v162, v79, v162
	v_mfma_f32_32x32x16_bf16 v[32:47], v[170:173], v[94:97], v[32:47]
	v_div_scale_f32 v170, s[0:1], v79, v79, v162
	v_rcp_f32_e32 v171, v170
	s_nop 0
	v_fma_f32 v120, -v170, v171, 1.0
	v_mfma_f32_32x32x16_bf16 v[48:63], v[110:113], v[98:101], v[48:63]
	v_fmac_f32_e32 v171, v120, v171
	v_mul_f32_e32 v103, v102, v171
	v_div_scale_f32 v98, s[0:1], v78, v78, v169
	v_fma_f32 v104, -v170, v103, v102
	v_rcp_f32_e32 v99, v98
	v_fmac_f32_e32 v103, v104, v171
	v_fma_f32 v102, -v170, v103, v102
	v_div_fmas_f32 v100, v102, v171, v103
	v_div_fixup_f32 v79, v100, v79, v162
	v_fma_f32 v100, -v98, v99, 1.0
	v_fmac_f32_e32 v99, v100, v99
	s_waitcnt vmcnt(14)
	v_mfma_f32_32x32x16_bf16 v[48:63], v[106:109], v[94:97], v[48:63]
	v_div_scale_f32 v94, vcc, v169, v78, v169
	v_mul_f32_e32 v95, v94, v99
	v_fma_f32 v96, -v98, v95, v94
	v_fmac_f32_e32 v95, v96, v99
	v_fma_f32 v94, -v98, v95, v94
	v_div_fmas_f32 v94, v94, v99, v95
	v_lshlrev_b32_e32 v96, 16, v163
	v_and_b32_e32 v97, 0xffff0000, v163
	v_div_fixup_f32 v78, v94, v78, v169
	v_mul_f32_e32 v94, 0xbfb8aa3b, v96
	v_mul_f32_e32 v95, 0xbfb8aa3b, v97
	v_exp_f32_e32 v94, v94
	v_exp_f32_e32 v95, v95
	v_pk_mul_f32 v[16:17], v[16:17], v[78:79]
	v_lshlrev_b32_e32 v78, 16, v161
	v_and_b32_e32 v79, 0xffff0000, v161
	v_pk_add_f32 v[64:65], v[94:95], 1.0 op_sel_hi:[1,0]
	v_pk_fma_f32 v[18:19], v[128:129], v[78:79], v[18:19] op_sel_hi:[0,1,1]
	v_div_scale_f32 v80, s[0:1], v65, v65, v97
	v_rcp_f32_e32 v81, v80
	v_pk_fma_f32 v[0:1], v[130:131], v[32:33], v[0:1] op_sel_hi:[0,1,1]
	v_pk_fma_f32 v[0:1], v[132:133], v[48:49], v[0:1] op_sel_hi:[0,1,1]
	v_pk_fma_f32 v[2:3], v[130:131], v[34:35], v[2:3] op_sel_hi:[0,1,1]
	v_fma_f32 v78, -v80, v81, 1.0
	v_fmac_f32_e32 v81, v78, v81
	v_div_scale_f32 v78, vcc, v97, v65, v97
	v_mul_f32_e32 v79, v78, v81
	v_fma_f32 v94, -v80, v79, v78
	v_fmac_f32_e32 v79, v94, v81
	v_fma_f32 v78, -v80, v79, v78
	v_div_scale_f32 v80, s[0:1], v64, v64, v96
	v_rcp_f32_e32 v94, v80
	v_div_fmas_f32 v78, v78, v81, v79
	v_div_fixup_f32 v65, v78, v65, v97
	v_pk_fma_f32 v[2:3], v[132:133], v[50:51], v[2:3] op_sel_hi:[0,1,1]
	v_fma_f32 v78, -v80, v94, 1.0
	v_fmac_f32_e32 v94, v78, v94
	v_div_scale_f32 v78, vcc, v96, v64, v96
	v_mul_f32_e32 v79, v78, v94
	v_fma_f32 v81, -v80, v79, v78
	v_fmac_f32_e32 v79, v81, v94
	v_fma_f32 v78, -v80, v79, v78
	v_div_fmas_f32 v78, v78, v94, v79
	v_div_fixup_f32 v64, v78, v64, v96
	v_pk_mul_f32 v[18:19], v[18:19], v[64:65]
	v_cvt_pk_bf16_f32 v64, v16, v17
	v_and_b32_e32 v17, 0xffff0000, v64
	v_cvt_pk_bf16_f32 v65, v18, v19
	v_lshlrev_b32_e32 v16, 16, v64
	v_mul_f32_e32 v80, v17, v17
	s_waitcnt vmcnt(6)
	v_lshlrev_b32_e32 v81, 16, v158
	v_and_b32_e32 v94, 0xffff0000, v158
	v_lshlrev_b32_e32 v18, 16, v65
	v_fmac_f32_e32 v80, v16, v16
	v_mul_f32_e32 v78, 0xbfb8aa3b, v81
	v_mul_f32_e32 v79, 0xbfb8aa3b, v94
	v_and_b32_e32 v19, 0xffff0000, v65
	v_fmac_f32_e32 v80, v18, v18
	v_exp_f32_e32 v78, v78
	v_exp_f32_e32 v79, v79
	v_fmac_f32_e32 v80, v19, v19
	v_lshl_add_u64 v[18:19], v[118:119], 0, v[122:123]
	v_lshl_add_u64 v[16:17], v[18:19], 0, s[64:65]
	v_add_co_u32_e32 v18, vcc, s75, v18
	s_nop 1
	v_addc_co_u32_e32 v19, vcc, 0, v19, vcc
	global_store_dwordx2 v[18:19], v[64:65], off offset:1024
	v_pk_fma_f32 v[18:19], v[130:131], v[66:67], v[20:21] op_sel_hi:[0,1,1]
	v_pk_add_f32 v[20:21], v[78:79], 1.0 op_sel_hi:[1,0]
	v_pk_fma_f32 v[18:19], v[132:133], v[82:83], v[18:19] op_sel_hi:[0,1,1]
	v_div_scale_f32 v66, s[0:1], v21, v21, v94
	v_rcp_f32_e32 v67, v66
	v_lshlrev_b32_e32 v64, 16, v156
	v_and_b32_e32 v65, 0xffff0000, v156
	v_pk_fma_f32 v[18:19], v[128:129], v[64:65], v[18:19] op_sel_hi:[0,1,1]
	v_fma_f32 v64, -v66, v67, 1.0
	v_fmac_f32_e32 v67, v64, v67
	v_div_scale_f32 v64, vcc, v94, v21, v94
	v_mul_f32_e32 v65, v64, v67
	v_fma_f32 v78, -v66, v65, v64
	v_fmac_f32_e32 v65, v78, v67
	v_fma_f32 v64, -v66, v65, v64
	v_div_scale_f32 v66, s[0:1], v20, v20, v81
	v_rcp_f32_e32 v78, v66
	v_div_fmas_f32 v64, v64, v67, v65
	v_div_fixup_f32 v21, v64, v21, v94
	v_fma_f32 v64, -v66, v78, 1.0
	v_fmac_f32_e32 v78, v64, v78
	v_div_scale_f32 v64, vcc, v81, v20, v81
	v_mul_f32_e32 v65, v64, v78
	v_fma_f32 v67, -v66, v65, v64
	v_fmac_f32_e32 v65, v67, v78
	v_fma_f32 v64, -v66, v65, v64
	v_div_fmas_f32 v64, v64, v78, v65
	v_lshlrev_b32_e32 v66, 16, v159
	v_and_b32_e32 v67, 0xffff0000, v159
	v_div_fixup_f32 v20, v64, v20, v81
	v_mul_f32_e32 v64, 0xbfb8aa3b, v66
	v_mul_f32_e32 v65, 0xbfb8aa3b, v67
	v_exp_f32_e32 v64, v64
	v_exp_f32_e32 v65, v65
	v_pk_mul_f32 v[18:19], v[18:19], v[20:21]
	v_pk_fma_f32 v[20:21], v[130:131], v[68:69], v[22:23] op_sel_hi:[0,1,1]
	v_pk_fma_f32 v[20:21], v[132:133], v[84:85], v[20:21] op_sel_hi:[0,1,1]
	v_pk_add_f32 v[22:23], v[64:65], 1.0 op_sel_hi:[1,0]
	v_lshlrev_b32_e32 v64, 16, v157
	v_div_scale_f32 v68, s[0:1], v23, v23, v67
	v_rcp_f32_e32 v69, v68
	v_and_b32_e32 v65, 0xffff0000, v157
	v_pk_fma_f32 v[20:21], v[128:129], v[64:65], v[20:21] op_sel_hi:[0,1,1]
	v_cvt_pk_bf16_f32 v18, v18, v19
	v_fma_f32 v64, -v68, v69, 1.0
	v_fmac_f32_e32 v69, v64, v69
	v_div_scale_f32 v64, vcc, v67, v23, v67
	v_mul_f32_e32 v65, v64, v69
	v_fma_f32 v78, -v68, v65, v64
	v_fmac_f32_e32 v65, v78, v69
	v_fma_f32 v64, -v68, v65, v64
	v_div_scale_f32 v68, s[0:1], v22, v22, v66
	v_rcp_f32_e32 v78, v68
	v_div_fmas_f32 v64, v64, v69, v65
	v_div_fixup_f32 v23, v64, v23, v67
	v_fma_f32 v64, -v68, v78, 1.0
	v_fmac_f32_e32 v78, v64, v78
	v_div_scale_f32 v64, vcc, v66, v22, v66
	v_mul_f32_e32 v65, v64, v78
	v_fma_f32 v67, -v68, v65, v64
	v_fmac_f32_e32 v65, v67, v78
	v_fma_f32 v64, -v68, v65, v64
	v_div_fmas_f32 v64, v64, v78, v65
	v_div_fixup_f32 v22, v64, v22, v66
	v_pk_mul_f32 v[20:21], v[20:21], v[22:23]
	s_waitcnt vmcnt(6)
	v_lshlrev_b32_e32 v65, 16, v154
	v_cvt_pk_bf16_f32 v19, v20, v21
	v_and_b32_e32 v21, 0xffff0000, v18
	v_lshlrev_b32_e32 v20, 16, v18
	v_mul_f32_e32 v21, v21, v21
	v_lshlrev_b32_e32 v22, 16, v19
	v_fmac_f32_e32 v21, v20, v20
	v_and_b32_e32 v23, 0xffff0000, v19
	v_fmac_f32_e32 v21, v22, v22
	v_fmac_f32_e32 v21, v23, v23
	v_and_b32_e32 v66, 0xffff0000, v154
	v_add_f32_e32 v64, v80, v21
	v_mul_f32_e32 v20, 0xbfb8aa3b, v65
	v_mul_f32_e32 v21, 0xbfb8aa3b, v66
	v_exp_f32_e32 v20, v20
	v_exp_f32_e32 v21, v21
	global_store_dwordx2 v[16:17], v[18:19], off offset:16
	v_pk_fma_f32 v[18:19], v[130:131], v[70:71], v[24:25] op_sel_hi:[0,1,1]
	v_pk_fma_f32 v[18:19], v[132:133], v[86:87], v[18:19] op_sel_hi:[0,1,1]
	v_pk_add_f32 v[20:21], v[20:21], 1.0 op_sel_hi:[1,0]
	v_lshlrev_b32_e32 v22, 16, v152
	v_div_scale_f32 v24, s[0:1], v21, v21, v66
	v_rcp_f32_e32 v25, v24
	v_and_b32_e32 v23, 0xffff0000, v152
	v_pk_fma_f32 v[18:19], v[128:129], v[22:23], v[18:19] op_sel_hi:[0,1,1]
	v_fma_f32 v22, -v24, v25, 1.0
	v_fmac_f32_e32 v25, v22, v25
	v_div_scale_f32 v22, vcc, v66, v21, v66
	v_mul_f32_e32 v23, v22, v25
	v_fma_f32 v67, -v24, v23, v22
	v_fmac_f32_e32 v23, v67, v25
	v_fma_f32 v22, -v24, v23, v22
	v_div_scale_f32 v24, s[0:1], v20, v20, v65
	v_rcp_f32_e32 v67, v24
	v_div_fmas_f32 v22, v22, v25, v23
	v_div_fixup_f32 v21, v22, v21, v66
	v_and_b32_e32 v66, 0xffff0000, v155
	v_fma_f32 v22, -v24, v67, 1.0
	v_fmac_f32_e32 v67, v22, v67
	v_div_scale_f32 v22, vcc, v65, v20, v65
	v_mul_f32_e32 v23, v22, v67
	v_fma_f32 v25, -v24, v23, v22
	v_fmac_f32_e32 v23, v25, v67
	v_fma_f32 v22, -v24, v23, v22
	v_div_fmas_f32 v22, v22, v67, v23
	v_div_fixup_f32 v20, v22, v20, v65
	v_lshlrev_b32_e32 v65, 16, v155
	v_mul_f32_e32 v22, 0xbfb8aa3b, v65
	v_mul_f32_e32 v23, 0xbfb8aa3b, v66
	v_exp_f32_e32 v22, v22
	v_exp_f32_e32 v23, v23
	v_pk_mul_f32 v[18:19], v[18:19], v[20:21]
	v_pk_fma_f32 v[20:21], v[130:131], v[72:73], v[26:27] op_sel_hi:[0,1,1]
	v_pk_fma_f32 v[20:21], v[132:133], v[88:89], v[20:21] op_sel_hi:[0,1,1]
	v_pk_add_f32 v[22:23], v[22:23], 1.0 op_sel_hi:[1,0]
	v_lshlrev_b32_e32 v24, 16, v153
	v_div_scale_f32 v26, s[0:1], v23, v23, v66
	v_rcp_f32_e32 v27, v26
	v_and_b32_e32 v25, 0xffff0000, v153
	v_pk_fma_f32 v[20:21], v[128:129], v[24:25], v[20:21] op_sel_hi:[0,1,1]
	v_cvt_pk_bf16_f32 v18, v18, v19
	v_fma_f32 v24, -v26, v27, 1.0
	v_fmac_f32_e32 v27, v24, v27
	v_div_scale_f32 v24, vcc, v66, v23, v66
	v_mul_f32_e32 v25, v24, v27
	v_fma_f32 v67, -v26, v25, v24
	v_fmac_f32_e32 v25, v67, v27
	v_fma_f32 v24, -v26, v25, v24
	v_div_scale_f32 v26, s[0:1], v22, v22, v65
	v_rcp_f32_e32 v67, v26
	v_div_fmas_f32 v24, v24, v27, v25
	v_div_fixup_f32 v23, v24, v23, v66
	v_fma_f32 v24, -v26, v67, 1.0
	v_fmac_f32_e32 v67, v24, v67
	v_div_scale_f32 v24, vcc, v65, v22, v65
	v_mul_f32_e32 v25, v24, v67
	v_fma_f32 v27, -v26, v25, v24
	v_fmac_f32_e32 v25, v27, v67
	v_fma_f32 v24, -v26, v25, v24
	v_div_fmas_f32 v24, v24, v67, v25
	v_div_fixup_f32 v22, v24, v22, v65
	v_pk_mul_f32 v[20:21], v[20:21], v[22:23]
	s_waitcnt vmcnt(6)
	v_lshlrev_b32_e32 v24, 16, v150
	v_cvt_pk_bf16_f32 v19, v20, v21
	v_and_b32_e32 v21, 0xffff0000, v18
	v_lshlrev_b32_e32 v20, 16, v18
	v_mul_f32_e32 v21, v21, v21
	v_lshlrev_b32_e32 v22, 16, v19
	v_fmac_f32_e32 v21, v20, v20
	v_and_b32_e32 v23, 0xffff0000, v19
	v_fmac_f32_e32 v21, v22, v22
	v_fmac_f32_e32 v21, v23, v23
	v_and_b32_e32 v25, 0xffff0000, v150
	v_add_f32_e32 v26, v64, v21
	v_mul_f32_e32 v20, 0xbfb8aa3b, v24
	v_mul_f32_e32 v21, 0xbfb8aa3b, v25
	v_exp_f32_e32 v20, v20
	v_exp_f32_e32 v21, v21
	global_store_dwordx2 v[16:17], v[18:19], off offset:32
	v_pk_fma_f32 v[18:19], v[130:131], v[74:75], v[28:29] op_sel_hi:[0,1,1]
	v_pk_fma_f32 v[18:19], v[132:133], v[90:91], v[18:19] op_sel_hi:[0,1,1]
	v_pk_add_f32 v[20:21], v[20:21], 1.0 op_sel_hi:[1,0]
	v_lshlrev_b32_e32 v22, 16, v148
	v_div_scale_f32 v27, s[0:1], v21, v21, v25
	v_rcp_f32_e32 v28, v27
	v_and_b32_e32 v23, 0xffff0000, v148
	v_pk_fma_f32 v[18:19], v[128:129], v[22:23], v[18:19] op_sel_hi:[0,1,1]
	v_fma_f32 v22, -v27, v28, 1.0
	v_fmac_f32_e32 v28, v22, v28
	v_div_scale_f32 v22, vcc, v25, v21, v25
	v_mul_f32_e32 v23, v22, v28
	v_fma_f32 v29, -v27, v23, v22
	v_fmac_f32_e32 v23, v29, v28
	v_fma_f32 v22, -v27, v23, v22
	v_div_scale_f32 v27, s[0:1], v20, v20, v24
	v_rcp_f32_e32 v29, v27
	v_div_fmas_f32 v22, v22, v28, v23
	v_div_fixup_f32 v21, v22, v21, v25
	v_and_b32_e32 v28, 0xffff0000, v151
	v_fma_f32 v22, -v27, v29, 1.0
	v_fmac_f32_e32 v29, v22, v29
	v_div_scale_f32 v22, vcc, v24, v20, v24
	v_mul_f32_e32 v23, v22, v29
	v_fma_f32 v25, -v27, v23, v22
	v_fmac_f32_e32 v23, v25, v29
	v_fma_f32 v22, -v27, v23, v22
	v_div_fmas_f32 v22, v22, v29, v23
	v_lshlrev_b32_e32 v27, 16, v151
	v_div_fixup_f32 v20, v22, v20, v24
	v_mul_f32_e32 v22, 0xbfb8aa3b, v27
	v_mul_f32_e32 v23, 0xbfb8aa3b, v28
	v_exp_f32_e32 v22, v22
	v_exp_f32_e32 v23, v23
	v_pk_mul_f32 v[18:19], v[18:19], v[20:21]
	v_pk_fma_f32 v[20:21], v[130:131], v[76:77], v[30:31] op_sel_hi:[0,1,1]
	v_pk_fma_f32 v[20:21], v[132:133], v[92:93], v[20:21] op_sel_hi:[0,1,1]
	v_pk_add_f32 v[22:23], v[22:23], 1.0 op_sel_hi:[1,0]
	v_lshlrev_b32_e32 v24, 16, v149
	v_div_scale_f32 v29, s[0:1], v23, v23, v28
	v_rcp_f32_e32 v30, v29
	v_and_b32_e32 v25, 0xffff0000, v149
	v_pk_fma_f32 v[20:21], v[128:129], v[24:25], v[20:21] op_sel_hi:[0,1,1]
	v_cvt_pk_bf16_f32 v18, v18, v19
	v_fma_f32 v24, -v29, v30, 1.0
	v_fmac_f32_e32 v30, v24, v30
	v_div_scale_f32 v24, vcc, v28, v23, v28
	v_mul_f32_e32 v25, v24, v30
	v_fma_f32 v31, -v29, v25, v24
	v_fmac_f32_e32 v25, v31, v30
	v_fma_f32 v24, -v29, v25, v24
	v_div_scale_f32 v29, s[0:1], v22, v22, v27
	v_rcp_f32_e32 v31, v29
	v_div_fmas_f32 v24, v24, v30, v25
	v_div_fixup_f32 v23, v24, v23, v28
	v_fma_f32 v24, -v29, v31, 1.0
	v_fmac_f32_e32 v31, v24, v31
	v_div_scale_f32 v24, vcc, v27, v22, v27
	v_mul_f32_e32 v25, v24, v31
	v_fma_f32 v28, -v29, v25, v24
	v_fmac_f32_e32 v25, v28, v31
	v_fma_f32 v24, -v29, v25, v24
	v_div_fmas_f32 v24, v24, v31, v25
	v_div_fixup_f32 v22, v24, v22, v27
	v_pk_mul_f32 v[20:21], v[20:21], v[22:23]
	s_waitcnt vmcnt(6)
	v_and_b32_e32 v24, 0xffff0000, v146
	v_cvt_pk_bf16_f32 v19, v20, v21
	v_and_b32_e32 v21, 0xffff0000, v18
	v_lshlrev_b32_e32 v20, 16, v18
	v_mul_f32_e32 v21, v21, v21
	v_lshlrev_b32_e32 v22, 16, v19
	v_fmac_f32_e32 v21, v20, v20
	v_and_b32_e32 v23, 0xffff0000, v19
	v_fmac_f32_e32 v21, v22, v22
	v_fmac_f32_e32 v21, v23, v23
	v_lshlrev_b32_e32 v23, 16, v146
	v_add_f32_e32 v22, v26, v21
	v_mul_f32_e32 v20, 0xbfb8aa3b, v23
	v_mul_f32_e32 v21, 0xbfb8aa3b, v24
	v_exp_f32_e32 v20, v20
	v_exp_f32_e32 v21, v21
	global_store_dwordx2 v[16:17], v[18:19], off offset:48
	v_pk_add_f32 v[18:19], v[20:21], 1.0 op_sel_hi:[1,0]
	s_nop 0
	v_div_scale_f32 v25, s[0:1], v19, v19, v24
	v_rcp_f32_e32 v26, v25
	v_lshlrev_b32_e32 v20, 16, v144
	v_and_b32_e32 v21, 0xffff0000, v144
	v_pk_fma_f32 v[0:1], v[128:129], v[20:21], v[0:1] op_sel_hi:[0,1,1]
	v_fma_f32 v20, -v25, v26, 1.0
	v_fmac_f32_e32 v26, v20, v26
	v_div_scale_f32 v20, vcc, v24, v19, v24
	v_mul_f32_e32 v21, v20, v26
	v_fma_f32 v27, -v25, v21, v20
	v_fmac_f32_e32 v21, v27, v26
	v_fma_f32 v20, -v25, v21, v20
	v_div_scale_f32 v25, s[0:1], v18, v18, v23
	v_rcp_f32_e32 v27, v25
	v_div_fmas_f32 v20, v20, v26, v21
	v_div_fixup_f32 v19, v20, v19, v24
	v_fma_f32 v20, -v25, v27, 1.0
	v_fmac_f32_e32 v27, v20, v27
	v_div_scale_f32 v20, vcc, v23, v18, v23
	v_mul_f32_e32 v21, v20, v27
	v_fma_f32 v24, -v25, v21, v20
	v_fmac_f32_e32 v21, v24, v27
	v_fma_f32 v20, -v25, v21, v20
	v_div_fmas_f32 v20, v20, v27, v21
	v_div_fixup_f32 v18, v20, v18, v23
	v_lshlrev_b32_e32 v23, 16, v147
	v_and_b32_e32 v24, 0xffff0000, v147
	v_mul_f32_e32 v20, 0xbfb8aa3b, v23
	v_mul_f32_e32 v21, 0xbfb8aa3b, v24
	v_exp_f32_e32 v20, v20
	v_exp_f32_e32 v21, v21
	v_pk_mul_f32 v[0:1], v[0:1], v[18:19]
	v_pk_add_f32 v[18:19], v[20:21], 1.0 op_sel_hi:[1,0]
	s_nop 0
	v_div_scale_f32 v25, s[0:1], v19, v19, v24
	v_rcp_f32_e32 v26, v25
	v_lshlrev_b32_e32 v20, 16, v145
	v_and_b32_e32 v21, 0xffff0000, v145
	v_pk_fma_f32 v[2:3], v[128:129], v[20:21], v[2:3] op_sel_hi:[0,1,1]
	v_fma_f32 v20, -v25, v26, 1.0
	v_fmac_f32_e32 v26, v20, v26
	v_div_scale_f32 v20, vcc, v24, v19, v24
	v_mul_f32_e32 v21, v20, v26
	v_fma_f32 v27, -v25, v21, v20
	v_fmac_f32_e32 v21, v27, v26
	v_fma_f32 v20, -v25, v21, v20
	v_div_scale_f32 v25, s[0:1], v18, v18, v23
	v_rcp_f32_e32 v27, v25
	v_div_fmas_f32 v20, v20, v26, v21
	v_div_fixup_f32 v19, v20, v19, v24
	v_cvt_pk_bf16_f32 v0, v0, v1
	v_fma_f32 v20, -v25, v27, 1.0
	v_fmac_f32_e32 v27, v20, v27
	v_div_scale_f32 v20, vcc, v23, v18, v23
	v_mul_f32_e32 v21, v20, v27
	v_fma_f32 v24, -v25, v21, v20
	v_fmac_f32_e32 v21, v24, v27
	v_fma_f32 v20, -v25, v21, v20
	v_div_fmas_f32 v20, v20, v27, v21
	v_div_fixup_f32 v18, v20, v18, v23
	v_pk_mul_f32 v[2:3], v[2:3], v[18:19]
	s_waitcnt vmcnt(6)
	v_and_b32_e32 v20, 0xffff0000, v142
	v_cvt_pk_bf16_f32 v1, v2, v3
	v_and_b32_e32 v3, 0xffff0000, v0
	v_lshlrev_b32_e32 v2, 16, v0
	v_mul_f32_e32 v3, v3, v3
	v_lshlrev_b32_e32 v18, 16, v1
	v_fmac_f32_e32 v3, v2, v2
	v_and_b32_e32 v19, 0xffff0000, v1
	v_fmac_f32_e32 v3, v18, v18
	v_fmac_f32_e32 v3, v19, v19
	v_lshlrev_b32_e32 v19, 16, v142
	v_add_f32_e32 v18, v22, v3
	v_mul_f32_e32 v2, 0xbfb8aa3b, v19
	v_mul_f32_e32 v3, 0xbfb8aa3b, v20
	v_exp_f32_e32 v2, v2
	v_exp_f32_e32 v3, v3
	global_store_dwordx2 v[16:17], v[0:1], off offset:64
	v_pk_fma_f32 v[0:1], v[130:131], v[36:37], v[4:5] op_sel_hi:[0,1,1]
	v_pk_fma_f32 v[0:1], v[132:133], v[52:53], v[0:1] op_sel_hi:[0,1,1]
	v_pk_add_f32 v[2:3], v[2:3], 1.0 op_sel_hi:[1,0]
	v_lshlrev_b32_e32 v4, 16, v140
	v_div_scale_f32 v21, s[0:1], v3, v3, v20
	v_rcp_f32_e32 v22, v21
	v_and_b32_e32 v5, 0xffff0000, v140
	v_pk_fma_f32 v[0:1], v[128:129], v[4:5], v[0:1] op_sel_hi:[0,1,1]
	v_fma_f32 v4, -v21, v22, 1.0
	v_fmac_f32_e32 v22, v4, v22
	v_div_scale_f32 v4, vcc, v20, v3, v20
	v_mul_f32_e32 v5, v4, v22
	v_fma_f32 v23, -v21, v5, v4
	v_fmac_f32_e32 v5, v23, v22
	v_fma_f32 v4, -v21, v5, v4
	v_div_scale_f32 v21, s[0:1], v2, v2, v19
	v_rcp_f32_e32 v23, v21
	v_div_fmas_f32 v4, v4, v22, v5
	v_div_fixup_f32 v3, v4, v3, v20
	v_fma_f32 v4, -v21, v23, 1.0
	v_fmac_f32_e32 v23, v4, v23
	v_div_scale_f32 v4, vcc, v19, v2, v19
	v_mul_f32_e32 v5, v4, v23
	v_fma_f32 v20, -v21, v5, v4
	v_fmac_f32_e32 v5, v20, v23
	v_fma_f32 v4, -v21, v5, v4
	v_div_fmas_f32 v4, v4, v23, v5
	v_div_fixup_f32 v2, v4, v2, v19
	v_lshlrev_b32_e32 v19, 16, v143
	v_and_b32_e32 v20, 0xffff0000, v143
	v_mul_f32_e32 v4, 0xbfb8aa3b, v19
	v_mul_f32_e32 v5, 0xbfb8aa3b, v20
	v_exp_f32_e32 v4, v4
	v_exp_f32_e32 v5, v5
	v_pk_mul_f32 v[0:1], v[0:1], v[2:3]
	v_pk_fma_f32 v[2:3], v[130:131], v[38:39], v[6:7] op_sel_hi:[0,1,1]
	v_pk_fma_f32 v[2:3], v[132:133], v[54:55], v[2:3] op_sel_hi:[0,1,1]
	v_pk_add_f32 v[4:5], v[4:5], 1.0 op_sel_hi:[1,0]
	v_lshlrev_b32_e32 v6, 16, v141
	v_div_scale_f32 v21, s[0:1], v5, v5, v20
	v_rcp_f32_e32 v22, v21
	v_and_b32_e32 v7, 0xffff0000, v141
	v_pk_fma_f32 v[2:3], v[128:129], v[6:7], v[2:3] op_sel_hi:[0,1,1]
	v_cvt_pk_bf16_f32 v0, v0, v1
	v_fma_f32 v6, -v21, v22, 1.0
	v_fmac_f32_e32 v22, v6, v22
	v_div_scale_f32 v6, vcc, v20, v5, v20
	v_mul_f32_e32 v7, v6, v22
	v_fma_f32 v23, -v21, v7, v6
	v_fmac_f32_e32 v7, v23, v22
	v_fma_f32 v6, -v21, v7, v6
	v_div_scale_f32 v21, s[0:1], v4, v4, v19
	v_rcp_f32_e32 v23, v21
	v_div_fmas_f32 v6, v6, v22, v7
	v_div_fixup_f32 v5, v6, v5, v20
	v_fma_f32 v6, -v21, v23, 1.0
	v_fmac_f32_e32 v23, v6, v23
	v_div_scale_f32 v6, vcc, v19, v4, v19
	v_mul_f32_e32 v7, v6, v23
	v_fma_f32 v20, -v21, v7, v6
	v_fmac_f32_e32 v7, v20, v23
	v_fma_f32 v6, -v21, v7, v6
	v_div_fmas_f32 v6, v6, v23, v7
	v_div_fixup_f32 v4, v6, v4, v19
	v_pk_mul_f32 v[2:3], v[2:3], v[4:5]
	s_waitcnt vmcnt(6)
	v_lshlrev_b32_e32 v19, 16, v138
	v_cvt_pk_bf16_f32 v1, v2, v3
	v_and_b32_e32 v3, 0xffff0000, v0
	v_lshlrev_b32_e32 v2, 16, v0
	v_mul_f32_e32 v6, v3, v3
	v_and_b32_e32 v20, 0xffff0000, v138
	v_fmac_f32_e32 v6, v2, v2
	v_mul_f32_e32 v2, 0xbfb8aa3b, v19
	v_mul_f32_e32 v3, 0xbfb8aa3b, v20
	v_exp_f32_e32 v2, v2
	v_exp_f32_e32 v3, v3
	v_lshlrev_b32_e32 v4, 16, v1
	v_and_b32_e32 v5, 0xffff0000, v1
	v_fmac_f32_e32 v6, v4, v4
	v_pk_add_f32 v[2:3], v[2:3], 1.0 op_sel_hi:[1,0]
	v_fmac_f32_e32 v6, v5, v5
	v_pk_fma_f32 v[4:5], v[130:131], v[40:41], v[8:9] op_sel_hi:[0,1,1]
	v_div_scale_f32 v8, s[0:1], v3, v3, v20
	v_rcp_f32_e32 v9, v8
	v_add_f32_e32 v18, v18, v6
	v_pk_fma_f32 v[4:5], v[132:133], v[56:57], v[4:5] op_sel_hi:[0,1,1]
	v_lshlrev_b32_e32 v6, 16, v136
	v_and_b32_e32 v7, 0xffff0000, v136
	v_pk_fma_f32 v[4:5], v[128:129], v[6:7], v[4:5] op_sel_hi:[0,1,1]
	v_fma_f32 v6, -v8, v9, 1.0
	v_fmac_f32_e32 v9, v6, v9
	v_div_scale_f32 v6, vcc, v20, v3, v20
	v_mul_f32_e32 v7, v6, v9
	v_fma_f32 v21, -v8, v7, v6
	v_fmac_f32_e32 v7, v21, v9
	v_fma_f32 v6, -v8, v7, v6
	v_div_scale_f32 v8, s[0:1], v2, v2, v19
	v_rcp_f32_e32 v21, v8
	v_div_fmas_f32 v6, v6, v9, v7
	v_div_fixup_f32 v3, v6, v3, v20
	v_and_b32_e32 v20, 0xffff0000, v139
	v_fma_f32 v6, -v8, v21, 1.0
	v_fmac_f32_e32 v21, v6, v21
	v_div_scale_f32 v6, vcc, v19, v2, v19
	v_mul_f32_e32 v7, v6, v21
	v_fma_f32 v9, -v8, v7, v6
	v_fmac_f32_e32 v7, v9, v21
	v_fma_f32 v6, -v8, v7, v6
	v_div_fmas_f32 v6, v6, v21, v7
	v_div_fixup_f32 v2, v6, v2, v19
	v_lshlrev_b32_e32 v19, 16, v139
	v_mul_f32_e32 v6, 0xbfb8aa3b, v19
	v_mul_f32_e32 v7, 0xbfb8aa3b, v20
	v_exp_f32_e32 v6, v6
	v_exp_f32_e32 v7, v7
	v_pk_mul_f32 v[2:3], v[4:5], v[2:3]
	v_pk_fma_f32 v[4:5], v[130:131], v[42:43], v[10:11] op_sel_hi:[0,1,1]
	v_pk_fma_f32 v[4:5], v[132:133], v[58:59], v[4:5] op_sel_hi:[0,1,1]
	v_pk_add_f32 v[6:7], v[6:7], 1.0 op_sel_hi:[1,0]
	v_lshlrev_b32_e32 v8, 16, v137
	v_div_scale_f32 v10, s[0:1], v7, v7, v20
	v_rcp_f32_e32 v11, v10
	v_and_b32_e32 v9, 0xffff0000, v137
	v_pk_fma_f32 v[4:5], v[128:129], v[8:9], v[4:5] op_sel_hi:[0,1,1]
	v_cvt_pk_bf16_f32 v2, v2, v3
	v_fma_f32 v8, -v10, v11, 1.0
	v_fmac_f32_e32 v11, v8, v11
	v_div_scale_f32 v8, vcc, v20, v7, v20
	v_mul_f32_e32 v9, v8, v11
	v_fma_f32 v21, -v10, v9, v8
	v_fmac_f32_e32 v9, v21, v11
	v_fma_f32 v8, -v10, v9, v8
	v_div_scale_f32 v10, s[0:1], v6, v6, v19
	v_rcp_f32_e32 v21, v10
	v_div_fmas_f32 v8, v8, v11, v9
	v_div_fixup_f32 v7, v8, v7, v20
	v_fma_f32 v8, -v10, v21, 1.0
	v_fmac_f32_e32 v21, v8, v21
	v_div_scale_f32 v8, vcc, v19, v6, v19
	v_mul_f32_e32 v9, v8, v21
	v_fma_f32 v11, -v10, v9, v8
	v_fmac_f32_e32 v9, v11, v21
	v_fma_f32 v8, -v10, v9, v8
	v_div_fmas_f32 v8, v8, v21, v9
	v_div_fixup_f32 v6, v8, v6, v19
	v_pk_mul_f32 v[4:5], v[4:5], v[6:7]
	s_waitcnt vmcnt(5)
	v_lshlrev_b32_e32 v10, 16, v134
	v_cvt_pk_bf16_f32 v3, v4, v5
	v_and_b32_e32 v5, 0xffff0000, v2
	v_lshlrev_b32_e32 v4, 16, v2
	v_mul_f32_e32 v8, v5, v5
	v_and_b32_e32 v11, 0xffff0000, v134
	v_fmac_f32_e32 v8, v4, v4
	v_mul_f32_e32 v4, 0xbfb8aa3b, v10
	v_mul_f32_e32 v5, 0xbfb8aa3b, v11
	v_exp_f32_e32 v4, v4
	v_exp_f32_e32 v5, v5
	v_lshlrev_b32_e32 v6, 16, v3
	v_and_b32_e32 v7, 0xffff0000, v3
	v_fmac_f32_e32 v8, v6, v6
	v_pk_add_f32 v[4:5], v[4:5], 1.0 op_sel_hi:[1,0]
	v_fmac_f32_e32 v8, v7, v7
	v_pk_fma_f32 v[6:7], v[130:131], v[44:45], v[12:13] op_sel_hi:[0,1,1]
	v_div_scale_f32 v12, s[0:1], v5, v5, v11
	v_rcp_f32_e32 v13, v12
	v_add_f32_e32 v18, v18, v8
	v_pk_fma_f32 v[6:7], v[132:133], v[60:61], v[6:7] op_sel_hi:[0,1,1]
	v_lshlrev_b32_e32 v8, 16, v126
	v_and_b32_e32 v9, 0xffff0000, v126
	v_pk_fma_f32 v[6:7], v[128:129], v[8:9], v[6:7] op_sel_hi:[0,1,1]
	v_fma_f32 v8, -v12, v13, 1.0
	v_fmac_f32_e32 v13, v8, v13
	v_div_scale_f32 v8, vcc, v11, v5, v11
	v_mul_f32_e32 v9, v8, v13
	v_fma_f32 v19, -v12, v9, v8
	v_fmac_f32_e32 v9, v19, v13
	v_fma_f32 v8, -v12, v9, v8
	v_div_scale_f32 v12, s[0:1], v4, v4, v10
	v_rcp_f32_e32 v19, v12
	v_div_fmas_f32 v8, v8, v13, v9
	v_div_fixup_f32 v5, v8, v5, v11
	v_and_b32_e32 v13, 0xffff0000, v135
	v_fma_f32 v8, -v12, v19, 1.0
	v_fmac_f32_e32 v19, v8, v19
	v_div_scale_f32 v8, vcc, v10, v4, v10
	v_mul_f32_e32 v9, v8, v19
	v_fma_f32 v11, -v12, v9, v8
	v_fmac_f32_e32 v9, v11, v19
	v_fma_f32 v8, -v12, v9, v8
	v_div_fmas_f32 v8, v8, v19, v9
	v_lshlrev_b32_e32 v12, 16, v135
	v_div_fixup_f32 v4, v8, v4, v10
	v_mul_f32_e32 v8, 0xbfb8aa3b, v12
	v_mul_f32_e32 v9, 0xbfb8aa3b, v13
	v_exp_f32_e32 v8, v8
	v_exp_f32_e32 v9, v9
	v_pk_mul_f32 v[4:5], v[6:7], v[4:5]
	v_pk_fma_f32 v[6:7], v[130:131], v[46:47], v[14:15] op_sel_hi:[0,1,1]
	v_pk_fma_f32 v[6:7], v[132:133], v[62:63], v[6:7] op_sel_hi:[0,1,1]
	v_pk_add_f32 v[8:9], v[8:9], 1.0 op_sel_hi:[1,0]
	v_lshlrev_b32_e32 v10, 16, v127
	v_div_scale_f32 v14, s[0:1], v9, v9, v13
	v_rcp_f32_e32 v15, v14
	v_and_b32_e32 v11, 0xffff0000, v127
	v_pk_fma_f32 v[6:7], v[128:129], v[10:11], v[6:7] op_sel_hi:[0,1,1]
	v_fma_f32 v10, -v14, v15, 1.0
	v_fmac_f32_e32 v15, v10, v15
	v_div_scale_f32 v10, vcc, v13, v9, v13
	v_mul_f32_e32 v11, v10, v15
	v_fma_f32 v19, -v14, v11, v10
	v_fmac_f32_e32 v11, v19, v15
	v_fma_f32 v10, -v14, v11, v10
	v_div_scale_f32 v14, s[0:1], v8, v8, v12
	v_rcp_f32_e32 v19, v14
	v_div_fmas_f32 v10, v10, v15, v11
	v_div_fixup_f32 v9, v10, v9, v13
	v_fma_f32 v10, -v14, v19, 1.0
	v_fmac_f32_e32 v19, v10, v19
	v_div_scale_f32 v10, vcc, v12, v8, v12
	v_mul_f32_e32 v11, v10, v19
	v_fma_f32 v13, -v14, v11, v10
	v_fmac_f32_e32 v11, v13, v19
	v_fma_f32 v10, -v14, v11, v10
	v_div_fmas_f32 v10, v10, v19, v11
	v_div_fixup_f32 v8, v10, v8, v12
	v_pk_mul_f32 v[6:7], v[6:7], v[8:9]
	v_cvt_pk_bf16_f32 v8, v4, v5
	v_and_b32_e32 v5, 0xffff0000, v8
	v_cvt_pk_bf16_f32 v9, v6, v7
	v_lshlrev_b32_e32 v4, 16, v8
	v_mul_f32_e32 v5, v5, v5
	v_lshlrev_b32_e32 v6, 16, v9
	v_fmac_f32_e32 v5, v4, v4
	v_and_b32_e32 v7, 0xffff0000, v9
	v_fmac_f32_e32 v5, v6, v6
	v_fmac_f32_e32 v5, v7, v7
	v_cmp_lt_i32_e32 vcc, v131, v167
	v_add_f32_e32 v4, v18, v5
	global_store_dwordx2 v[16:17], v[0:1], off offset:80
	global_store_dwordx2 v[16:17], v[2:3], off offset:96
	global_store_dwordx2 v[16:17], v[8:9], off offset:112
	v_cndmask_b32_e32 v5, v165, v131, vcc
	v_lshlrev_b32_e32 v5, 2, v5
	ds_bpermute_b32 v5, v5, v4
	v_cmp_eq_u32_e32 vcc, 0, v168
	s_and_saveexec_b64 s[66:67], vcc
	s_cbranch_execz .LBB0_720
	v_lshlrev_b64 v[0:1], 5, v[124:125]
	v_lshl_add_u64 v[0:1], s[58:59], 0, v[0:1]
	s_mov_b32 s5, s61
	v_lshl_add_u64 v[0:1], v[0:1], 0, s[4:5]
	s_waitcnt lgkmcnt(0)
	v_add_f32_e32 v2, v4, v5
	global_store_dword v[0:1], v2, off
	s_branch .LBB0_720

.LBB0_2197:
	s_or_b64 exec, exec, s[30:31]
	v_lshlrev_b32_e32 v59, 3, v111
	v_mov_b32_e32 v2, s1
	v_mov_b32_e32 v3, s0
	v_cndmask_b32_e32 v1, v5, v4, vcc
	v_cndmask_b32_e32 v2, v2, v3, vcc
	v_lshl_add_u32 v64, v59, 1, s23
	v_lshl_add_u32 v1, v1, 2, v2
	v_mad_u32_u24 v8, v56, s39, v64
	ds_write_b32 v1, v0
	s_waitcnt lgkmcnt(0)
	s_barrier
	ds_read_b128 v[0:3], v8 offset:17408
	ds_read_b128 v[4:7], v8 offset:17440
	s_waitcnt lgkmcnt(1)
	v_mfma_f32_32x32x16_bf16 v[24:39], v[0:3], v[48:51], 0
	v_lshlrev_b32_e32 v58, 2, v111
	v_cmp_ge_u32_e32 vcc, v58, v57
	s_waitcnt lgkmcnt(0)
	v_mfma_f32_32x32x16_bf16 v[24:39], v[4:7], v[102:105], v[24:39]
	ds_read_b128 v[0:3], v8 offset:17472
	ds_read_b128 v[4:7], v8 offset:17504
	s_waitcnt lgkmcnt(1)
	v_mfma_f32_32x32x16_bf16 v[24:39], v[0:3], v[98:101], v[24:39]
	v_lshl_add_u32 v0, v57, 2, s23
	ds_read2st64_b32 v[54:55], v0 offset0:140 offset1:142
	s_waitcnt lgkmcnt(1)
	v_mfma_f32_32x32x16_bf16 v[24:39], v[4:7], v[94:97], v[24:39]
	v_lshl_add_u32 v236, v58, 2, s23
	v_lshrrev_b32_e32 v239, 5, v57
	s_nop 0
	v_readfirstlane_b32 s4, v239
	s_cmp_gt_u32 s4, 0
	s_cbranch_scc1 .Lssdb4_lt
	s_cmp_lt_u32 s4, 0
	s_cbranch_scc1 .Lssdb4_gt
	v_sub_u32_e32 v237, v57, v58
	ds_read_b128 v[170:173], v236 offset:35840
	ds_read_b128 v[174:177], v236 offset:36352
	ds_read_b128 v[178:181], v236 offset:36864
	ds_read_b128 v[182:185], v236 offset:37376
	ds_read_b128 v[186:189], v236 offset:35872
	ds_read_b128 v[190:193], v236 offset:36384
	ds_read_b128 v[194:197], v236 offset:36896
	ds_read_b128 v[198:201], v236 offset:37408
	ds_read_b128 v[202:205], v236 offset:35904
	ds_read_b128 v[206:209], v236 offset:36416
	ds_read_b128 v[210:213], v236 offset:36928
	ds_read_b128 v[214:217], v236 offset:37440
	s_waitcnt lgkmcnt(8)
	ds_read_b128 v[218:221], v236 offset:35936
	ds_read_b128 v[222:225], v236 offset:36448
	ds_read_b128 v[226:229], v236 offset:36960
	ds_read_b128 v[230:233], v236 offset:37472
	v_mov_b32_e32 v238, v237
	v_cmp_lt_i32_e32 vcc, 0, v238
	v_cmp_lt_i32_e64 s[4:5], 1, v238
	v_cmp_lt_i32_e64 s[6:7], 2, v238
	v_cmp_lt_i32_e64 s[30:31], 3, v238
	v_sub_f32_e32 v170, v54, v170
	v_sub_f32_e32 v171, v54, v171
	v_sub_f32_e32 v172, v54, v172
	v_sub_f32_e32 v173, v54, v173
	v_sub_f32_e32 v174, v55, v174
	v_sub_f32_e32 v175, v55, v175
	v_sub_f32_e32 v176, v55, v176
	v_sub_f32_e32 v177, v55, v177
	v_cndmask_b32_e64 v170, v174, v170, vcc
	v_cndmask_b32_e64 v171, v175, v171, s[4:5]
	v_cndmask_b32_e64 v172, v176, v172, s[6:7]
	v_cndmask_b32_e64 v173, v177, v173, s[30:31]
	v_add_f32_e32 v174, v178, v182
	v_add_f32_e32 v175, v179, v183
	v_add_f32_e32 v176, v180, v184
	v_add_f32_e32 v177, v181, v185
	v_cndmask_b32_e64 v178, v182, v178, vcc
	v_cndmask_b32_e64 v179, v183, v179, s[4:5]
	v_cndmask_b32_e64 v180, v184, v180, s[6:7]
	v_cndmask_b32_e64 v181, v185, v181, s[30:31]
	v_cmp_eq_u32_e32 vcc, 0, v238
	v_cmp_eq_u32_e64 s[4:5], 1, v238
	v_cmp_eq_u32_e64 s[6:7], 2, v238
	v_cmp_eq_u32_e64 s[30:31], 3, v238
	v_mul_f32_e32 v170, 0x3fb8aa3b, v170
	v_mul_f32_e32 v171, 0x3fb8aa3b, v171
	v_mul_f32_e32 v172, 0x3fb8aa3b, v172
	v_mul_f32_e32 v173, 0x3fb8aa3b, v173
	v_exp_f32_e32 v170, v170
	v_exp_f32_e32 v171, v171
	v_exp_f32_e32 v172, v172
	v_exp_f32_e32 v173, v173
	v_mul_f32_e32 v178, v178, v170
	v_mul_f32_e32 v179, v179, v171
	v_mul_f32_e32 v180, v180, v172
	v_mul_f32_e32 v181, v181, v173
	v_cndmask_b32_e64 v0, v178, v174, vcc
	v_cndmask_b32_e64 v1, v179, v175, s[4:5]
	v_cndmask_b32_e64 v2, v180, v176, s[6:7]
	v_cndmask_b32_e64 v3, v181, v177, s[30:31]
	s_waitcnt lgkmcnt(8)
	v_add_u32_e32 v238, -8, v237
	v_cmp_lt_i32_e32 vcc, 0, v238
	v_cmp_lt_i32_e64 s[4:5], 1, v238
	v_cmp_lt_i32_e64 s[6:7], 2, v238
	v_cmp_lt_i32_e64 s[30:31], 3, v238
	v_sub_f32_e32 v186, v54, v186
	v_sub_f32_e32 v187, v54, v187
	v_sub_f32_e32 v188, v54, v188
	v_sub_f32_e32 v189, v54, v189
	v_sub_f32_e32 v190, v55, v190
	v_sub_f32_e32 v191, v55, v191
	v_sub_f32_e32 v192, v55, v192
	v_sub_f32_e32 v193, v55, v193
	v_cndmask_b32_e64 v186, v190, v186, vcc
	v_cndmask_b32_e64 v187, v191, v187, s[4:5]
	v_cndmask_b32_e64 v188, v192, v188, s[6:7]
	v_cndmask_b32_e64 v189, v193, v189, s[30:31]
	v_add_f32_e32 v190, v194, v198
	v_add_f32_e32 v191, v195, v199
	v_add_f32_e32 v192, v196, v200
	v_add_f32_e32 v193, v197, v201
	v_cndmask_b32_e64 v194, v198, v194, vcc
	v_cndmask_b32_e64 v195, v199, v195, s[4:5]
	v_cndmask_b32_e64 v196, v200, v196, s[6:7]
	v_cndmask_b32_e64 v197, v201, v197, s[30:31]
	v_cmp_eq_u32_e32 vcc, 0, v238
	v_cmp_eq_u32_e64 s[4:5], 1, v238
	v_cmp_eq_u32_e64 s[6:7], 2, v238
	v_cmp_eq_u32_e64 s[30:31], 3, v238
	v_mul_f32_e32 v186, 0x3fb8aa3b, v186
	v_mul_f32_e32 v187, 0x3fb8aa3b, v187
	v_mul_f32_e32 v188, 0x3fb8aa3b, v188
	v_mul_f32_e32 v189, 0x3fb8aa3b, v189
	v_exp_f32_e32 v186, v186
	v_exp_f32_e32 v187, v187
	v_exp_f32_e32 v188, v188
	v_exp_f32_e32 v189, v189
	v_mul_f32_e32 v194, v194, v186
	v_mul_f32_e32 v195, v195, v187
	v_mul_f32_e32 v196, v196, v188
	v_mul_f32_e32 v197, v197, v189
	v_cndmask_b32_e64 v4, v194, v190, vcc
	v_cndmask_b32_e64 v5, v195, v191, s[4:5]
	v_cndmask_b32_e64 v6, v196, v192, s[6:7]
	v_cndmask_b32_e64 v7, v197, v193, s[30:31]
	s_waitcnt lgkmcnt(4)
	v_add_u32_e32 v238, -16, v237
	v_cmp_lt_i32_e32 vcc, 0, v238
	v_cmp_lt_i32_e64 s[4:5], 1, v238
	v_cmp_lt_i32_e64 s[6:7], 2, v238
	v_cmp_lt_i32_e64 s[30:31], 3, v238
	v_sub_f32_e32 v202, v54, v202
	v_sub_f32_e32 v203, v54, v203
	v_sub_f32_e32 v204, v54, v204
	v_sub_f32_e32 v205, v54, v205
	v_sub_f32_e32 v206, v55, v206
	v_sub_f32_e32 v207, v55, v207
	v_sub_f32_e32 v208, v55, v208
	v_sub_f32_e32 v209, v55, v209
	v_cndmask_b32_e64 v202, v206, v202, vcc
	v_cndmask_b32_e64 v203, v207, v203, s[4:5]
	v_cndmask_b32_e64 v204, v208, v204, s[6:7]
	v_cndmask_b32_e64 v205, v209, v205, s[30:31]
	v_add_f32_e32 v206, v210, v214
	v_add_f32_e32 v207, v211, v215
	v_add_f32_e32 v208, v212, v216
	v_add_f32_e32 v209, v213, v217
	v_cndmask_b32_e64 v210, v214, v210, vcc
	v_cndmask_b32_e64 v211, v215, v211, s[4:5]
	v_cndmask_b32_e64 v212, v216, v212, s[6:7]
	v_cndmask_b32_e64 v213, v217, v213, s[30:31]
	v_cmp_eq_u32_e32 vcc, 0, v238
	v_cmp_eq_u32_e64 s[4:5], 1, v238
	v_cmp_eq_u32_e64 s[6:7], 2, v238
	v_cmp_eq_u32_e64 s[30:31], 3, v238
	v_mul_f32_e32 v202, 0x3fb8aa3b, v202
	v_mul_f32_e32 v203, 0x3fb8aa3b, v203
	v_mul_f32_e32 v204, 0x3fb8aa3b, v204
	v_mul_f32_e32 v205, 0x3fb8aa3b, v205
	v_exp_f32_e32 v202, v202
	v_exp_f32_e32 v203, v203
	v_exp_f32_e32 v204, v204
	v_exp_f32_e32 v205, v205
	v_mul_f32_e32 v210, v210, v202
	v_mul_f32_e32 v211, v211, v203
	v_mul_f32_e32 v212, v212, v204
	v_mul_f32_e32 v213, v213, v205
	v_cndmask_b32_e64 v40, v210, v206, vcc
	v_cndmask_b32_e64 v41, v211, v207, s[4:5]
	v_cndmask_b32_e64 v8, v212, v208, s[6:7]
	v_cndmask_b32_e64 v9, v213, v209, s[30:31]
	s_waitcnt lgkmcnt(0)
	v_add_u32_e32 v238, 0xffffffe8, v237
	v_cmp_lt_i32_e32 vcc, 0, v238
	v_cmp_lt_i32_e64 s[4:5], 1, v238
	v_cmp_lt_i32_e64 s[6:7], 2, v238
	v_cmp_lt_i32_e64 s[30:31], 3, v238
	v_sub_f32_e32 v218, v54, v218
	v_sub_f32_e32 v219, v54, v219
	v_sub_f32_e32 v220, v54, v220
	v_sub_f32_e32 v221, v54, v221
	v_sub_f32_e32 v222, v55, v222
	v_sub_f32_e32 v223, v55, v223
	v_sub_f32_e32 v224, v55, v224
	v_sub_f32_e32 v225, v55, v225
	v_cndmask_b32_e64 v218, v222, v218, vcc
	v_cndmask_b32_e64 v219, v223, v219, s[4:5]
	v_cndmask_b32_e64 v220, v224, v220, s[6:7]
	v_cndmask_b32_e64 v221, v225, v221, s[30:31]
	v_add_f32_e32 v222, v226, v230
	v_add_f32_e32 v223, v227, v231
	v_add_f32_e32 v224, v228, v232
	v_add_f32_e32 v225, v229, v233
	v_cndmask_b32_e64 v226, v230, v226, vcc
	v_cndmask_b32_e64 v227, v231, v227, s[4:5]
	v_cndmask_b32_e64 v228, v232, v228, s[6:7]
	v_cndmask_b32_e64 v229, v233, v229, s[30:31]
	v_cmp_eq_u32_e32 vcc, 0, v238
	v_cmp_eq_u32_e64 s[4:5], 1, v238
	v_cmp_eq_u32_e64 s[6:7], 2, v238
	v_cmp_eq_u32_e64 s[30:31], 3, v238
	v_mul_f32_e32 v218, 0x3fb8aa3b, v218
	v_mul_f32_e32 v219, 0x3fb8aa3b, v219
	v_mul_f32_e32 v220, 0x3fb8aa3b, v220
	v_mul_f32_e32 v221, 0x3fb8aa3b, v221
	v_exp_f32_e32 v218, v218
	v_exp_f32_e32 v219, v219
	v_exp_f32_e32 v220, v220
	v_exp_f32_e32 v221, v221
	v_mul_f32_e32 v226, v226, v218
	v_mul_f32_e32 v227, v227, v219
	v_mul_f32_e32 v228, v228, v220
	v_mul_f32_e32 v229, v229, v221
	v_cndmask_b32_e64 v10, v226, v222, vcc
	v_cndmask_b32_e64 v11, v227, v223, s[4:5]
	v_cndmask_b32_e64 v12, v228, v224, s[6:7]
	v_cndmask_b32_e64 v42, v229, v225, s[30:31]
	s_branch .Lssdb4_done
.Lssdb4_lt:
	ds_read_b128 v[170:173], v236 offset:35840
	ds_read_b128 v[178:181], v236 offset:36864
	ds_read_b128 v[186:189], v236 offset:35872
	ds_read_b128 v[194:197], v236 offset:36896
	ds_read_b128 v[202:205], v236 offset:35904
	ds_read_b128 v[210:213], v236 offset:36928
	ds_read_b128 v[218:221], v236 offset:35936
	ds_read_b128 v[226:229], v236 offset:36960
	s_waitcnt lgkmcnt(6)
	v_sub_f32_e32 v170, v54, v170
	v_sub_f32_e32 v171, v54, v171
	v_sub_f32_e32 v172, v54, v172
	v_sub_f32_e32 v173, v54, v173
	v_mul_f32_e32 v170, 0x3fb8aa3b, v170
	v_mul_f32_e32 v171, 0x3fb8aa3b, v171
	v_mul_f32_e32 v172, 0x3fb8aa3b, v172
	v_mul_f32_e32 v173, 0x3fb8aa3b, v173
	v_exp_f32_e32 v170, v170
	v_exp_f32_e32 v171, v171
	v_exp_f32_e32 v172, v172
	v_exp_f32_e32 v173, v173
	v_mul_f32_e32 v0, v178, v170
	v_mul_f32_e32 v1, v179, v171
	v_mul_f32_e32 v2, v180, v172
	v_mul_f32_e32 v3, v181, v173
	s_waitcnt lgkmcnt(4)
	v_sub_f32_e32 v186, v54, v186
	v_sub_f32_e32 v187, v54, v187
	v_sub_f32_e32 v188, v54, v188
	v_sub_f32_e32 v189, v54, v189
	v_mul_f32_e32 v186, 0x3fb8aa3b, v186
	v_mul_f32_e32 v187, 0x3fb8aa3b, v187
	v_mul_f32_e32 v188, 0x3fb8aa3b, v188
	v_mul_f32_e32 v189, 0x3fb8aa3b, v189
	v_exp_f32_e32 v186, v186
	v_exp_f32_e32 v187, v187
	v_exp_f32_e32 v188, v188
	v_exp_f32_e32 v189, v189
	v_mul_f32_e32 v4, v194, v186
	v_mul_f32_e32 v5, v195, v187
	v_mul_f32_e32 v6, v196, v188
	v_mul_f32_e32 v7, v197, v189
	s_waitcnt lgkmcnt(2)
	v_sub_f32_e32 v202, v54, v202
	v_sub_f32_e32 v203, v54, v203
	v_sub_f32_e32 v204, v54, v204
	v_sub_f32_e32 v205, v54, v205
	v_mul_f32_e32 v202, 0x3fb8aa3b, v202
	v_mul_f32_e32 v203, 0x3fb8aa3b, v203
	v_mul_f32_e32 v204, 0x3fb8aa3b, v204
	v_mul_f32_e32 v205, 0x3fb8aa3b, v205
	v_exp_f32_e32 v202, v202
	v_exp_f32_e32 v203, v203
	v_exp_f32_e32 v204, v204
	v_exp_f32_e32 v205, v205
	v_mul_f32_e32 v40, v210, v202
	v_mul_f32_e32 v41, v211, v203
	v_mul_f32_e32 v8, v212, v204
	v_mul_f32_e32 v9, v213, v205
	s_waitcnt lgkmcnt(0)
	v_sub_f32_e32 v218, v54, v218
	v_sub_f32_e32 v219, v54, v219
	v_sub_f32_e32 v220, v54, v220
	v_sub_f32_e32 v221, v54, v221
	v_mul_f32_e32 v218, 0x3fb8aa3b, v218
	v_mul_f32_e32 v219, 0x3fb8aa3b, v219
	v_mul_f32_e32 v220, 0x3fb8aa3b, v220
	v_mul_f32_e32 v221, 0x3fb8aa3b, v221
	v_exp_f32_e32 v218, v218
	v_exp_f32_e32 v219, v219
	v_exp_f32_e32 v220, v220
	v_exp_f32_e32 v221, v221
	v_mul_f32_e32 v10, v226, v218
	v_mul_f32_e32 v11, v227, v219
	v_mul_f32_e32 v12, v228, v220
	v_mul_f32_e32 v42, v229, v221
	s_branch .Lssdb4_done
.Lssdb4_gt:
	ds_read_b128 v[170:173], v236 offset:36352
	ds_read_b128 v[178:181], v236 offset:37376
	ds_read_b128 v[186:189], v236 offset:36384
	ds_read_b128 v[194:197], v236 offset:37408
	ds_read_b128 v[202:205], v236 offset:36416
	ds_read_b128 v[210:213], v236 offset:37440
	ds_read_b128 v[218:221], v236 offset:36448
	ds_read_b128 v[226:229], v236 offset:37472
	s_waitcnt lgkmcnt(6)
	v_sub_f32_e32 v170, v55, v170
	v_sub_f32_e32 v171, v55, v171
	v_sub_f32_e32 v172, v55, v172
	v_sub_f32_e32 v173, v55, v173
	v_mul_f32_e32 v170, 0x3fb8aa3b, v170
	v_mul_f32_e32 v171, 0x3fb8aa3b, v171
	v_mul_f32_e32 v172, 0x3fb8aa3b, v172
	v_mul_f32_e32 v173, 0x3fb8aa3b, v173
	v_exp_f32_e32 v170, v170
	v_exp_f32_e32 v171, v171
	v_exp_f32_e32 v172, v172
	v_exp_f32_e32 v173, v173
	v_mul_f32_e32 v0, v178, v170
	v_mul_f32_e32 v1, v179, v171
	v_mul_f32_e32 v2, v180, v172
	v_mul_f32_e32 v3, v181, v173
	s_waitcnt lgkmcnt(4)
	v_sub_f32_e32 v186, v55, v186
	v_sub_f32_e32 v187, v55, v187
	v_sub_f32_e32 v188, v55, v188
	v_sub_f32_e32 v189, v55, v189
	v_mul_f32_e32 v186, 0x3fb8aa3b, v186
	v_mul_f32_e32 v187, 0x3fb8aa3b, v187
	v_mul_f32_e32 v188, 0x3fb8aa3b, v188
	v_mul_f32_e32 v189, 0x3fb8aa3b, v189
	v_exp_f32_e32 v186, v186
	v_exp_f32_e32 v187, v187
	v_exp_f32_e32 v188, v188
	v_exp_f32_e32 v189, v189
	v_mul_f32_e32 v4, v194, v186
	v_mul_f32_e32 v5, v195, v187
	v_mul_f32_e32 v6, v196, v188
	v_mul_f32_e32 v7, v197, v189
	s_waitcnt lgkmcnt(2)
	v_sub_f32_e32 v202, v55, v202
	v_sub_f32_e32 v203, v55, v203
	v_sub_f32_e32 v204, v55, v204
	v_sub_f32_e32 v205, v55, v205
	v_mul_f32_e32 v202, 0x3fb8aa3b, v202
	v_mul_f32_e32 v203, 0x3fb8aa3b, v203
	v_mul_f32_e32 v204, 0x3fb8aa3b, v204
	v_mul_f32_e32 v205, 0x3fb8aa3b, v205
	v_exp_f32_e32 v202, v202
	v_exp_f32_e32 v203, v203
	v_exp_f32_e32 v204, v204
	v_exp_f32_e32 v205, v205
	v_mul_f32_e32 v40, v210, v202
	v_mul_f32_e32 v41, v211, v203
	v_mul_f32_e32 v8, v212, v204
	v_mul_f32_e32 v9, v213, v205
	s_waitcnt lgkmcnt(0)
	v_sub_f32_e32 v218, v55, v218
	v_sub_f32_e32 v219, v55, v219
	v_sub_f32_e32 v220, v55, v220
	v_sub_f32_e32 v221, v55, v221
	v_mul_f32_e32 v218, 0x3fb8aa3b, v218
	v_mul_f32_e32 v219, 0x3fb8aa3b, v219
	v_mul_f32_e32 v220, 0x3fb8aa3b, v220
	v_mul_f32_e32 v221, 0x3fb8aa3b, v221
	v_exp_f32_e32 v218, v218
	v_exp_f32_e32 v219, v219
	v_exp_f32_e32 v220, v220
	v_exp_f32_e32 v221, v221
	v_mul_f32_e32 v10, v226, v218
	v_mul_f32_e32 v11, v227, v219
	v_mul_f32_e32 v12, v228, v220
	v_mul_f32_e32 v42, v229, v221
.Lssdb4_done:
	v_mul_f32_e32 v16, v28, v4
	v_mul_u32_u24_e32 v4, 0x88, v56
	v_lshl_add_u32 v63, v58, 1, s23
	v_lshl_add_u32 v61, v4, 1, v63
	v_mul_f32_e32 v13, v31, v7
	v_mul_f32_e32 v14, v30, v6
	v_mul_f32_e32 v15, v29, v5
	ds_read2_b64 v[4:7], v61 offset1:2
	v_mul_f32_e32 v3, v27, v3
	v_mul_f32_e32 v2, v26, v2
	v_mul_f32_e32 v1, v25, v1
	v_mul_f32_e32 v0, v24, v0
	v_cvt_pk_bf16_f32 v0, v0, v1
	v_cvt_pk_bf16_f32 v1, v2, v3
	v_cvt_pk_bf16_f32 v2, v16, v15
	v_cvt_pk_bf16_f32 v3, v14, v13
	v_add_u32_e32 v62, 0x2000, v61
	v_mul_f32_e32 v44, v37, v11
	v_mul_f32_e32 v45, v36, v10
	v_mul_f32_e32 v46, v35, v9
	v_mul_f32_e32 v47, v34, v8
	ds_read2_b64 v[34:37], v61 offset0:4 offset1:6
	s_waitcnt lgkmcnt(1)
	v_mfma_f32_32x32x16_bf16 v[16:31], v[4:7], v[0:3], 0
	ds_read2_b64 v[4:7], v62 offset0:64 offset1:66
	v_mul_f32_e32 v43, v38, v12
	v_mul_f32_e32 v33, v33, v41
	v_mul_f32_e32 v32, v32, v40
	v_mul_f32_e32 v41, v39, v42
	v_cvt_pk_bf16_f32 v38, v32, v33
	v_cvt_pk_bf16_f32 v39, v47, v46
	v_cvt_pk_bf16_f32 v40, v45, v44
	v_cvt_pk_bf16_f32 v41, v43, v41
	s_waitcnt lgkmcnt(0)
	v_mfma_f32_32x32x16_bf16 v[0:15], v[4:7], v[0:3], 0
	v_mfma_f32_32x32x16_bf16 v[16:31], v[34:37], v[38:41], v[16:31]
	ds_read2_b64 v[32:35], v62 offset0:68 offset1:70
	v_or_b32_e32 v36, 32, v56
	v_mad_u32_u24 v65, v36, s39, v64
	s_waitcnt lgkmcnt(0)
	v_mfma_f32_32x32x16_bf16 v[0:15], v[32:35], v[38:41], v[0:15]
	ds_read_b128 v[32:35], v65 offset:17408
	ds_read_b128 v[66:69], v65 offset:17440
	s_waitcnt lgkmcnt(1)
	v_mfma_f32_32x32x16_bf16 v[32:47], v[32:35], v[48:51], 0
	s_waitcnt lgkmcnt(0)
	v_mfma_f32_32x32x16_bf16 v[32:47], v[66:69], v[102:105], v[32:47]
	ds_read_b128 v[66:69], v65 offset:17472
	ds_read_b128 v[70:73], v65 offset:17504
	s_waitcnt lgkmcnt(1)
	v_mfma_f32_32x32x16_bf16 v[32:47], v[66:69], v[98:101], v[32:47]
	v_or_b32_e32 v66, 32, v58
	v_cmp_ge_u32_e32 vcc, v66, v57
	s_waitcnt lgkmcnt(0)
	v_mfma_f32_32x32x16_bf16 v[32:47], v[70:73], v[94:97], v[32:47]
	v_lshl_add_u32 v236, v58, 2, s23
	v_lshrrev_b32_e32 v239, 5, v57
	s_nop 0
	v_readfirstlane_b32 s4, v239
	s_cmp_gt_u32 s4, 1
	s_cbranch_scc1 .Lssdb5_lt
	s_cmp_lt_u32 s4, 1
	s_cbranch_scc1 .Lssdb5_gt
	v_sub_u32_e32 v237, v57, v58
	ds_read_b128 v[170:173], v236 offset:35968
	ds_read_b128 v[174:177], v236 offset:36480
	ds_read_b128 v[178:181], v236 offset:36992
	ds_read_b128 v[182:185], v236 offset:37504
	ds_read_b128 v[186:189], v236 offset:36000
	ds_read_b128 v[190:193], v236 offset:36512
	ds_read_b128 v[194:197], v236 offset:37024
	ds_read_b128 v[198:201], v236 offset:37536
	ds_read_b128 v[202:205], v236 offset:36032
	ds_read_b128 v[206:209], v236 offset:36544
	ds_read_b128 v[210:213], v236 offset:37056
	ds_read_b128 v[214:217], v236 offset:37568
	s_waitcnt lgkmcnt(8)
	ds_read_b128 v[218:221], v236 offset:36064
	ds_read_b128 v[222:225], v236 offset:36576
	ds_read_b128 v[226:229], v236 offset:37088
	ds_read_b128 v[230:233], v236 offset:37600
	v_add_u32_e32 v238, 0xffffffe0, v237
	v_cmp_lt_i32_e32 vcc, 0, v238
	v_cmp_lt_i32_e64 s[4:5], 1, v238
	v_cmp_lt_i32_e64 s[6:7], 2, v238
	v_cmp_lt_i32_e64 s[30:31], 3, v238
	v_sub_f32_e32 v170, v54, v170
	v_sub_f32_e32 v171, v54, v171
	v_sub_f32_e32 v172, v54, v172
	v_sub_f32_e32 v173, v54, v173
	v_sub_f32_e32 v174, v55, v174
	v_sub_f32_e32 v175, v55, v175
	v_sub_f32_e32 v176, v55, v176
	v_sub_f32_e32 v177, v55, v177
	v_cndmask_b32_e64 v170, v174, v170, vcc
	v_cndmask_b32_e64 v171, v175, v171, s[4:5]
	v_cndmask_b32_e64 v172, v176, v172, s[6:7]
	v_cndmask_b32_e64 v173, v177, v173, s[30:31]
	v_add_f32_e32 v174, v178, v182
	v_add_f32_e32 v175, v179, v183
	v_add_f32_e32 v176, v180, v184
	v_add_f32_e32 v177, v181, v185
	v_cndmask_b32_e64 v178, v182, v178, vcc
	v_cndmask_b32_e64 v179, v183, v179, s[4:5]
	v_cndmask_b32_e64 v180, v184, v180, s[6:7]
	v_cndmask_b32_e64 v181, v185, v181, s[30:31]
	v_cmp_eq_u32_e32 vcc, 0, v238
	v_cmp_eq_u32_e64 s[4:5], 1, v238
	v_cmp_eq_u32_e64 s[6:7], 2, v238
	v_cmp_eq_u32_e64 s[30:31], 3, v238
	v_mul_f32_e32 v170, 0x3fb8aa3b, v170
	v_mul_f32_e32 v171, 0x3fb8aa3b, v171
	v_mul_f32_e32 v172, 0x3fb8aa3b, v172
	v_mul_f32_e32 v173, 0x3fb8aa3b, v173
	v_exp_f32_e32 v170, v170
	v_exp_f32_e32 v171, v171
	v_exp_f32_e32 v172, v172
	v_exp_f32_e32 v173, v173
	v_mul_f32_e32 v178, v178, v170
	v_mul_f32_e32 v179, v179, v171
	v_mul_f32_e32 v180, v180, v172
	v_mul_f32_e32 v181, v181, v173
	v_cndmask_b32_e64 v65, v178, v174, vcc
	v_cndmask_b32_e64 v66, v179, v175, s[4:5]
	v_cndmask_b32_e64 v67, v180, v176, s[6:7]
	v_cndmask_b32_e64 v68, v181, v177, s[30:31]
	s_waitcnt lgkmcnt(8)
	v_add_u32_e32 v238, 0xffffffd8, v237
	v_cmp_lt_i32_e32 vcc, 0, v238
	v_cmp_lt_i32_e64 s[4:5], 1, v238
	v_cmp_lt_i32_e64 s[6:7], 2, v238
	v_cmp_lt_i32_e64 s[30:31], 3, v238
	v_sub_f32_e32 v186, v54, v186
	v_sub_f32_e32 v187, v54, v187
	v_sub_f32_e32 v188, v54, v188
	v_sub_f32_e32 v189, v54, v189
	v_sub_f32_e32 v190, v55, v190
	v_sub_f32_e32 v191, v55, v191
	v_sub_f32_e32 v192, v55, v192
	v_sub_f32_e32 v193, v55, v193
	v_cndmask_b32_e64 v186, v190, v186, vcc
	v_cndmask_b32_e64 v187, v191, v187, s[4:5]
	v_cndmask_b32_e64 v188, v192, v188, s[6:7]
	v_cndmask_b32_e64 v189, v193, v189, s[30:31]
	v_add_f32_e32 v190, v194, v198
	v_add_f32_e32 v191, v195, v199
	v_add_f32_e32 v192, v196, v200
	v_add_f32_e32 v193, v197, v201
	v_cndmask_b32_e64 v194, v198, v194, vcc
	v_cndmask_b32_e64 v195, v199, v195, s[4:5]
	v_cndmask_b32_e64 v196, v200, v196, s[6:7]
	v_cndmask_b32_e64 v197, v201, v197, s[30:31]
	v_cmp_eq_u32_e32 vcc, 0, v238
	v_cmp_eq_u32_e64 s[4:5], 1, v238
	v_cmp_eq_u32_e64 s[6:7], 2, v238
	v_cmp_eq_u32_e64 s[30:31], 3, v238
	v_mul_f32_e32 v186, 0x3fb8aa3b, v186
	v_mul_f32_e32 v187, 0x3fb8aa3b, v187
	v_mul_f32_e32 v188, 0x3fb8aa3b, v188
	v_mul_f32_e32 v189, 0x3fb8aa3b, v189
	v_exp_f32_e32 v186, v186
	v_exp_f32_e32 v187, v187
	v_exp_f32_e32 v188, v188
	v_exp_f32_e32 v189, v189
	v_mul_f32_e32 v194, v194, v186
	v_mul_f32_e32 v195, v195, v187
	v_mul_f32_e32 v196, v196, v188
	v_mul_f32_e32 v197, v197, v189
	v_cndmask_b32_e64 v69, v194, v190, vcc
	v_cndmask_b32_e64 v70, v195, v191, s[4:5]
	v_cndmask_b32_e64 v71, v196, v192, s[6:7]
	v_cndmask_b32_e64 v72, v197, v193, s[30:31]
	s_waitcnt lgkmcnt(4)
	v_add_u32_e32 v238, 0xffffffd0, v237
	v_cmp_lt_i32_e32 vcc, 0, v238
	v_cmp_lt_i32_e64 s[4:5], 1, v238
	v_cmp_lt_i32_e64 s[6:7], 2, v238
	v_cmp_lt_i32_e64 s[30:31], 3, v238
	v_sub_f32_e32 v202, v54, v202
	v_sub_f32_e32 v203, v54, v203
	v_sub_f32_e32 v204, v54, v204
	v_sub_f32_e32 v205, v54, v205
	v_sub_f32_e32 v206, v55, v206
	v_sub_f32_e32 v207, v55, v207
	v_sub_f32_e32 v208, v55, v208
	v_sub_f32_e32 v209, v55, v209
	v_cndmask_b32_e64 v202, v206, v202, vcc
	v_cndmask_b32_e64 v203, v207, v203, s[4:5]
	v_cndmask_b32_e64 v204, v208, v204, s[6:7]
	v_cndmask_b32_e64 v205, v209, v205, s[30:31]
	v_add_f32_e32 v206, v210, v214
	v_add_f32_e32 v207, v211, v215
	v_add_f32_e32 v208, v212, v216
	v_add_f32_e32 v209, v213, v217
	v_cndmask_b32_e64 v210, v214, v210, vcc
	v_cndmask_b32_e64 v211, v215, v211, s[4:5]
	v_cndmask_b32_e64 v212, v216, v212, s[6:7]
	v_cndmask_b32_e64 v213, v217, v213, s[30:31]
	v_cmp_eq_u32_e32 vcc, 0, v238
	v_cmp_eq_u32_e64 s[4:5], 1, v238
	v_cmp_eq_u32_e64 s[6:7], 2, v238
	v_cmp_eq_u32_e64 s[30:31], 3, v238
	v_mul_f32_e32 v202, 0x3fb8aa3b, v202
	v_mul_f32_e32 v203, 0x3fb8aa3b, v203
	v_mul_f32_e32 v204, 0x3fb8aa3b, v204
	v_mul_f32_e32 v205, 0x3fb8aa3b, v205
	v_exp_f32_e32 v202, v202
	v_exp_f32_e32 v203, v203
	v_exp_f32_e32 v204, v204
	v_exp_f32_e32 v205, v205
	v_mul_f32_e32 v210, v210, v202
	v_mul_f32_e32 v211, v211, v203
	v_mul_f32_e32 v212, v212, v204
	v_mul_f32_e32 v213, v213, v205
	v_cndmask_b32_e64 v73, v210, v206, vcc
	v_cndmask_b32_e64 v74, v211, v207, s[4:5]
	v_cndmask_b32_e64 v75, v212, v208, s[6:7]
	v_cndmask_b32_e64 v76, v213, v209, s[30:31]
	s_waitcnt lgkmcnt(0)
	v_add_u32_e32 v238, 0xffffffc8, v237
	v_cmp_lt_i32_e32 vcc, 0, v238
	v_cmp_lt_i32_e64 s[4:5], 1, v238
	v_cmp_lt_i32_e64 s[6:7], 2, v238
	v_cmp_lt_i32_e64 s[30:31], 3, v238
	v_sub_f32_e32 v218, v54, v218
	v_sub_f32_e32 v219, v54, v219
	v_sub_f32_e32 v220, v54, v220
	v_sub_f32_e32 v221, v54, v221
	v_sub_f32_e32 v222, v55, v222
	v_sub_f32_e32 v223, v55, v223
	v_sub_f32_e32 v224, v55, v224
	v_sub_f32_e32 v225, v55, v225
	v_cndmask_b32_e64 v218, v222, v218, vcc
	v_cndmask_b32_e64 v219, v223, v219, s[4:5]
	v_cndmask_b32_e64 v220, v224, v220, s[6:7]
	v_cndmask_b32_e64 v221, v225, v221, s[30:31]
	v_add_f32_e32 v222, v226, v230
	v_add_f32_e32 v223, v227, v231
	v_add_f32_e32 v224, v228, v232
	v_add_f32_e32 v225, v229, v233
	v_cndmask_b32_e64 v226, v230, v226, vcc
	v_cndmask_b32_e64 v227, v231, v227, s[4:5]
	v_cndmask_b32_e64 v228, v232, v228, s[6:7]
	v_cndmask_b32_e64 v229, v233, v229, s[30:31]
	v_cmp_eq_u32_e32 vcc, 0, v238
	v_cmp_eq_u32_e64 s[4:5], 1, v238
	v_cmp_eq_u32_e64 s[6:7], 2, v238
	v_cmp_eq_u32_e64 s[30:31], 3, v238
	v_mul_f32_e32 v218, 0x3fb8aa3b, v218
	v_mul_f32_e32 v219, 0x3fb8aa3b, v219
	v_mul_f32_e32 v220, 0x3fb8aa3b, v220
	v_mul_f32_e32 v221, 0x3fb8aa3b, v221
	v_exp_f32_e32 v218, v218
	v_exp_f32_e32 v219, v219
	v_exp_f32_e32 v220, v220
	v_exp_f32_e32 v221, v221
	v_mul_f32_e32 v226, v226, v218
	v_mul_f32_e32 v227, v227, v219
	v_mul_f32_e32 v228, v228, v220
	v_mul_f32_e32 v229, v229, v221
	v_cndmask_b32_e64 v77, v226, v222, vcc
	v_cndmask_b32_e64 v78, v227, v223, s[4:5]
	v_cndmask_b32_e64 v79, v228, v224, s[6:7]
	v_cndmask_b32_e64 v80, v229, v225, s[30:31]
	s_branch .Lssdb5_done
.Lssdb5_lt:
	ds_read_b128 v[170:173], v236 offset:35968
	ds_read_b128 v[178:181], v236 offset:36992
	ds_read_b128 v[186:189], v236 offset:36000
	ds_read_b128 v[194:197], v236 offset:37024
	ds_read_b128 v[202:205], v236 offset:36032
	ds_read_b128 v[210:213], v236 offset:37056
	ds_read_b128 v[218:221], v236 offset:36064
	ds_read_b128 v[226:229], v236 offset:37088
	s_waitcnt lgkmcnt(6)
	v_sub_f32_e32 v170, v54, v170
	v_sub_f32_e32 v171, v54, v171
	v_sub_f32_e32 v172, v54, v172
	v_sub_f32_e32 v173, v54, v173
	v_mul_f32_e32 v170, 0x3fb8aa3b, v170
	v_mul_f32_e32 v171, 0x3fb8aa3b, v171
	v_mul_f32_e32 v172, 0x3fb8aa3b, v172
	v_mul_f32_e32 v173, 0x3fb8aa3b, v173
	v_exp_f32_e32 v170, v170
	v_exp_f32_e32 v171, v171
	v_exp_f32_e32 v172, v172
	v_exp_f32_e32 v173, v173
	v_mul_f32_e32 v65, v178, v170
	v_mul_f32_e32 v66, v179, v171
	v_mul_f32_e32 v67, v180, v172
	v_mul_f32_e32 v68, v181, v173
	s_waitcnt lgkmcnt(4)
	v_sub_f32_e32 v186, v54, v186
	v_sub_f32_e32 v187, v54, v187
	v_sub_f32_e32 v188, v54, v188
	v_sub_f32_e32 v189, v54, v189
	v_mul_f32_e32 v186, 0x3fb8aa3b, v186
	v_mul_f32_e32 v187, 0x3fb8aa3b, v187
	v_mul_f32_e32 v188, 0x3fb8aa3b, v188
	v_mul_f32_e32 v189, 0x3fb8aa3b, v189
	v_exp_f32_e32 v186, v186
	v_exp_f32_e32 v187, v187
	v_exp_f32_e32 v188, v188
	v_exp_f32_e32 v189, v189
	v_mul_f32_e32 v69, v194, v186
	v_mul_f32_e32 v70, v195, v187
	v_mul_f32_e32 v71, v196, v188
	v_mul_f32_e32 v72, v197, v189
	s_waitcnt lgkmcnt(2)
	v_sub_f32_e32 v202, v54, v202
	v_sub_f32_e32 v203, v54, v203
	v_sub_f32_e32 v204, v54, v204
	v_sub_f32_e32 v205, v54, v205
	v_mul_f32_e32 v202, 0x3fb8aa3b, v202
	v_mul_f32_e32 v203, 0x3fb8aa3b, v203
	v_mul_f32_e32 v204, 0x3fb8aa3b, v204
	v_mul_f32_e32 v205, 0x3fb8aa3b, v205
	v_exp_f32_e32 v202, v202
	v_exp_f32_e32 v203, v203
	v_exp_f32_e32 v204, v204
	v_exp_f32_e32 v205, v205
	v_mul_f32_e32 v73, v210, v202
	v_mul_f32_e32 v74, v211, v203
	v_mul_f32_e32 v75, v212, v204
	v_mul_f32_e32 v76, v213, v205
	s_waitcnt lgkmcnt(0)
	v_sub_f32_e32 v218, v54, v218
	v_sub_f32_e32 v219, v54, v219
	v_sub_f32_e32 v220, v54, v220
	v_sub_f32_e32 v221, v54, v221
	v_mul_f32_e32 v218, 0x3fb8aa3b, v218
	v_mul_f32_e32 v219, 0x3fb8aa3b, v219
	v_mul_f32_e32 v220, 0x3fb8aa3b, v220
	v_mul_f32_e32 v221, 0x3fb8aa3b, v221
	v_exp_f32_e32 v218, v218
	v_exp_f32_e32 v219, v219
	v_exp_f32_e32 v220, v220
	v_exp_f32_e32 v221, v221
	v_mul_f32_e32 v77, v226, v218
	v_mul_f32_e32 v78, v227, v219
	v_mul_f32_e32 v79, v228, v220
	v_mul_f32_e32 v80, v229, v221
	s_branch .Lssdb5_done
.Lssdb5_gt:
	ds_read_b128 v[170:173], v236 offset:36480
	ds_read_b128 v[178:181], v236 offset:37504
	ds_read_b128 v[186:189], v236 offset:36512
	ds_read_b128 v[194:197], v236 offset:37536
	ds_read_b128 v[202:205], v236 offset:36544
	ds_read_b128 v[210:213], v236 offset:37568
	ds_read_b128 v[218:221], v236 offset:36576
	ds_read_b128 v[226:229], v236 offset:37600
	s_waitcnt lgkmcnt(6)
	v_sub_f32_e32 v170, v55, v170
	v_sub_f32_e32 v171, v55, v171
	v_sub_f32_e32 v172, v55, v172
	v_sub_f32_e32 v173, v55, v173
	v_mul_f32_e32 v170, 0x3fb8aa3b, v170
	v_mul_f32_e32 v171, 0x3fb8aa3b, v171
	v_mul_f32_e32 v172, 0x3fb8aa3b, v172
	v_mul_f32_e32 v173, 0x3fb8aa3b, v173
	v_exp_f32_e32 v170, v170
	v_exp_f32_e32 v171, v171
	v_exp_f32_e32 v172, v172
	v_exp_f32_e32 v173, v173
	v_mul_f32_e32 v65, v178, v170
	v_mul_f32_e32 v66, v179, v171
	v_mul_f32_e32 v67, v180, v172
	v_mul_f32_e32 v68, v181, v173
	s_waitcnt lgkmcnt(4)
	v_sub_f32_e32 v186, v55, v186
	v_sub_f32_e32 v187, v55, v187
	v_sub_f32_e32 v188, v55, v188
	v_sub_f32_e32 v189, v55, v189
	v_mul_f32_e32 v186, 0x3fb8aa3b, v186
	v_mul_f32_e32 v187, 0x3fb8aa3b, v187
	v_mul_f32_e32 v188, 0x3fb8aa3b, v188
	v_mul_f32_e32 v189, 0x3fb8aa3b, v189
	v_exp_f32_e32 v186, v186
	v_exp_f32_e32 v187, v187
	v_exp_f32_e32 v188, v188
	v_exp_f32_e32 v189, v189
	v_mul_f32_e32 v69, v194, v186
	v_mul_f32_e32 v70, v195, v187
	v_mul_f32_e32 v71, v196, v188
	v_mul_f32_e32 v72, v197, v189
	s_waitcnt lgkmcnt(2)
	v_sub_f32_e32 v202, v55, v202
	v_sub_f32_e32 v203, v55, v203
	v_sub_f32_e32 v204, v55, v204
	v_sub_f32_e32 v205, v55, v205
	v_mul_f32_e32 v202, 0x3fb8aa3b, v202
	v_mul_f32_e32 v203, 0x3fb8aa3b, v203
	v_mul_f32_e32 v204, 0x3fb8aa3b, v204
	v_mul_f32_e32 v205, 0x3fb8aa3b, v205
	v_exp_f32_e32 v202, v202
	v_exp_f32_e32 v203, v203
	v_exp_f32_e32 v204, v204
	v_exp_f32_e32 v205, v205
	v_mul_f32_e32 v73, v210, v202
	v_mul_f32_e32 v74, v211, v203
	v_mul_f32_e32 v75, v212, v204
	v_mul_f32_e32 v76, v213, v205
	s_waitcnt lgkmcnt(0)
	v_sub_f32_e32 v218, v55, v218
	v_sub_f32_e32 v219, v55, v219
	v_sub_f32_e32 v220, v55, v220
	v_sub_f32_e32 v221, v55, v221
	v_mul_f32_e32 v218, 0x3fb8aa3b, v218
	v_mul_f32_e32 v219, 0x3fb8aa3b, v219
	v_mul_f32_e32 v220, 0x3fb8aa3b, v220
	v_mul_f32_e32 v221, 0x3fb8aa3b, v221
	v_exp_f32_e32 v218, v218
	v_exp_f32_e32 v219, v219
	v_exp_f32_e32 v220, v220
	v_exp_f32_e32 v221, v221
	v_mul_f32_e32 v77, v226, v218
	v_mul_f32_e32 v78, v227, v219
	v_mul_f32_e32 v79, v228, v220
	v_mul_f32_e32 v80, v229, v221
.Lssdb5_done:
	v_mul_f32_e32 v72, v39, v72
	v_mul_f32_e32 v71, v38, v71
	v_mul_f32_e32 v70, v37, v70
	v_mul_f32_e32 v69, v36, v69
	ds_read2_b64 v[36:39], v61 offset0:8 offset1:10
	v_mul_f32_e32 v35, v35, v68
	v_mul_f32_e32 v34, v34, v67
	v_mul_f32_e32 v33, v33, v66
	v_mul_f32_e32 v32, v32, v65
	v_cvt_pk_bf16_f32 v32, v32, v33
	v_cvt_pk_bf16_f32 v33, v34, v35
	v_cvt_pk_bf16_f32 v34, v69, v70
	v_cvt_pk_bf16_f32 v35, v71, v72
	v_mul_f32_e32 v65, v45, v78
	v_mul_f32_e32 v66, v44, v77
	s_waitcnt lgkmcnt(0)
	v_mfma_f32_32x32x16_bf16 v[16:31], v[36:39], v[32:35], v[16:31]
	ds_read2_b64 v[36:39], v62 offset0:72 offset1:74
	v_mul_f32_e32 v67, v43, v76
	v_mul_f32_e32 v68, v42, v75
	ds_read2_b64 v[42:45], v61 offset0:12 offset1:14
	v_mul_f32_e32 v46, v46, v79
	s_waitcnt lgkmcnt(1)
	v_mfma_f32_32x32x16_bf16 v[0:15], v[36:39], v[32:35], v[0:15]
	ds_read2_b64 v[36:39], v62 offset0:76 offset1:78
	v_mul_f32_e32 v32, v41, v74
	v_mul_f32_e32 v33, v40, v73
	v_mul_f32_e32 v35, v47, v80
	v_mul_u32_u24_e32 v40, 0x90, v56
	v_cvt_pk_bf16_f32 v32, v33, v32
	v_cvt_pk_bf16_f32 v33, v68, v67
	v_cvt_pk_bf16_f32 v34, v66, v65
	v_cvt_pk_bf16_f32 v35, v46, v35
	v_add_u32_e32 v64, v64, v40
	s_waitcnt lgkmcnt(1)
	v_mfma_f32_32x32x16_bf16 v[16:31], v[42:45], v[32:35], v[16:31]
	s_waitcnt lgkmcnt(0)
	v_mfma_f32_32x32x16_bf16 v[0:15], v[36:39], v[32:35], v[0:15]
	ds_read_b128 v[32:35], v64 offset:26624
	ds_read_b128 v[66:69], v64 offset:26656
	s_waitcnt lgkmcnt(1)
	v_mfma_f32_32x32x16_bf16 v[32:47], v[32:35], v[48:51], 0
	s_waitcnt lgkmcnt(0)
	v_mfma_f32_32x32x16_bf16 v[32:47], v[66:69], v[102:105], v[32:47]
	ds_read_b128 v[66:69], v64 offset:26688
	ds_read_b128 v[70:73], v64 offset:26720
	s_waitcnt lgkmcnt(1)
	v_mfma_f32_32x32x16_bf16 v[32:47], v[66:69], v[98:101], v[32:47]
	v_or_b32_e32 v66, 64, v58
	v_cmp_ge_u32_e32 vcc, v66, v57
	s_waitcnt lgkmcnt(0)
	v_mfma_f32_32x32x16_bf16 v[32:47], v[70:73], v[94:97], v[32:47]
	v_lshl_add_u32 v236, v58, 2, s23
	v_lshrrev_b32_e32 v239, 5, v57
	s_nop 0
	v_readfirstlane_b32 s4, v239
	s_cmp_gt_u32 s4, 2
	s_cbranch_scc1 .Lssdb6_lt
	s_cmp_lt_u32 s4, 2
	s_cbranch_scc1 .Lssdb6_gt
	v_sub_u32_e32 v237, v57, v58
	ds_read_b128 v[170:173], v236 offset:36096
	ds_read_b128 v[174:177], v236 offset:36608
	ds_read_b128 v[178:181], v236 offset:37120
	ds_read_b128 v[182:185], v236 offset:37632
	ds_read_b128 v[186:189], v236 offset:36128
	ds_read_b128 v[190:193], v236 offset:36640
	ds_read_b128 v[194:197], v236 offset:37152
	ds_read_b128 v[198:201], v236 offset:37664
	ds_read_b128 v[202:205], v236 offset:36160
	ds_read_b128 v[206:209], v236 offset:36672
	ds_read_b128 v[210:213], v236 offset:37184
	ds_read_b128 v[214:217], v236 offset:37696
	s_waitcnt lgkmcnt(8)
	ds_read_b128 v[218:221], v236 offset:36192
	ds_read_b128 v[222:225], v236 offset:36704
	ds_read_b128 v[226:229], v236 offset:37216
	ds_read_b128 v[230:233], v236 offset:37728
	v_add_u32_e32 v238, 0xffffffc0, v237
	v_cmp_lt_i32_e32 vcc, 0, v238
	v_cmp_lt_i32_e64 s[4:5], 1, v238
	v_cmp_lt_i32_e64 s[6:7], 2, v238
	v_cmp_lt_i32_e64 s[30:31], 3, v238
	v_sub_f32_e32 v170, v54, v170
	v_sub_f32_e32 v171, v54, v171
	v_sub_f32_e32 v172, v54, v172
	v_sub_f32_e32 v173, v54, v173
	v_sub_f32_e32 v174, v55, v174
	v_sub_f32_e32 v175, v55, v175
	v_sub_f32_e32 v176, v55, v176
	v_sub_f32_e32 v177, v55, v177
	v_cndmask_b32_e64 v170, v174, v170, vcc
	v_cndmask_b32_e64 v171, v175, v171, s[4:5]
	v_cndmask_b32_e64 v172, v176, v172, s[6:7]
	v_cndmask_b32_e64 v173, v177, v173, s[30:31]
	v_add_f32_e32 v174, v178, v182
	v_add_f32_e32 v175, v179, v183
	v_add_f32_e32 v176, v180, v184
	v_add_f32_e32 v177, v181, v185
	v_cndmask_b32_e64 v178, v182, v178, vcc
	v_cndmask_b32_e64 v179, v183, v179, s[4:5]
	v_cndmask_b32_e64 v180, v184, v180, s[6:7]
	v_cndmask_b32_e64 v181, v185, v181, s[30:31]
	v_cmp_eq_u32_e32 vcc, 0, v238
	v_cmp_eq_u32_e64 s[4:5], 1, v238
	v_cmp_eq_u32_e64 s[6:7], 2, v238
	v_cmp_eq_u32_e64 s[30:31], 3, v238
	v_mul_f32_e32 v170, 0x3fb8aa3b, v170
	v_mul_f32_e32 v171, 0x3fb8aa3b, v171
	v_mul_f32_e32 v172, 0x3fb8aa3b, v172
	v_mul_f32_e32 v173, 0x3fb8aa3b, v173
	v_exp_f32_e32 v170, v170
	v_exp_f32_e32 v171, v171
	v_exp_f32_e32 v172, v172
	v_exp_f32_e32 v173, v173
	v_mul_f32_e32 v178, v178, v170
	v_mul_f32_e32 v179, v179, v171
	v_mul_f32_e32 v180, v180, v172
	v_mul_f32_e32 v181, v181, v173
	v_cndmask_b32_e64 v65, v178, v174, vcc
	v_cndmask_b32_e64 v66, v179, v175, s[4:5]
	v_cndmask_b32_e64 v67, v180, v176, s[6:7]
	v_cndmask_b32_e64 v68, v181, v177, s[30:31]
	s_waitcnt lgkmcnt(8)
	v_add_u32_e32 v238, 0xffffffb8, v237
	v_cmp_lt_i32_e32 vcc, 0, v238
	v_cmp_lt_i32_e64 s[4:5], 1, v238
	v_cmp_lt_i32_e64 s[6:7], 2, v238
	v_cmp_lt_i32_e64 s[30:31], 3, v238
	v_sub_f32_e32 v186, v54, v186
	v_sub_f32_e32 v187, v54, v187
	v_sub_f32_e32 v188, v54, v188
	v_sub_f32_e32 v189, v54, v189
	v_sub_f32_e32 v190, v55, v190
	v_sub_f32_e32 v191, v55, v191
	v_sub_f32_e32 v192, v55, v192
	v_sub_f32_e32 v193, v55, v193
	v_cndmask_b32_e64 v186, v190, v186, vcc
	v_cndmask_b32_e64 v187, v191, v187, s[4:5]
	v_cndmask_b32_e64 v188, v192, v188, s[6:7]
	v_cndmask_b32_e64 v189, v193, v189, s[30:31]
	v_add_f32_e32 v190, v194, v198
	v_add_f32_e32 v191, v195, v199
	v_add_f32_e32 v192, v196, v200
	v_add_f32_e32 v193, v197, v201
	v_cndmask_b32_e64 v194, v198, v194, vcc
	v_cndmask_b32_e64 v195, v199, v195, s[4:5]
	v_cndmask_b32_e64 v196, v200, v196, s[6:7]
	v_cndmask_b32_e64 v197, v201, v197, s[30:31]
	v_cmp_eq_u32_e32 vcc, 0, v238
	v_cmp_eq_u32_e64 s[4:5], 1, v238
	v_cmp_eq_u32_e64 s[6:7], 2, v238
	v_cmp_eq_u32_e64 s[30:31], 3, v238
	v_mul_f32_e32 v186, 0x3fb8aa3b, v186
	v_mul_f32_e32 v187, 0x3fb8aa3b, v187
	v_mul_f32_e32 v188, 0x3fb8aa3b, v188
	v_mul_f32_e32 v189, 0x3fb8aa3b, v189
	v_exp_f32_e32 v186, v186
	v_exp_f32_e32 v187, v187
	v_exp_f32_e32 v188, v188
	v_exp_f32_e32 v189, v189
	v_mul_f32_e32 v194, v194, v186
	v_mul_f32_e32 v195, v195, v187
	v_mul_f32_e32 v196, v196, v188
	v_mul_f32_e32 v197, v197, v189
	v_cndmask_b32_e64 v69, v194, v190, vcc
	v_cndmask_b32_e64 v70, v195, v191, s[4:5]
	v_cndmask_b32_e64 v71, v196, v192, s[6:7]
	v_cndmask_b32_e64 v72, v197, v193, s[30:31]
	s_waitcnt lgkmcnt(4)
	v_add_u32_e32 v238, 0xffffffb0, v237
	v_cmp_lt_i32_e32 vcc, 0, v238
	v_cmp_lt_i32_e64 s[4:5], 1, v238
	v_cmp_lt_i32_e64 s[6:7], 2, v238
	v_cmp_lt_i32_e64 s[30:31], 3, v238
	v_sub_f32_e32 v202, v54, v202
	v_sub_f32_e32 v203, v54, v203
	v_sub_f32_e32 v204, v54, v204
	v_sub_f32_e32 v205, v54, v205
	v_sub_f32_e32 v206, v55, v206
	v_sub_f32_e32 v207, v55, v207
	v_sub_f32_e32 v208, v55, v208
	v_sub_f32_e32 v209, v55, v209
	v_cndmask_b32_e64 v202, v206, v202, vcc
	v_cndmask_b32_e64 v203, v207, v203, s[4:5]
	v_cndmask_b32_e64 v204, v208, v204, s[6:7]
	v_cndmask_b32_e64 v205, v209, v205, s[30:31]
	v_add_f32_e32 v206, v210, v214
	v_add_f32_e32 v207, v211, v215
	v_add_f32_e32 v208, v212, v216
	v_add_f32_e32 v209, v213, v217
	v_cndmask_b32_e64 v210, v214, v210, vcc
	v_cndmask_b32_e64 v211, v215, v211, s[4:5]
	v_cndmask_b32_e64 v212, v216, v212, s[6:7]
	v_cndmask_b32_e64 v213, v217, v213, s[30:31]
	v_cmp_eq_u32_e32 vcc, 0, v238
	v_cmp_eq_u32_e64 s[4:5], 1, v238
	v_cmp_eq_u32_e64 s[6:7], 2, v238
	v_cmp_eq_u32_e64 s[30:31], 3, v238
	v_mul_f32_e32 v202, 0x3fb8aa3b, v202
	v_mul_f32_e32 v203, 0x3fb8aa3b, v203
	v_mul_f32_e32 v204, 0x3fb8aa3b, v204
	v_mul_f32_e32 v205, 0x3fb8aa3b, v205
	v_exp_f32_e32 v202, v202
	v_exp_f32_e32 v203, v203
	v_exp_f32_e32 v204, v204
	v_exp_f32_e32 v205, v205
	v_mul_f32_e32 v210, v210, v202
	v_mul_f32_e32 v211, v211, v203
	v_mul_f32_e32 v212, v212, v204
	v_mul_f32_e32 v213, v213, v205
	v_cndmask_b32_e64 v73, v210, v206, vcc
	v_cndmask_b32_e64 v74, v211, v207, s[4:5]
	v_cndmask_b32_e64 v75, v212, v208, s[6:7]
	v_cndmask_b32_e64 v76, v213, v209, s[30:31]
	s_waitcnt lgkmcnt(0)
	v_add_u32_e32 v238, 0xffffffa8, v237
	v_cmp_lt_i32_e32 vcc, 0, v238
	v_cmp_lt_i32_e64 s[4:5], 1, v238
	v_cmp_lt_i32_e64 s[6:7], 2, v238
	v_cmp_lt_i32_e64 s[30:31], 3, v238
	v_sub_f32_e32 v218, v54, v218
	v_sub_f32_e32 v219, v54, v219
	v_sub_f32_e32 v220, v54, v220
	v_sub_f32_e32 v221, v54, v221
	v_sub_f32_e32 v222, v55, v222
	v_sub_f32_e32 v223, v55, v223
	v_sub_f32_e32 v224, v55, v224
	v_sub_f32_e32 v225, v55, v225
	v_cndmask_b32_e64 v218, v222, v218, vcc
	v_cndmask_b32_e64 v219, v223, v219, s[4:5]
	v_cndmask_b32_e64 v220, v224, v220, s[6:7]
	v_cndmask_b32_e64 v221, v225, v221, s[30:31]
	v_add_f32_e32 v222, v226, v230
	v_add_f32_e32 v223, v227, v231
	v_add_f32_e32 v224, v228, v232
	v_add_f32_e32 v225, v229, v233
	v_cndmask_b32_e64 v226, v230, v226, vcc
	v_cndmask_b32_e64 v227, v231, v227, s[4:5]
	v_cndmask_b32_e64 v228, v232, v228, s[6:7]
	v_cndmask_b32_e64 v229, v233, v229, s[30:31]
	v_cmp_eq_u32_e32 vcc, 0, v238
	v_cmp_eq_u32_e64 s[4:5], 1, v238
	v_cmp_eq_u32_e64 s[6:7], 2, v238
	v_cmp_eq_u32_e64 s[30:31], 3, v238
	v_mul_f32_e32 v218, 0x3fb8aa3b, v218
	v_mul_f32_e32 v219, 0x3fb8aa3b, v219
	v_mul_f32_e32 v220, 0x3fb8aa3b, v220
	v_mul_f32_e32 v221, 0x3fb8aa3b, v221
	v_exp_f32_e32 v218, v218
	v_exp_f32_e32 v219, v219
	v_exp_f32_e32 v220, v220
	v_exp_f32_e32 v221, v221
	v_mul_f32_e32 v226, v226, v218
	v_mul_f32_e32 v227, v227, v219
	v_mul_f32_e32 v228, v228, v220
	v_mul_f32_e32 v229, v229, v221
	v_cndmask_b32_e64 v77, v226, v222, vcc
	v_cndmask_b32_e64 v78, v227, v223, s[4:5]
	v_cndmask_b32_e64 v79, v228, v224, s[6:7]
	v_cndmask_b32_e64 v80, v229, v225, s[30:31]
	s_branch .Lssdb6_done
.Lssdb6_lt:
	ds_read_b128 v[170:173], v236 offset:36096
	ds_read_b128 v[178:181], v236 offset:37120
	ds_read_b128 v[186:189], v236 offset:36128
	ds_read_b128 v[194:197], v236 offset:37152
	ds_read_b128 v[202:205], v236 offset:36160
	ds_read_b128 v[210:213], v236 offset:37184
	ds_read_b128 v[218:221], v236 offset:36192
	ds_read_b128 v[226:229], v236 offset:37216
	s_waitcnt lgkmcnt(6)
	v_sub_f32_e32 v170, v54, v170
	v_sub_f32_e32 v171, v54, v171
	v_sub_f32_e32 v172, v54, v172
	v_sub_f32_e32 v173, v54, v173
	v_mul_f32_e32 v170, 0x3fb8aa3b, v170
	v_mul_f32_e32 v171, 0x3fb8aa3b, v171
	v_mul_f32_e32 v172, 0x3fb8aa3b, v172
	v_mul_f32_e32 v173, 0x3fb8aa3b, v173
	v_exp_f32_e32 v170, v170
	v_exp_f32_e32 v171, v171
	v_exp_f32_e32 v172, v172
	v_exp_f32_e32 v173, v173
	v_mul_f32_e32 v65, v178, v170
	v_mul_f32_e32 v66, v179, v171
	v_mul_f32_e32 v67, v180, v172
	v_mul_f32_e32 v68, v181, v173
	s_waitcnt lgkmcnt(4)
	v_sub_f32_e32 v186, v54, v186
	v_sub_f32_e32 v187, v54, v187
	v_sub_f32_e32 v188, v54, v188
	v_sub_f32_e32 v189, v54, v189
	v_mul_f32_e32 v186, 0x3fb8aa3b, v186
	v_mul_f32_e32 v187, 0x3fb8aa3b, v187
	v_mul_f32_e32 v188, 0x3fb8aa3b, v188
	v_mul_f32_e32 v189, 0x3fb8aa3b, v189
	v_exp_f32_e32 v186, v186
	v_exp_f32_e32 v187, v187
	v_exp_f32_e32 v188, v188
	v_exp_f32_e32 v189, v189
	v_mul_f32_e32 v69, v194, v186
	v_mul_f32_e32 v70, v195, v187
	v_mul_f32_e32 v71, v196, v188
	v_mul_f32_e32 v72, v197, v189
	s_waitcnt lgkmcnt(2)
	v_sub_f32_e32 v202, v54, v202
	v_sub_f32_e32 v203, v54, v203
	v_sub_f32_e32 v204, v54, v204
	v_sub_f32_e32 v205, v54, v205
	v_mul_f32_e32 v202, 0x3fb8aa3b, v202
	v_mul_f32_e32 v203, 0x3fb8aa3b, v203
	v_mul_f32_e32 v204, 0x3fb8aa3b, v204
	v_mul_f32_e32 v205, 0x3fb8aa3b, v205
	v_exp_f32_e32 v202, v202
	v_exp_f32_e32 v203, v203
	v_exp_f32_e32 v204, v204
	v_exp_f32_e32 v205, v205
	v_mul_f32_e32 v73, v210, v202
	v_mul_f32_e32 v74, v211, v203
	v_mul_f32_e32 v75, v212, v204
	v_mul_f32_e32 v76, v213, v205
	s_waitcnt lgkmcnt(0)
	v_sub_f32_e32 v218, v54, v218
	v_sub_f32_e32 v219, v54, v219
	v_sub_f32_e32 v220, v54, v220
	v_sub_f32_e32 v221, v54, v221
	v_mul_f32_e32 v218, 0x3fb8aa3b, v218
	v_mul_f32_e32 v219, 0x3fb8aa3b, v219
	v_mul_f32_e32 v220, 0x3fb8aa3b, v220
	v_mul_f32_e32 v221, 0x3fb8aa3b, v221
	v_exp_f32_e32 v218, v218
	v_exp_f32_e32 v219, v219
	v_exp_f32_e32 v220, v220
	v_exp_f32_e32 v221, v221
	v_mul_f32_e32 v77, v226, v218
	v_mul_f32_e32 v78, v227, v219
	v_mul_f32_e32 v79, v228, v220
	v_mul_f32_e32 v80, v229, v221
	s_branch .Lssdb6_done
.Lssdb6_gt:
	ds_read_b128 v[170:173], v236 offset:36608
	ds_read_b128 v[178:181], v236 offset:37632
	ds_read_b128 v[186:189], v236 offset:36640
	ds_read_b128 v[194:197], v236 offset:37664
	ds_read_b128 v[202:205], v236 offset:36672
	ds_read_b128 v[210:213], v236 offset:37696
	ds_read_b128 v[218:221], v236 offset:36704
	ds_read_b128 v[226:229], v236 offset:37728
	s_waitcnt lgkmcnt(6)
	v_sub_f32_e32 v170, v55, v170
	v_sub_f32_e32 v171, v55, v171
	v_sub_f32_e32 v172, v55, v172
	v_sub_f32_e32 v173, v55, v173
	v_mul_f32_e32 v170, 0x3fb8aa3b, v170
	v_mul_f32_e32 v171, 0x3fb8aa3b, v171
	v_mul_f32_e32 v172, 0x3fb8aa3b, v172
	v_mul_f32_e32 v173, 0x3fb8aa3b, v173
	v_exp_f32_e32 v170, v170
	v_exp_f32_e32 v171, v171
	v_exp_f32_e32 v172, v172
	v_exp_f32_e32 v173, v173
	v_mul_f32_e32 v65, v178, v170
	v_mul_f32_e32 v66, v179, v171
	v_mul_f32_e32 v67, v180, v172
	v_mul_f32_e32 v68, v181, v173
	s_waitcnt lgkmcnt(4)
	v_sub_f32_e32 v186, v55, v186
	v_sub_f32_e32 v187, v55, v187
	v_sub_f32_e32 v188, v55, v188
	v_sub_f32_e32 v189, v55, v189
	v_mul_f32_e32 v186, 0x3fb8aa3b, v186
	v_mul_f32_e32 v187, 0x3fb8aa3b, v187
	v_mul_f32_e32 v188, 0x3fb8aa3b, v188
	v_mul_f32_e32 v189, 0x3fb8aa3b, v189
	v_exp_f32_e32 v186, v186
	v_exp_f32_e32 v187, v187
	v_exp_f32_e32 v188, v188
	v_exp_f32_e32 v189, v189
	v_mul_f32_e32 v69, v194, v186
	v_mul_f32_e32 v70, v195, v187
	v_mul_f32_e32 v71, v196, v188
	v_mul_f32_e32 v72, v197, v189
	s_waitcnt lgkmcnt(2)
	v_sub_f32_e32 v202, v55, v202
	v_sub_f32_e32 v203, v55, v203
	v_sub_f32_e32 v204, v55, v204
	v_sub_f32_e32 v205, v55, v205
	v_mul_f32_e32 v202, 0x3fb8aa3b, v202
	v_mul_f32_e32 v203, 0x3fb8aa3b, v203
	v_mul_f32_e32 v204, 0x3fb8aa3b, v204
	v_mul_f32_e32 v205, 0x3fb8aa3b, v205
	v_exp_f32_e32 v202, v202
	v_exp_f32_e32 v203, v203
	v_exp_f32_e32 v204, v204
	v_exp_f32_e32 v205, v205
	v_mul_f32_e32 v73, v210, v202
	v_mul_f32_e32 v74, v211, v203
	v_mul_f32_e32 v75, v212, v204
	v_mul_f32_e32 v76, v213, v205
	s_waitcnt lgkmcnt(0)
	v_sub_f32_e32 v218, v55, v218
	v_sub_f32_e32 v219, v55, v219
	v_sub_f32_e32 v220, v55, v220
	v_sub_f32_e32 v221, v55, v221
	v_mul_f32_e32 v218, 0x3fb8aa3b, v218
	v_mul_f32_e32 v219, 0x3fb8aa3b, v219
	v_mul_f32_e32 v220, 0x3fb8aa3b, v220
	v_mul_f32_e32 v221, 0x3fb8aa3b, v221
	v_exp_f32_e32 v218, v218
	v_exp_f32_e32 v219, v219
	v_exp_f32_e32 v220, v220
	v_exp_f32_e32 v221, v221
	v_mul_f32_e32 v77, v226, v218
	v_mul_f32_e32 v78, v227, v219
	v_mul_f32_e32 v79, v228, v220
	v_mul_f32_e32 v80, v229, v221
.Lssdb6_done:
	v_mul_f32_e32 v72, v39, v72
	v_mul_f32_e32 v71, v38, v71
	v_mul_f32_e32 v70, v37, v70
	v_mul_f32_e32 v69, v36, v69
	ds_read2_b64 v[36:39], v61 offset0:16 offset1:18
	v_mul_f32_e32 v35, v35, v68
	v_mul_f32_e32 v34, v34, v67
	v_mul_f32_e32 v33, v33, v66
	v_mul_f32_e32 v32, v32, v65
	v_cvt_pk_bf16_f32 v32, v32, v33
	v_cvt_pk_bf16_f32 v33, v34, v35
	v_cvt_pk_bf16_f32 v34, v69, v70
	v_cvt_pk_bf16_f32 v35, v71, v72
	v_mul_f32_e32 v65, v45, v78
	v_mul_f32_e32 v66, v44, v77
	s_waitcnt lgkmcnt(0)
	v_mfma_f32_32x32x16_bf16 v[16:31], v[36:39], v[32:35], v[16:31]
	ds_read2_b64 v[36:39], v62 offset0:80 offset1:82
	v_mul_f32_e32 v67, v43, v76
	v_mul_f32_e32 v68, v42, v75
	ds_read2_b64 v[42:45], v61 offset0:20 offset1:22
	v_mul_f32_e32 v46, v46, v79
	s_waitcnt lgkmcnt(1)
	v_mfma_f32_32x32x16_bf16 v[0:15], v[36:39], v[32:35], v[0:15]
	ds_read2_b64 v[36:39], v62 offset0:84 offset1:86
	v_mul_f32_e32 v32, v41, v74
	v_mul_f32_e32 v33, v40, v73
	v_mul_f32_e32 v35, v47, v80
	v_cvt_pk_bf16_f32 v32, v33, v32
	v_cvt_pk_bf16_f32 v33, v68, v67
	v_cvt_pk_bf16_f32 v34, v66, v65
	v_cvt_pk_bf16_f32 v35, v46, v35
	v_or_b32_e32 v65, 0x60, v58
	v_cmp_ge_u32_e32 vcc, v65, v57
	s_waitcnt lgkmcnt(1)
	v_mfma_f32_32x32x16_bf16 v[16:31], v[42:45], v[32:35], v[16:31]
	s_waitcnt lgkmcnt(0)
	v_mfma_f32_32x32x16_bf16 v[0:15], v[36:39], v[32:35], v[0:15]
	ds_read_b128 v[32:35], v64 offset:31232
	ds_read_b128 v[66:69], v64 offset:31264
	s_waitcnt lgkmcnt(1)
	v_mfma_f32_32x32x16_bf16 v[32:47], v[32:35], v[48:51], 0
	s_waitcnt lgkmcnt(0)
	v_mfma_f32_32x32x16_bf16 v[32:47], v[66:69], v[102:105], v[32:47]
	ds_read_b128 v[66:69], v64 offset:31296
	ds_read_b128 v[70:73], v64 offset:31328
	s_waitcnt lgkmcnt(1)
	v_mfma_f32_32x32x16_bf16 v[32:47], v[66:69], v[98:101], v[32:47]
	s_waitcnt lgkmcnt(0)
	v_mfma_f32_32x32x16_bf16 v[32:47], v[70:73], v[94:97], v[32:47]
	v_lshl_add_u32 v236, v58, 2, s23
	v_lshrrev_b32_e32 v239, 5, v57
	s_nop 0
	v_readfirstlane_b32 s4, v239
	s_cmp_gt_u32 s4, 3
	s_cbranch_scc1 .Lssdb7_lt
	s_cmp_lt_u32 s4, 3
	s_cbranch_scc1 .Lssdb7_gt
	v_sub_u32_e32 v237, v57, v58
	ds_read_b128 v[170:173], v236 offset:36224
	ds_read_b128 v[174:177], v236 offset:36736
	ds_read_b128 v[178:181], v236 offset:37248
	ds_read_b128 v[182:185], v236 offset:37760
	ds_read_b128 v[186:189], v236 offset:36256
	ds_read_b128 v[190:193], v236 offset:36768
	ds_read_b128 v[194:197], v236 offset:37280
	ds_read_b128 v[198:201], v236 offset:37792
	ds_read_b128 v[202:205], v236 offset:36288
	ds_read_b128 v[206:209], v236 offset:36800
	ds_read_b128 v[210:213], v236 offset:37312
	ds_read_b128 v[214:217], v236 offset:37824
	s_waitcnt lgkmcnt(8)
	ds_read_b128 v[218:221], v236 offset:36320
	ds_read_b128 v[222:225], v236 offset:36832
	ds_read_b128 v[226:229], v236 offset:37344
	ds_read_b128 v[230:233], v236 offset:37856
	v_add_u32_e32 v238, 0xffffffa0, v237
	v_cmp_lt_i32_e32 vcc, 0, v238
	v_cmp_lt_i32_e64 s[4:5], 1, v238
	v_cmp_lt_i32_e64 s[6:7], 2, v238
	v_cmp_lt_i32_e64 s[30:31], 3, v238
	v_sub_f32_e32 v170, v54, v170
	v_sub_f32_e32 v171, v54, v171
	v_sub_f32_e32 v172, v54, v172
	v_sub_f32_e32 v173, v54, v173
	v_sub_f32_e32 v174, v55, v174
	v_sub_f32_e32 v175, v55, v175
	v_sub_f32_e32 v176, v55, v176
	v_sub_f32_e32 v177, v55, v177
	v_cndmask_b32_e64 v170, v174, v170, vcc
	v_cndmask_b32_e64 v171, v175, v171, s[4:5]
	v_cndmask_b32_e64 v172, v176, v172, s[6:7]
	v_cndmask_b32_e64 v173, v177, v173, s[30:31]
	v_add_f32_e32 v174, v178, v182
	v_add_f32_e32 v175, v179, v183
	v_add_f32_e32 v176, v180, v184
	v_add_f32_e32 v177, v181, v185
	v_cndmask_b32_e64 v178, v182, v178, vcc
	v_cndmask_b32_e64 v179, v183, v179, s[4:5]
	v_cndmask_b32_e64 v180, v184, v180, s[6:7]
	v_cndmask_b32_e64 v181, v185, v181, s[30:31]
	v_cmp_eq_u32_e32 vcc, 0, v238
	v_cmp_eq_u32_e64 s[4:5], 1, v238
	v_cmp_eq_u32_e64 s[6:7], 2, v238
	v_cmp_eq_u32_e64 s[30:31], 3, v238
	v_mul_f32_e32 v170, 0x3fb8aa3b, v170
	v_mul_f32_e32 v171, 0x3fb8aa3b, v171
	v_mul_f32_e32 v172, 0x3fb8aa3b, v172
	v_mul_f32_e32 v173, 0x3fb8aa3b, v173
	v_exp_f32_e32 v170, v170
	v_exp_f32_e32 v171, v171
	v_exp_f32_e32 v172, v172
	v_exp_f32_e32 v173, v173
	v_mul_f32_e32 v178, v178, v170
	v_mul_f32_e32 v179, v179, v171
	v_mul_f32_e32 v180, v180, v172
	v_mul_f32_e32 v181, v181, v173
	v_cndmask_b32_e64 v64, v178, v174, vcc
	v_cndmask_b32_e64 v65, v179, v175, s[4:5]
	v_cndmask_b32_e64 v66, v180, v176, s[6:7]
	v_cndmask_b32_e64 v67, v181, v177, s[30:31]
	s_waitcnt lgkmcnt(8)
	v_add_u32_e32 v238, 0xffffff98, v237
	v_cmp_lt_i32_e32 vcc, 0, v238
	v_cmp_lt_i32_e64 s[4:5], 1, v238
	v_cmp_lt_i32_e64 s[6:7], 2, v238
	v_cmp_lt_i32_e64 s[30:31], 3, v238
	v_sub_f32_e32 v186, v54, v186
	v_sub_f32_e32 v187, v54, v187
	v_sub_f32_e32 v188, v54, v188
	v_sub_f32_e32 v189, v54, v189
	v_sub_f32_e32 v190, v55, v190
	v_sub_f32_e32 v191, v55, v191
	v_sub_f32_e32 v192, v55, v192
	v_sub_f32_e32 v193, v55, v193
	v_cndmask_b32_e64 v186, v190, v186, vcc
	v_cndmask_b32_e64 v187, v191, v187, s[4:5]
	v_cndmask_b32_e64 v188, v192, v188, s[6:7]
	v_cndmask_b32_e64 v189, v193, v189, s[30:31]
	v_add_f32_e32 v190, v194, v198
	v_add_f32_e32 v191, v195, v199
	v_add_f32_e32 v192, v196, v200
	v_add_f32_e32 v193, v197, v201
	v_cndmask_b32_e64 v194, v198, v194, vcc
	v_cndmask_b32_e64 v195, v199, v195, s[4:5]
	v_cndmask_b32_e64 v196, v200, v196, s[6:7]
	v_cndmask_b32_e64 v197, v201, v197, s[30:31]
	v_cmp_eq_u32_e32 vcc, 0, v238
	v_cmp_eq_u32_e64 s[4:5], 1, v238
	v_cmp_eq_u32_e64 s[6:7], 2, v238
	v_cmp_eq_u32_e64 s[30:31], 3, v238
	v_mul_f32_e32 v186, 0x3fb8aa3b, v186
	v_mul_f32_e32 v187, 0x3fb8aa3b, v187
	v_mul_f32_e32 v188, 0x3fb8aa3b, v188
	v_mul_f32_e32 v189, 0x3fb8aa3b, v189
	v_exp_f32_e32 v186, v186
	v_exp_f32_e32 v187, v187
	v_exp_f32_e32 v188, v188
	v_exp_f32_e32 v189, v189
	v_mul_f32_e32 v194, v194, v186
	v_mul_f32_e32 v195, v195, v187
	v_mul_f32_e32 v196, v196, v188
	v_mul_f32_e32 v197, v197, v189
	v_cndmask_b32_e64 v63, v194, v190, vcc
	v_cndmask_b32_e64 v68, v195, v191, s[4:5]
	v_cndmask_b32_e64 v69, v196, v192, s[6:7]
	v_cndmask_b32_e64 v70, v197, v193, s[30:31]
	s_waitcnt lgkmcnt(4)
	v_add_u32_e32 v238, 0xffffff90, v237
	v_cmp_lt_i32_e32 vcc, 0, v238
	v_cmp_lt_i32_e64 s[4:5], 1, v238
	v_cmp_lt_i32_e64 s[6:7], 2, v238
	v_cmp_lt_i32_e64 s[30:31], 3, v238
	v_sub_f32_e32 v202, v54, v202
	v_sub_f32_e32 v203, v54, v203
	v_sub_f32_e32 v204, v54, v204
	v_sub_f32_e32 v205, v54, v205
	v_sub_f32_e32 v206, v55, v206
	v_sub_f32_e32 v207, v55, v207
	v_sub_f32_e32 v208, v55, v208
	v_sub_f32_e32 v209, v55, v209
	v_cndmask_b32_e64 v202, v206, v202, vcc
	v_cndmask_b32_e64 v203, v207, v203, s[4:5]
	v_cndmask_b32_e64 v204, v208, v204, s[6:7]
	v_cndmask_b32_e64 v205, v209, v205, s[30:31]
	v_add_f32_e32 v206, v210, v214
	v_add_f32_e32 v207, v211, v215
	v_add_f32_e32 v208, v212, v216
	v_add_f32_e32 v209, v213, v217
	v_cndmask_b32_e64 v210, v214, v210, vcc
	v_cndmask_b32_e64 v211, v215, v211, s[4:5]
	v_cndmask_b32_e64 v212, v216, v212, s[6:7]
	v_cndmask_b32_e64 v213, v217, v213, s[30:31]
	v_cmp_eq_u32_e32 vcc, 0, v238
	v_cmp_eq_u32_e64 s[4:5], 1, v238
	v_cmp_eq_u32_e64 s[6:7], 2, v238
	v_cmp_eq_u32_e64 s[30:31], 3, v238
	v_mul_f32_e32 v202, 0x3fb8aa3b, v202
	v_mul_f32_e32 v203, 0x3fb8aa3b, v203
	v_mul_f32_e32 v204, 0x3fb8aa3b, v204
	v_mul_f32_e32 v205, 0x3fb8aa3b, v205
	v_exp_f32_e32 v202, v202
	v_exp_f32_e32 v203, v203
	v_exp_f32_e32 v204, v204
	v_exp_f32_e32 v205, v205
	v_mul_f32_e32 v210, v210, v202
	v_mul_f32_e32 v211, v211, v203
	v_mul_f32_e32 v212, v212, v204
	v_mul_f32_e32 v213, v213, v205
	v_cndmask_b32_e64 v71, v210, v206, vcc
	v_cndmask_b32_e64 v72, v211, v207, s[4:5]
	v_cndmask_b32_e64 v73, v212, v208, s[6:7]
	v_cndmask_b32_e64 v74, v213, v209, s[30:31]
	s_waitcnt lgkmcnt(0)
	v_add_u32_e32 v238, 0xffffff88, v237
	v_cmp_lt_i32_e32 vcc, 0, v238
	v_cmp_lt_i32_e64 s[4:5], 1, v238
	v_cmp_lt_i32_e64 s[6:7], 2, v238
	v_cmp_lt_i32_e64 s[30:31], 3, v238
	v_sub_f32_e32 v218, v54, v218
	v_sub_f32_e32 v219, v54, v219
	v_sub_f32_e32 v220, v54, v220
	v_sub_f32_e32 v221, v54, v221
	v_sub_f32_e32 v222, v55, v222
	v_sub_f32_e32 v223, v55, v223
	v_sub_f32_e32 v224, v55, v224
	v_sub_f32_e32 v225, v55, v225
	v_cndmask_b32_e64 v218, v222, v218, vcc
	v_cndmask_b32_e64 v219, v223, v219, s[4:5]
	v_cndmask_b32_e64 v220, v224, v220, s[6:7]
	v_cndmask_b32_e64 v221, v225, v221, s[30:31]
	v_add_f32_e32 v222, v226, v230
	v_add_f32_e32 v223, v227, v231
	v_add_f32_e32 v224, v228, v232
	v_add_f32_e32 v225, v229, v233
	v_cndmask_b32_e64 v226, v230, v226, vcc
	v_cndmask_b32_e64 v227, v231, v227, s[4:5]
	v_cndmask_b32_e64 v228, v232, v228, s[6:7]
	v_cndmask_b32_e64 v229, v233, v229, s[30:31]
	v_cmp_eq_u32_e32 vcc, 0, v238
	v_cmp_eq_u32_e64 s[4:5], 1, v238
	v_cmp_eq_u32_e64 s[6:7], 2, v238
	v_cmp_eq_u32_e64 s[30:31], 3, v238
	v_mul_f32_e32 v218, 0x3fb8aa3b, v218
	v_mul_f32_e32 v219, 0x3fb8aa3b, v219
	v_mul_f32_e32 v220, 0x3fb8aa3b, v220
	v_mul_f32_e32 v221, 0x3fb8aa3b, v221
	v_exp_f32_e32 v218, v218
	v_exp_f32_e32 v219, v219
	v_exp_f32_e32 v220, v220
	v_exp_f32_e32 v221, v221
	v_mul_f32_e32 v226, v226, v218
	v_mul_f32_e32 v227, v227, v219
	v_mul_f32_e32 v228, v228, v220
	v_mul_f32_e32 v229, v229, v221
	v_cndmask_b32_e64 v75, v226, v222, vcc
	v_cndmask_b32_e64 v76, v227, v223, s[4:5]
	v_cndmask_b32_e64 v77, v228, v224, s[6:7]
	v_cndmask_b32_e64 v78, v229, v225, s[30:31]
	s_branch .Lssdb7_done
.Lssdb7_lt:
	ds_read_b128 v[170:173], v236 offset:36224
	ds_read_b128 v[178:181], v236 offset:37248
	ds_read_b128 v[186:189], v236 offset:36256
	ds_read_b128 v[194:197], v236 offset:37280
	ds_read_b128 v[202:205], v236 offset:36288
	ds_read_b128 v[210:213], v236 offset:37312
	ds_read_b128 v[218:221], v236 offset:36320
	ds_read_b128 v[226:229], v236 offset:37344
	s_waitcnt lgkmcnt(6)
	v_sub_f32_e32 v170, v54, v170
	v_sub_f32_e32 v171, v54, v171
	v_sub_f32_e32 v172, v54, v172
	v_sub_f32_e32 v173, v54, v173
	v_mul_f32_e32 v170, 0x3fb8aa3b, v170
	v_mul_f32_e32 v171, 0x3fb8aa3b, v171
	v_mul_f32_e32 v172, 0x3fb8aa3b, v172
	v_mul_f32_e32 v173, 0x3fb8aa3b, v173
	v_exp_f32_e32 v170, v170
	v_exp_f32_e32 v171, v171
	v_exp_f32_e32 v172, v172
	v_exp_f32_e32 v173, v173
	v_mul_f32_e32 v64, v178, v170
	v_mul_f32_e32 v65, v179, v171
	v_mul_f32_e32 v66, v180, v172
	v_mul_f32_e32 v67, v181, v173
	s_waitcnt lgkmcnt(4)
	v_sub_f32_e32 v186, v54, v186
	v_sub_f32_e32 v187, v54, v187
	v_sub_f32_e32 v188, v54, v188
	v_sub_f32_e32 v189, v54, v189
	v_mul_f32_e32 v186, 0x3fb8aa3b, v186
	v_mul_f32_e32 v187, 0x3fb8aa3b, v187
	v_mul_f32_e32 v188, 0x3fb8aa3b, v188
	v_mul_f32_e32 v189, 0x3fb8aa3b, v189
	v_exp_f32_e32 v186, v186
	v_exp_f32_e32 v187, v187
	v_exp_f32_e32 v188, v188
	v_exp_f32_e32 v189, v189
	v_mul_f32_e32 v63, v194, v186
	v_mul_f32_e32 v68, v195, v187
	v_mul_f32_e32 v69, v196, v188
	v_mul_f32_e32 v70, v197, v189
	s_waitcnt lgkmcnt(2)
	v_sub_f32_e32 v202, v54, v202
	v_sub_f32_e32 v203, v54, v203
	v_sub_f32_e32 v204, v54, v204
	v_sub_f32_e32 v205, v54, v205
	v_mul_f32_e32 v202, 0x3fb8aa3b, v202
	v_mul_f32_e32 v203, 0x3fb8aa3b, v203
	v_mul_f32_e32 v204, 0x3fb8aa3b, v204
	v_mul_f32_e32 v205, 0x3fb8aa3b, v205
	v_exp_f32_e32 v202, v202
	v_exp_f32_e32 v203, v203
	v_exp_f32_e32 v204, v204
	v_exp_f32_e32 v205, v205
	v_mul_f32_e32 v71, v210, v202
	v_mul_f32_e32 v72, v211, v203
	v_mul_f32_e32 v73, v212, v204
	v_mul_f32_e32 v74, v213, v205
	s_waitcnt lgkmcnt(0)
	v_sub_f32_e32 v218, v54, v218
	v_sub_f32_e32 v219, v54, v219
	v_sub_f32_e32 v220, v54, v220
	v_sub_f32_e32 v221, v54, v221
	v_mul_f32_e32 v218, 0x3fb8aa3b, v218
	v_mul_f32_e32 v219, 0x3fb8aa3b, v219
	v_mul_f32_e32 v220, 0x3fb8aa3b, v220
	v_mul_f32_e32 v221, 0x3fb8aa3b, v221
	v_exp_f32_e32 v218, v218
	v_exp_f32_e32 v219, v219
	v_exp_f32_e32 v220, v220
	v_exp_f32_e32 v221, v221
	v_mul_f32_e32 v75, v226, v218
	v_mul_f32_e32 v76, v227, v219
	v_mul_f32_e32 v77, v228, v220
	v_mul_f32_e32 v78, v229, v221
	s_branch .Lssdb7_done
.Lssdb7_gt:
	ds_read_b128 v[170:173], v236 offset:36736
	ds_read_b128 v[178:181], v236 offset:37760
	ds_read_b128 v[186:189], v236 offset:36768
	ds_read_b128 v[194:197], v236 offset:37792
	ds_read_b128 v[202:205], v236 offset:36800
	ds_read_b128 v[210:213], v236 offset:37824
	ds_read_b128 v[218:221], v236 offset:36832
	ds_read_b128 v[226:229], v236 offset:37856
	s_waitcnt lgkmcnt(6)
	v_sub_f32_e32 v170, v55, v170
	v_sub_f32_e32 v171, v55, v171
	v_sub_f32_e32 v172, v55, v172
	v_sub_f32_e32 v173, v55, v173
	v_mul_f32_e32 v170, 0x3fb8aa3b, v170
	v_mul_f32_e32 v171, 0x3fb8aa3b, v171
	v_mul_f32_e32 v172, 0x3fb8aa3b, v172
	v_mul_f32_e32 v173, 0x3fb8aa3b, v173
	v_exp_f32_e32 v170, v170
	v_exp_f32_e32 v171, v171
	v_exp_f32_e32 v172, v172
	v_exp_f32_e32 v173, v173
	v_mul_f32_e32 v64, v178, v170
	v_mul_f32_e32 v65, v179, v171
	v_mul_f32_e32 v66, v180, v172
	v_mul_f32_e32 v67, v181, v173
	s_waitcnt lgkmcnt(4)
	v_sub_f32_e32 v186, v55, v186
	v_sub_f32_e32 v187, v55, v187
	v_sub_f32_e32 v188, v55, v188
	v_sub_f32_e32 v189, v55, v189
	v_mul_f32_e32 v186, 0x3fb8aa3b, v186
	v_mul_f32_e32 v187, 0x3fb8aa3b, v187
	v_mul_f32_e32 v188, 0x3fb8aa3b, v188
	v_mul_f32_e32 v189, 0x3fb8aa3b, v189
	v_exp_f32_e32 v186, v186
	v_exp_f32_e32 v187, v187
	v_exp_f32_e32 v188, v188
	v_exp_f32_e32 v189, v189
	v_mul_f32_e32 v63, v194, v186
	v_mul_f32_e32 v68, v195, v187
	v_mul_f32_e32 v69, v196, v188
	v_mul_f32_e32 v70, v197, v189
	s_waitcnt lgkmcnt(2)
	v_sub_f32_e32 v202, v55, v202
	v_sub_f32_e32 v203, v55, v203
	v_sub_f32_e32 v204, v55, v204
	v_sub_f32_e32 v205, v55, v205
	v_mul_f32_e32 v202, 0x3fb8aa3b, v202
	v_mul_f32_e32 v203, 0x3fb8aa3b, v203
	v_mul_f32_e32 v204, 0x3fb8aa3b, v204
	v_mul_f32_e32 v205, 0x3fb8aa3b, v205
	v_exp_f32_e32 v202, v202
	v_exp_f32_e32 v203, v203
	v_exp_f32_e32 v204, v204
	v_exp_f32_e32 v205, v205
	v_mul_f32_e32 v71, v210, v202
	v_mul_f32_e32 v72, v211, v203
	v_mul_f32_e32 v73, v212, v204
	v_mul_f32_e32 v74, v213, v205
	s_waitcnt lgkmcnt(0)
	v_sub_f32_e32 v218, v55, v218
	v_sub_f32_e32 v219, v55, v219
	v_sub_f32_e32 v220, v55, v220
	v_sub_f32_e32 v221, v55, v221
	v_mul_f32_e32 v218, 0x3fb8aa3b, v218
	v_mul_f32_e32 v219, 0x3fb8aa3b, v219
	v_mul_f32_e32 v220, 0x3fb8aa3b, v220
	v_mul_f32_e32 v221, 0x3fb8aa3b, v221
	v_exp_f32_e32 v218, v218
	v_exp_f32_e32 v219, v219
	v_exp_f32_e32 v220, v220
	v_exp_f32_e32 v221, v221
	v_mul_f32_e32 v75, v226, v218
	v_mul_f32_e32 v76, v227, v219
	v_mul_f32_e32 v77, v228, v220
	v_mul_f32_e32 v78, v229, v221
.Lssdb7_done:
	s_lshl_b32 s2, s48, 6
	s_mul_i32 s4, s50, 34
	s_add_i32 s4, s4, s49
	s_ashr_i32 s5, s4, 31
	s_lshl_b64 s[4:5], s[4:5], 16
	s_lshl_b32 s6, s48, 13
	s_add_u32 s6, s34, s6
	s_addc_u32 s7, s35, 0
	v_lshlrev_b32_e32 v106, 1, v59
	v_lshl_add_u64 v[80:81], s[6:7], 0, v[106:107]
	v_lshl_add_u64 v[88:89], v[80:81], 0, s[4:5]
	v_lshlrev_b32_e32 v106, 7, v56
	v_lshl_add_u64 v[56:57], v[88:89], 0, v[106:107]
	global_load_dwordx4 v[80:83], v[56:57], off
	v_mov_b32_e32 v147, v107
	v_or_b32_e32 v146, 0x1000, v106
	v_lshl_add_u64 v[148:149], v[88:89], 0, s[24:25]
	v_lshl_add_u64 v[142:143], v[88:89], 0, v[146:147]
	v_lshl_add_u64 v[92:93], v[148:149], 0, v[106:107]
	global_load_dwordx4 v[84:87], v[142:143], off
	global_load_dwordx4 v[88:91], v[92:93], off
	global_load_dwordx4 v[114:117], v[56:57], off offset:32
	global_load_dwordx4 v[118:121], v[142:143], off offset:32
	v_mul_f32_e32 v59, v37, v68
	v_mul_f32_e32 v60, v36, v63
	v_mul_f32_e32 v63, v35, v67
	v_mul_f32_e32 v68, v34, v66
	ds_read2_b64 v[34:37], v61 offset0:24 offset1:26
	v_mul_f32_e32 v39, v39, v70
	v_mul_f32_e32 v38, v38, v69
	v_mul_f32_e32 v33, v33, v65
	v_mul_f32_e32 v32, v32, v64
	ds_read2_b64 v[64:67], v62 offset0:88 offset1:90
	global_load_dwordx4 v[122:125], v[92:93], off offset:32
	global_load_dwordx4 v[134:137], v[92:93], off offset:64
	v_cvt_pk_bf16_f32 v126, v32, v33
	v_cvt_pk_bf16_f32 v127, v68, v63
	v_cvt_pk_bf16_f32 v128, v60, v59
	global_load_dwordx4 v[130:133], v[56:57], off offset:64
	v_cvt_pk_bf16_f32 v129, v38, v39
	v_mul_f32_e32 v46, v46, v77
	v_mul_f32_e32 v45, v45, v76
	s_waitcnt lgkmcnt(1)
	v_mfma_f32_32x32x16_bf16 v[16:31], v[34:37], v[126:129], v[16:31]
	ds_read2_b64 v[32:35], v61 offset0:28 offset1:30
	v_mul_f32_e32 v44, v44, v75
	v_mul_f32_e32 v43, v43, v74
	v_mul_f32_e32 v42, v42, v73
	v_mul_f32_e32 v41, v41, v72
	v_mul_f32_e32 v40, v40, v71
	v_mul_f32_e32 v47, v47, v78
	s_waitcnt lgkmcnt(1)
	v_mfma_f32_32x32x16_bf16 v[0:15], v[64:67], v[126:129], v[0:15]
	global_load_dwordx4 v[126:129], v[142:143], off offset:64
	global_load_dwordx4 v[138:141], v[56:57], off offset:96
	v_cvt_pk_bf16_f32 v40, v40, v41
	v_cvt_pk_bf16_f32 v41, v42, v43
	v_cvt_pk_bf16_f32 v42, v44, v45
	v_cvt_pk_bf16_f32 v43, v46, v47
	s_lshl_b32 s20, s2, 1
	v_lshlrev_b32_e32 v106, 1, v58
	s_waitcnt lgkmcnt(0)
	v_mfma_f32_32x32x16_bf16 v[16:31], v[32:35], v[40:43], v[16:31]
	v_mov_b64_e32 v[32:33], s[8:9]
	v_mad_i64_i32 v[60:61], s[4:5], v108, s44, v[32:33]
	v_lshl_add_u64 v[32:33], v[60:61], 0, s[20:21]
	v_lshl_add_u64 v[162:163], v[32:33], 0, v[106:107]
	v_add_co_u32_e32 v78, vcc, s45, v162
	v_lshl_add_u64 v[52:53], v[52:53], 0, s[20:21]
	s_nop 0
	v_addc_co_u32_e32 v79, vcc, 0, v163, vcc
	v_lshl_add_u64 v[52:53], v[52:53], 0, v[106:107]
	global_load_dwordx2 v[168:169], v[78:79], off offset:2368
	global_load_dwordx2 v[170:171], v[52:53], off
	global_load_dwordx4 v[56:59], v[92:93], off offset:96
	v_lshl_add_u64 v[158:159], v[148:149], 0, v[146:147]
	global_load_dwordx4 v[142:145], v[142:143], off offset:96
	s_lshl_b32 s6, s48, 2
	global_load_dwordx4 v[146:149], v[158:159], off
	v_mov_b32_e32 v109, s6
	global_load_dword v110, v109, s[12:13] offset:32
	global_load_dwordx4 v[150:153], v[158:159], off offset:32
	global_load_dwordx4 v[154:157], v[158:159], off offset:64
	ds_read2_b64 v[36:39], v62 offset0:92 offset1:94
	global_load_dwordx4 v[158:161], v[158:159], off offset:96
	s_waitcnt lgkmcnt(0)
	v_mfma_f32_32x32x16_bf16 v[0:15], v[36:39], v[40:43], v[0:15]
	v_mul_f32_e32 v54, 0x3fb8aa3b, v54
	v_mul_f32_e32 v55, 0x3fb8aa3b, v55
	v_exp_f32_e32 v112, v54
	v_ashrrev_i32_e32 v109, 31, v108
	s_waitcnt vmcnt(8)
	v_and_b32_e32 v167, 0xffff0000, v168
	v_mfma_f32_32x32x16_bf16 v[62:77], v[80:83], v[48:51], 0
	v_mfma_f32_32x32x16_bf16 v[32:47], v[84:87], v[48:51], 0
	v_mfma_f32_32x32x16_bf16 v[78:93], v[88:91], v[48:51], 0
	v_mfma_f32_32x32x16_bf16 v[62:77], v[114:117], v[102:105], v[62:77]
	v_exp_f32_e32 v114, v55
	v_mad_i64_i32 v[54:55], s[4:5], v108, s46, v[60:61]
	v_lshl_add_u64 v[172:173], v[54:55], 0, s[20:21]
	v_lshl_add_u64 v[54:55], v[162:163], 0, s[26:27]
	v_lshlrev_b32_e32 v115, 16, v168
	v_mfma_f32_32x32x16_bf16 v[32:47], v[118:121], v[102:105], v[32:47]
	v_mfma_f32_32x32x16_bf16 v[78:93], v[122:125], v[102:105], v[78:93]
	v_mfma_f32_32x32x16_bf16 v[62:77], v[130:133], v[98:101], v[62:77]
	v_mfma_f32_32x32x16_bf16 v[32:47], v[126:129], v[98:101], v[32:47]
	v_mfma_f32_32x32x16_bf16 v[78:93], v[134:137], v[98:101], v[78:93]
	global_load_dwordx2 v[162:163], v[52:53], off offset:16
	global_load_dwordx2 v[136:137], v[52:53], off offset:32
	global_load_dwordx2 v[132:133], v[52:53], off offset:48
	global_load_dwordx2 v[128:129], v[52:53], off offset:64
	global_load_dwordx2 v[124:125], v[52:53], off offset:80
	global_load_dwordx2 v[120:121], v[52:53], off offset:96
	global_load_dwordx2 v[116:117], v[52:53], off offset:112
	v_mul_f32_e32 v52, 0xbfb8aa3b, v115
	v_mul_f32_e32 v53, 0xbfb8aa3b, v167
	v_exp_f32_e32 v52, v52
	v_exp_f32_e32 v53, v53
	v_mfma_f32_32x32x16_bf16 v[62:77], v[138:141], v[94:97], v[62:77]
	global_load_dwordx2 v[140:141], v[54:55], off offset:16
	global_load_dwordx2 v[138:139], v[54:55], off offset:32
	global_load_dwordx2 v[134:135], v[54:55], off offset:48
	global_load_dwordx2 v[130:131], v[54:55], off offset:64
	global_load_dwordx2 v[126:127], v[54:55], off offset:80
	global_load_dwordx2 v[122:123], v[54:55], off offset:96
	global_load_dwordx2 v[118:119], v[54:55], off offset:112
	s_waitcnt vmcnt(21)
	v_lshlrev_b32_e32 v54, 16, v170
	v_and_b32_e32 v55, 0xffff0000, v170
	s_nop 1
	v_pk_fma_f32 v[16:17], v[112:113], v[62:63], v[16:17] op_sel_hi:[0,1,1]
	s_waitcnt vmcnt(20)
	v_mfma_f32_32x32x16_bf16 v[78:93], v[56:59], v[94:97], v[78:93]
	v_fma_f32 v18, v112, v64, v18
	v_fma_f32 v19, v112, v65, v19
	s_waitcnt vmcnt(19)
	v_mfma_f32_32x32x16_bf16 v[32:47], v[142:145], v[94:97], v[32:47]
	s_nop 7
	v_fma_f32 v16, v114, v78, v16
	v_fma_f32 v17, v114, v79, v17
	v_add_f32_e64 v78, v52, 1.0
	v_add_f32_e64 v79, v53, 1.0
	s_waitcnt vmcnt(17)
	v_pk_fma_f32 v[16:17], v[110:111], v[54:55], v[16:17] op_sel_hi:[0,1,1]
	v_div_scale_f32 v142, s[4:5], v79, v79, v167
	v_rcp_f32_e32 v143, v142
	v_pk_fma_f32 v[18:19], v[114:115], v[80:81], v[18:19] op_sel_hi:[0,1,1]
	v_mfma_f32_32x32x16_bf16 v[48:63], v[146:149], v[48:51], 0
	v_fma_f32 v0, v112, v32, v0
	v_fma_f32 v1, v112, v33, v1
	v_fma_f32 v144, -v142, v143, 1.0
	v_fmac_f32_e32 v143, v144, v143
	v_div_scale_f32 v144, vcc, v167, v79, v167
	v_mul_f32_e32 v145, v144, v143
	v_fma_f32 v146, -v142, v145, v144
	s_waitcnt vmcnt(16)
	v_mfma_f32_32x32x16_bf16 v[48:63], v[150:153], v[102:105], v[48:63]
	v_div_scale_f32 v103, s[4:5], v78, v78, v115
	v_rcp_f32_e32 v104, v103
	v_fmac_f32_e32 v145, v146, v143
	v_fma_f32 v102, -v142, v145, v144
	v_div_fmas_f32 v102, v102, v143, v145
	v_div_fixup_f32 v79, v102, v79, v167
	s_waitcnt vmcnt(15)
	v_mfma_f32_32x32x16_bf16 v[48:63], v[154:157], v[98:101], v[48:63]
	v_fma_f32 v98, -v103, v104, 1.0
	v_fmac_f32_e32 v104, v98, v104
	v_div_scale_f32 v98, vcc, v115, v78, v115
	v_mul_f32_e32 v99, v98, v104
	v_fma_f32 v100, -v103, v99, v98
	v_fmac_f32_e32 v99, v100, v104
	s_waitcnt vmcnt(14)
	v_mfma_f32_32x32x16_bf16 v[48:63], v[158:161], v[94:97], v[48:63]
	v_fma_f32 v94, -v103, v99, v98
	v_div_fmas_f32 v94, v94, v104, v99
	v_lshlrev_b32_e32 v96, 16, v169
	v_and_b32_e32 v97, 0xffff0000, v169
	v_div_fixup_f32 v78, v94, v78, v115
	v_mul_f32_e32 v94, 0xbfb8aa3b, v96
	v_mul_f32_e32 v95, 0xbfb8aa3b, v97
	v_exp_f32_e32 v94, v94
	v_exp_f32_e32 v95, v95
	v_pk_mul_f32 v[16:17], v[16:17], v[78:79]
	v_lshlrev_b32_e32 v78, 16, v171
	v_and_b32_e32 v79, 0xffff0000, v171
	v_pk_add_f32 v[64:65], v[94:95], 1.0 op_sel_hi:[1,0]
	v_pk_fma_f32 v[18:19], v[110:111], v[78:79], v[18:19] op_sel_hi:[0,1,1]
	v_div_scale_f32 v80, s[4:5], v65, v65, v97
	v_rcp_f32_e32 v81, v80
	v_pk_fma_f32 v[0:1], v[114:115], v[48:49], v[0:1] op_sel_hi:[0,1,1]
	v_pk_fma_f32 v[2:3], v[112:113], v[34:35], v[2:3] op_sel_hi:[0,1,1]
	v_pk_fma_f32 v[2:3], v[114:115], v[50:51], v[2:3] op_sel_hi:[0,1,1]
	v_fma_f32 v78, -v80, v81, 1.0
	v_fmac_f32_e32 v81, v78, v81
	v_div_scale_f32 v78, vcc, v97, v65, v97
	v_mul_f32_e32 v79, v78, v81
	v_fma_f32 v94, -v80, v79, v78
	v_fmac_f32_e32 v79, v94, v81
	v_fma_f32 v78, -v80, v79, v78
	v_div_scale_f32 v80, s[4:5], v64, v64, v96
	v_rcp_f32_e32 v94, v80
	v_div_fmas_f32 v78, v78, v81, v79
	v_div_fixup_f32 v65, v78, v65, v97
	v_fma_f32 v78, -v80, v94, 1.0
	v_fmac_f32_e32 v94, v78, v94
	v_div_scale_f32 v78, vcc, v96, v64, v96
	v_mul_f32_e32 v79, v78, v94
	v_fma_f32 v81, -v80, v79, v78
	v_fmac_f32_e32 v79, v81, v94
	v_fma_f32 v78, -v80, v79, v78
	v_div_fmas_f32 v78, v78, v94, v79
	v_div_fixup_f32 v64, v78, v64, v96
	v_pk_mul_f32 v[18:19], v[18:19], v[64:65]
	v_cvt_pk_bf16_f32 v64, v16, v17
	v_and_b32_e32 v17, 0xffff0000, v64
	v_cvt_pk_bf16_f32 v65, v18, v19
	v_lshlrev_b32_e32 v16, 16, v64
	v_mul_f32_e32 v80, v17, v17
	s_waitcnt vmcnt(6)
	v_lshlrev_b32_e32 v81, 16, v140
	v_and_b32_e32 v94, 0xffff0000, v140
	v_lshlrev_b32_e32 v18, 16, v65
	v_fmac_f32_e32 v80, v16, v16
	v_mul_f32_e32 v78, 0xbfb8aa3b, v81
	v_mul_f32_e32 v79, 0xbfb8aa3b, v94
	v_and_b32_e32 v19, 0xffff0000, v65
	v_fmac_f32_e32 v80, v18, v18
	v_exp_f32_e32 v78, v78
	v_exp_f32_e32 v79, v79
	v_fmac_f32_e32 v80, v19, v19
	v_lshl_add_u64 v[18:19], v[172:173], 0, v[106:107]
	v_lshl_add_u64 v[16:17], v[18:19], 0, s[28:29]
	v_add_co_u32_e32 v18, vcc, s47, v18
	s_nop 1
	v_addc_co_u32_e32 v19, vcc, 0, v19, vcc
	global_store_dwordx2 v[18:19], v[64:65], off offset:1024
	v_pk_fma_f32 v[18:19], v[112:113], v[66:67], v[20:21] op_sel_hi:[0,1,1]
	v_pk_add_f32 v[20:21], v[78:79], 1.0 op_sel_hi:[1,0]
	v_pk_fma_f32 v[18:19], v[114:115], v[82:83], v[18:19] op_sel_hi:[0,1,1]
	v_div_scale_f32 v66, s[4:5], v21, v21, v94
	v_rcp_f32_e32 v67, v66
	v_lshlrev_b32_e32 v64, 16, v162
	v_and_b32_e32 v65, 0xffff0000, v162
	v_pk_fma_f32 v[18:19], v[110:111], v[64:65], v[18:19] op_sel_hi:[0,1,1]
	v_fma_f32 v64, -v66, v67, 1.0
	v_fmac_f32_e32 v67, v64, v67
	v_div_scale_f32 v64, vcc, v94, v21, v94
	v_mul_f32_e32 v65, v64, v67
	v_fma_f32 v78, -v66, v65, v64
	v_fmac_f32_e32 v65, v78, v67
	v_fma_f32 v64, -v66, v65, v64
	v_div_scale_f32 v66, s[4:5], v20, v20, v81
	v_rcp_f32_e32 v78, v66
	v_div_fmas_f32 v64, v64, v67, v65
	v_div_fixup_f32 v21, v64, v21, v94
	v_fma_f32 v64, -v66, v78, 1.0
	v_fmac_f32_e32 v78, v64, v78
	v_div_scale_f32 v64, vcc, v81, v20, v81
	v_mul_f32_e32 v65, v64, v78
	v_fma_f32 v67, -v66, v65, v64
	v_fmac_f32_e32 v65, v67, v78
	v_fma_f32 v64, -v66, v65, v64
	v_div_fmas_f32 v64, v64, v78, v65
	v_lshlrev_b32_e32 v66, 16, v141
	v_and_b32_e32 v67, 0xffff0000, v141
	v_div_fixup_f32 v20, v64, v20, v81
	v_mul_f32_e32 v64, 0xbfb8aa3b, v66
	v_mul_f32_e32 v65, 0xbfb8aa3b, v67
	v_exp_f32_e32 v64, v64
	v_exp_f32_e32 v65, v65
	v_pk_mul_f32 v[18:19], v[18:19], v[20:21]
	v_pk_fma_f32 v[20:21], v[112:113], v[68:69], v[22:23] op_sel_hi:[0,1,1]
	v_pk_fma_f32 v[20:21], v[114:115], v[84:85], v[20:21] op_sel_hi:[0,1,1]
	v_pk_add_f32 v[22:23], v[64:65], 1.0 op_sel_hi:[1,0]
	v_lshlrev_b32_e32 v64, 16, v163
	v_div_scale_f32 v68, s[4:5], v23, v23, v67
	v_rcp_f32_e32 v69, v68
	v_and_b32_e32 v65, 0xffff0000, v163
	v_pk_fma_f32 v[20:21], v[110:111], v[64:65], v[20:21] op_sel_hi:[0,1,1]
	v_cvt_pk_bf16_f32 v18, v18, v19
	v_fma_f32 v64, -v68, v69, 1.0
	v_fmac_f32_e32 v69, v64, v69
	v_div_scale_f32 v64, vcc, v67, v23, v67
	v_mul_f32_e32 v65, v64, v69
	v_fma_f32 v78, -v68, v65, v64
	v_fmac_f32_e32 v65, v78, v69
	v_fma_f32 v64, -v68, v65, v64
	v_div_scale_f32 v68, s[4:5], v22, v22, v66
	v_rcp_f32_e32 v78, v68
	v_div_fmas_f32 v64, v64, v69, v65
	v_div_fixup_f32 v23, v64, v23, v67
	v_fma_f32 v64, -v68, v78, 1.0
	v_fmac_f32_e32 v78, v64, v78
	v_div_scale_f32 v64, vcc, v66, v22, v66
	v_mul_f32_e32 v65, v64, v78
	v_fma_f32 v67, -v68, v65, v64
	v_fmac_f32_e32 v65, v67, v78
	v_fma_f32 v64, -v68, v65, v64
	v_div_fmas_f32 v64, v64, v78, v65
	v_div_fixup_f32 v22, v64, v22, v66
	v_pk_mul_f32 v[20:21], v[20:21], v[22:23]
	s_waitcnt vmcnt(6)
	v_lshlrev_b32_e32 v65, 16, v138
	v_cvt_pk_bf16_f32 v19, v20, v21
	v_and_b32_e32 v21, 0xffff0000, v18
	v_lshlrev_b32_e32 v20, 16, v18
	v_mul_f32_e32 v21, v21, v21
	v_lshlrev_b32_e32 v22, 16, v19
	v_fmac_f32_e32 v21, v20, v20
	v_and_b32_e32 v23, 0xffff0000, v19
	v_fmac_f32_e32 v21, v22, v22
	v_fmac_f32_e32 v21, v23, v23
	v_and_b32_e32 v66, 0xffff0000, v138
	v_add_f32_e32 v64, v80, v21
	v_mul_f32_e32 v20, 0xbfb8aa3b, v65
	v_mul_f32_e32 v21, 0xbfb8aa3b, v66
	v_exp_f32_e32 v20, v20
	v_exp_f32_e32 v21, v21
	global_store_dwordx2 v[16:17], v[18:19], off offset:16
	v_pk_fma_f32 v[18:19], v[112:113], v[70:71], v[24:25] op_sel_hi:[0,1,1]
	v_pk_fma_f32 v[18:19], v[114:115], v[86:87], v[18:19] op_sel_hi:[0,1,1]
	v_pk_add_f32 v[20:21], v[20:21], 1.0 op_sel_hi:[1,0]
	v_lshlrev_b32_e32 v22, 16, v136
	v_div_scale_f32 v24, s[4:5], v21, v21, v66
	v_rcp_f32_e32 v25, v24
	v_and_b32_e32 v23, 0xffff0000, v136
	v_pk_fma_f32 v[18:19], v[110:111], v[22:23], v[18:19] op_sel_hi:[0,1,1]
	v_fma_f32 v22, -v24, v25, 1.0
	v_fmac_f32_e32 v25, v22, v25
	v_div_scale_f32 v22, vcc, v66, v21, v66
	v_mul_f32_e32 v23, v22, v25
	v_fma_f32 v67, -v24, v23, v22
	v_fmac_f32_e32 v23, v67, v25
	v_fma_f32 v22, -v24, v23, v22
	v_div_scale_f32 v24, s[4:5], v20, v20, v65
	v_rcp_f32_e32 v67, v24
	v_div_fmas_f32 v22, v22, v25, v23
	v_div_fixup_f32 v21, v22, v21, v66
	v_and_b32_e32 v66, 0xffff0000, v139
	v_fma_f32 v22, -v24, v67, 1.0
	v_fmac_f32_e32 v67, v22, v67
	v_div_scale_f32 v22, vcc, v65, v20, v65
	v_mul_f32_e32 v23, v22, v67
	v_fma_f32 v25, -v24, v23, v22
	v_fmac_f32_e32 v23, v25, v67
	v_fma_f32 v22, -v24, v23, v22
	v_div_fmas_f32 v22, v22, v67, v23
	v_div_fixup_f32 v20, v22, v20, v65
	v_lshlrev_b32_e32 v65, 16, v139
	v_mul_f32_e32 v22, 0xbfb8aa3b, v65
	v_mul_f32_e32 v23, 0xbfb8aa3b, v66
	v_exp_f32_e32 v22, v22
	v_exp_f32_e32 v23, v23
	v_pk_mul_f32 v[18:19], v[18:19], v[20:21]
	v_pk_fma_f32 v[20:21], v[112:113], v[72:73], v[26:27] op_sel_hi:[0,1,1]
	v_pk_fma_f32 v[20:21], v[114:115], v[88:89], v[20:21] op_sel_hi:[0,1,1]
	v_pk_add_f32 v[22:23], v[22:23], 1.0 op_sel_hi:[1,0]
	v_lshlrev_b32_e32 v24, 16, v137
	v_div_scale_f32 v26, s[4:5], v23, v23, v66
	v_rcp_f32_e32 v27, v26
	v_and_b32_e32 v25, 0xffff0000, v137
	v_pk_fma_f32 v[20:21], v[110:111], v[24:25], v[20:21] op_sel_hi:[0,1,1]
	v_cvt_pk_bf16_f32 v18, v18, v19
	v_fma_f32 v24, -v26, v27, 1.0
	v_fmac_f32_e32 v27, v24, v27
	v_div_scale_f32 v24, vcc, v66, v23, v66
	v_mul_f32_e32 v25, v24, v27
	v_fma_f32 v67, -v26, v25, v24
	v_fmac_f32_e32 v25, v67, v27
	v_fma_f32 v24, -v26, v25, v24
	v_div_scale_f32 v26, s[4:5], v22, v22, v65
	v_rcp_f32_e32 v67, v26
	v_div_fmas_f32 v24, v24, v27, v25
	v_div_fixup_f32 v23, v24, v23, v66
	v_fma_f32 v24, -v26, v67, 1.0
	v_fmac_f32_e32 v67, v24, v67
	v_div_scale_f32 v24, vcc, v65, v22, v65
	v_mul_f32_e32 v25, v24, v67
	v_fma_f32 v27, -v26, v25, v24
	v_fmac_f32_e32 v25, v27, v67
	v_fma_f32 v24, -v26, v25, v24
	v_div_fmas_f32 v24, v24, v67, v25
	v_div_fixup_f32 v22, v24, v22, v65
	v_pk_mul_f32 v[20:21], v[20:21], v[22:23]
	s_waitcnt vmcnt(6)
	v_lshlrev_b32_e32 v24, 16, v134
	v_cvt_pk_bf16_f32 v19, v20, v21
	v_and_b32_e32 v21, 0xffff0000, v18
	v_lshlrev_b32_e32 v20, 16, v18
	v_mul_f32_e32 v21, v21, v21
	v_lshlrev_b32_e32 v22, 16, v19
	v_fmac_f32_e32 v21, v20, v20
	v_and_b32_e32 v23, 0xffff0000, v19
	v_fmac_f32_e32 v21, v22, v22
	v_fmac_f32_e32 v21, v23, v23
	v_and_b32_e32 v25, 0xffff0000, v134
	v_add_f32_e32 v26, v64, v21
	v_mul_f32_e32 v20, 0xbfb8aa3b, v24
	v_mul_f32_e32 v21, 0xbfb8aa3b, v25
	v_exp_f32_e32 v20, v20
	v_exp_f32_e32 v21, v21
	global_store_dwordx2 v[16:17], v[18:19], off offset:32
	v_pk_fma_f32 v[18:19], v[112:113], v[74:75], v[28:29] op_sel_hi:[0,1,1]
	v_pk_fma_f32 v[18:19], v[114:115], v[90:91], v[18:19] op_sel_hi:[0,1,1]
	v_pk_add_f32 v[20:21], v[20:21], 1.0 op_sel_hi:[1,0]
	v_lshlrev_b32_e32 v22, 16, v132
	v_div_scale_f32 v27, s[4:5], v21, v21, v25
	v_rcp_f32_e32 v28, v27
	v_and_b32_e32 v23, 0xffff0000, v132
	v_pk_fma_f32 v[18:19], v[110:111], v[22:23], v[18:19] op_sel_hi:[0,1,1]
	v_fma_f32 v22, -v27, v28, 1.0
	v_fmac_f32_e32 v28, v22, v28
	v_div_scale_f32 v22, vcc, v25, v21, v25
	v_mul_f32_e32 v23, v22, v28
	v_fma_f32 v29, -v27, v23, v22
	v_fmac_f32_e32 v23, v29, v28
	v_fma_f32 v22, -v27, v23, v22
	v_div_scale_f32 v27, s[4:5], v20, v20, v24
	v_rcp_f32_e32 v29, v27
	v_div_fmas_f32 v22, v22, v28, v23
	v_div_fixup_f32 v21, v22, v21, v25
	v_and_b32_e32 v28, 0xffff0000, v135
	v_fma_f32 v22, -v27, v29, 1.0
	v_fmac_f32_e32 v29, v22, v29
	v_div_scale_f32 v22, vcc, v24, v20, v24
	v_mul_f32_e32 v23, v22, v29
	v_fma_f32 v25, -v27, v23, v22
	v_fmac_f32_e32 v23, v25, v29
	v_fma_f32 v22, -v27, v23, v22
	v_div_fmas_f32 v22, v22, v29, v23
	v_lshlrev_b32_e32 v27, 16, v135
	v_div_fixup_f32 v20, v22, v20, v24
	v_mul_f32_e32 v22, 0xbfb8aa3b, v27
	v_mul_f32_e32 v23, 0xbfb8aa3b, v28
	v_exp_f32_e32 v22, v22
	v_exp_f32_e32 v23, v23
	v_pk_mul_f32 v[18:19], v[18:19], v[20:21]
	v_pk_fma_f32 v[20:21], v[112:113], v[76:77], v[30:31] op_sel_hi:[0,1,1]
	v_pk_fma_f32 v[20:21], v[114:115], v[92:93], v[20:21] op_sel_hi:[0,1,1]
	v_pk_add_f32 v[22:23], v[22:23], 1.0 op_sel_hi:[1,0]
	v_lshlrev_b32_e32 v24, 16, v133
	v_div_scale_f32 v29, s[4:5], v23, v23, v28
	v_rcp_f32_e32 v30, v29
	v_and_b32_e32 v25, 0xffff0000, v133
	v_pk_fma_f32 v[20:21], v[110:111], v[24:25], v[20:21] op_sel_hi:[0,1,1]
	v_cvt_pk_bf16_f32 v18, v18, v19
	v_fma_f32 v24, -v29, v30, 1.0
	v_fmac_f32_e32 v30, v24, v30
	v_div_scale_f32 v24, vcc, v28, v23, v28
	v_mul_f32_e32 v25, v24, v30
	v_fma_f32 v31, -v29, v25, v24
	v_fmac_f32_e32 v25, v31, v30
	v_fma_f32 v24, -v29, v25, v24
	v_div_scale_f32 v29, s[4:5], v22, v22, v27
	v_rcp_f32_e32 v31, v29
	v_div_fmas_f32 v24, v24, v30, v25
	v_div_fixup_f32 v23, v24, v23, v28
	v_fma_f32 v24, -v29, v31, 1.0
	v_fmac_f32_e32 v31, v24, v31
	v_div_scale_f32 v24, vcc, v27, v22, v27
	v_mul_f32_e32 v25, v24, v31
	v_fma_f32 v28, -v29, v25, v24
	v_fmac_f32_e32 v25, v28, v31
	v_fma_f32 v24, -v29, v25, v24
	v_div_fmas_f32 v24, v24, v31, v25
	v_div_fixup_f32 v22, v24, v22, v27
	v_pk_mul_f32 v[20:21], v[20:21], v[22:23]
	s_waitcnt vmcnt(6)
	v_and_b32_e32 v24, 0xffff0000, v130
	v_cvt_pk_bf16_f32 v19, v20, v21
	v_and_b32_e32 v21, 0xffff0000, v18
	v_lshlrev_b32_e32 v20, 16, v18
	v_mul_f32_e32 v21, v21, v21
	v_lshlrev_b32_e32 v22, 16, v19
	v_fmac_f32_e32 v21, v20, v20
	v_and_b32_e32 v23, 0xffff0000, v19
	v_fmac_f32_e32 v21, v22, v22
	v_fmac_f32_e32 v21, v23, v23
	v_lshlrev_b32_e32 v23, 16, v130
	v_add_f32_e32 v22, v26, v21
	v_mul_f32_e32 v20, 0xbfb8aa3b, v23
	v_mul_f32_e32 v21, 0xbfb8aa3b, v24
	v_exp_f32_e32 v20, v20
	v_exp_f32_e32 v21, v21
	global_store_dwordx2 v[16:17], v[18:19], off offset:48
	v_pk_add_f32 v[18:19], v[20:21], 1.0 op_sel_hi:[1,0]
	s_nop 0
	v_div_scale_f32 v25, s[4:5], v19, v19, v24
	v_rcp_f32_e32 v26, v25
	v_lshlrev_b32_e32 v20, 16, v128
	v_and_b32_e32 v21, 0xffff0000, v128
	v_pk_fma_f32 v[0:1], v[110:111], v[20:21], v[0:1] op_sel_hi:[0,1,1]
	v_fma_f32 v20, -v25, v26, 1.0
	v_fmac_f32_e32 v26, v20, v26
	v_div_scale_f32 v20, vcc, v24, v19, v24
	v_mul_f32_e32 v21, v20, v26
	v_fma_f32 v27, -v25, v21, v20
	v_fmac_f32_e32 v21, v27, v26
	v_fma_f32 v20, -v25, v21, v20
	v_div_scale_f32 v25, s[4:5], v18, v18, v23
	v_rcp_f32_e32 v27, v25
	v_div_fmas_f32 v20, v20, v26, v21
	v_div_fixup_f32 v19, v20, v19, v24
	v_fma_f32 v20, -v25, v27, 1.0
	v_fmac_f32_e32 v27, v20, v27
	v_div_scale_f32 v20, vcc, v23, v18, v23
	v_mul_f32_e32 v21, v20, v27
	v_fma_f32 v24, -v25, v21, v20
	v_fmac_f32_e32 v21, v24, v27
	v_fma_f32 v20, -v25, v21, v20
	v_div_fmas_f32 v20, v20, v27, v21
	v_div_fixup_f32 v18, v20, v18, v23
	v_lshlrev_b32_e32 v23, 16, v131
	v_and_b32_e32 v24, 0xffff0000, v131
	v_mul_f32_e32 v20, 0xbfb8aa3b, v23
	v_mul_f32_e32 v21, 0xbfb8aa3b, v24
	v_exp_f32_e32 v20, v20
	v_exp_f32_e32 v21, v21
	v_pk_mul_f32 v[0:1], v[0:1], v[18:19]
	v_pk_add_f32 v[18:19], v[20:21], 1.0 op_sel_hi:[1,0]
	s_nop 0
	v_div_scale_f32 v25, s[4:5], v19, v19, v24
	v_rcp_f32_e32 v26, v25
	v_lshlrev_b32_e32 v20, 16, v129
	v_and_b32_e32 v21, 0xffff0000, v129
	v_pk_fma_f32 v[2:3], v[110:111], v[20:21], v[2:3] op_sel_hi:[0,1,1]
	v_fma_f32 v20, -v25, v26, 1.0
	v_fmac_f32_e32 v26, v20, v26
	v_div_scale_f32 v20, vcc, v24, v19, v24
	v_mul_f32_e32 v21, v20, v26
	v_fma_f32 v27, -v25, v21, v20
	v_fmac_f32_e32 v21, v27, v26
	v_fma_f32 v20, -v25, v21, v20
	v_div_scale_f32 v25, s[4:5], v18, v18, v23
	v_rcp_f32_e32 v27, v25
	v_div_fmas_f32 v20, v20, v26, v21
	v_div_fixup_f32 v19, v20, v19, v24
	v_cvt_pk_bf16_f32 v0, v0, v1
	v_fma_f32 v20, -v25, v27, 1.0
	v_fmac_f32_e32 v27, v20, v27
	v_div_scale_f32 v20, vcc, v23, v18, v23
	v_mul_f32_e32 v21, v20, v27
	v_fma_f32 v24, -v25, v21, v20
	v_fmac_f32_e32 v21, v24, v27
	v_fma_f32 v20, -v25, v21, v20
	v_div_fmas_f32 v20, v20, v27, v21
	v_div_fixup_f32 v18, v20, v18, v23
	v_pk_mul_f32 v[2:3], v[2:3], v[18:19]
	s_waitcnt vmcnt(6)
	v_and_b32_e32 v20, 0xffff0000, v126
	v_cvt_pk_bf16_f32 v1, v2, v3
	v_and_b32_e32 v3, 0xffff0000, v0
	v_lshlrev_b32_e32 v2, 16, v0
	v_mul_f32_e32 v3, v3, v3
	v_lshlrev_b32_e32 v18, 16, v1
	v_fmac_f32_e32 v3, v2, v2
	v_and_b32_e32 v19, 0xffff0000, v1
	v_fmac_f32_e32 v3, v18, v18
	v_fmac_f32_e32 v3, v19, v19
	v_lshlrev_b32_e32 v19, 16, v126
	v_add_f32_e32 v18, v22, v3
	v_mul_f32_e32 v2, 0xbfb8aa3b, v19
	v_mul_f32_e32 v3, 0xbfb8aa3b, v20
	v_exp_f32_e32 v2, v2
	v_exp_f32_e32 v3, v3
	global_store_dwordx2 v[16:17], v[0:1], off offset:64
	v_pk_fma_f32 v[0:1], v[112:113], v[36:37], v[4:5] op_sel_hi:[0,1,1]
	v_pk_fma_f32 v[0:1], v[114:115], v[52:53], v[0:1] op_sel_hi:[0,1,1]
	v_pk_add_f32 v[2:3], v[2:3], 1.0 op_sel_hi:[1,0]
	v_lshlrev_b32_e32 v4, 16, v124
	v_div_scale_f32 v21, s[4:5], v3, v3, v20
	v_rcp_f32_e32 v22, v21
	v_and_b32_e32 v5, 0xffff0000, v124
	v_pk_fma_f32 v[0:1], v[110:111], v[4:5], v[0:1] op_sel_hi:[0,1,1]
	v_fma_f32 v4, -v21, v22, 1.0
	v_fmac_f32_e32 v22, v4, v22
	v_div_scale_f32 v4, vcc, v20, v3, v20
	v_mul_f32_e32 v5, v4, v22
	v_fma_f32 v23, -v21, v5, v4
	v_fmac_f32_e32 v5, v23, v22
	v_fma_f32 v4, -v21, v5, v4
	v_div_scale_f32 v21, s[4:5], v2, v2, v19
	v_rcp_f32_e32 v23, v21
	v_div_fmas_f32 v4, v4, v22, v5
	v_div_fixup_f32 v3, v4, v3, v20
	v_fma_f32 v4, -v21, v23, 1.0
	v_fmac_f32_e32 v23, v4, v23
	v_div_scale_f32 v4, vcc, v19, v2, v19
	v_mul_f32_e32 v5, v4, v23
	v_fma_f32 v20, -v21, v5, v4
	v_fmac_f32_e32 v5, v20, v23
	v_fma_f32 v4, -v21, v5, v4
	v_div_fmas_f32 v4, v4, v23, v5
	v_div_fixup_f32 v2, v4, v2, v19
	v_lshlrev_b32_e32 v19, 16, v127
	v_and_b32_e32 v20, 0xffff0000, v127
	v_mul_f32_e32 v4, 0xbfb8aa3b, v19
	v_mul_f32_e32 v5, 0xbfb8aa3b, v20
	v_exp_f32_e32 v4, v4
	v_exp_f32_e32 v5, v5
	v_pk_mul_f32 v[0:1], v[0:1], v[2:3]
	v_pk_fma_f32 v[2:3], v[112:113], v[38:39], v[6:7] op_sel_hi:[0,1,1]
	v_pk_fma_f32 v[2:3], v[114:115], v[54:55], v[2:3] op_sel_hi:[0,1,1]
	v_pk_add_f32 v[4:5], v[4:5], 1.0 op_sel_hi:[1,0]
	v_lshlrev_b32_e32 v6, 16, v125
	v_div_scale_f32 v21, s[4:5], v5, v5, v20
	v_rcp_f32_e32 v22, v21
	v_and_b32_e32 v7, 0xffff0000, v125
	v_pk_fma_f32 v[2:3], v[110:111], v[6:7], v[2:3] op_sel_hi:[0,1,1]
	v_cvt_pk_bf16_f32 v0, v0, v1
	v_fma_f32 v6, -v21, v22, 1.0
	v_fmac_f32_e32 v22, v6, v22
	v_div_scale_f32 v6, vcc, v20, v5, v20
	v_mul_f32_e32 v7, v6, v22
	v_fma_f32 v23, -v21, v7, v6
	v_fmac_f32_e32 v7, v23, v22
	v_fma_f32 v6, -v21, v7, v6
	v_div_scale_f32 v21, s[4:5], v4, v4, v19
	v_rcp_f32_e32 v23, v21
	v_div_fmas_f32 v6, v6, v22, v7
	v_div_fixup_f32 v5, v6, v5, v20
	v_fma_f32 v6, -v21, v23, 1.0
	v_fmac_f32_e32 v23, v6, v23
	v_div_scale_f32 v6, vcc, v19, v4, v19
	v_mul_f32_e32 v7, v6, v23
	v_fma_f32 v20, -v21, v7, v6
	v_fmac_f32_e32 v7, v20, v23
	v_fma_f32 v6, -v21, v7, v6
	v_div_fmas_f32 v6, v6, v23, v7
	v_div_fixup_f32 v4, v6, v4, v19
	v_pk_mul_f32 v[2:3], v[2:3], v[4:5]
	s_waitcnt vmcnt(6)
	v_lshlrev_b32_e32 v19, 16, v122
	v_cvt_pk_bf16_f32 v1, v2, v3
	v_and_b32_e32 v3, 0xffff0000, v0
	v_lshlrev_b32_e32 v2, 16, v0
	v_mul_f32_e32 v6, v3, v3
	v_and_b32_e32 v20, 0xffff0000, v122
	v_fmac_f32_e32 v6, v2, v2
	v_mul_f32_e32 v2, 0xbfb8aa3b, v19
	v_mul_f32_e32 v3, 0xbfb8aa3b, v20
	v_exp_f32_e32 v2, v2
	v_exp_f32_e32 v3, v3
	v_lshlrev_b32_e32 v4, 16, v1
	v_and_b32_e32 v5, 0xffff0000, v1
	v_fmac_f32_e32 v6, v4, v4
	v_pk_add_f32 v[2:3], v[2:3], 1.0 op_sel_hi:[1,0]
	v_fmac_f32_e32 v6, v5, v5
	v_pk_fma_f32 v[4:5], v[112:113], v[40:41], v[8:9] op_sel_hi:[0,1,1]
	v_div_scale_f32 v8, s[4:5], v3, v3, v20
	v_rcp_f32_e32 v9, v8
	v_add_f32_e32 v18, v18, v6
	v_pk_fma_f32 v[4:5], v[114:115], v[56:57], v[4:5] op_sel_hi:[0,1,1]
	v_lshlrev_b32_e32 v6, 16, v120
	v_and_b32_e32 v7, 0xffff0000, v120
	v_pk_fma_f32 v[4:5], v[110:111], v[6:7], v[4:5] op_sel_hi:[0,1,1]
	v_fma_f32 v6, -v8, v9, 1.0
	v_fmac_f32_e32 v9, v6, v9
	v_div_scale_f32 v6, vcc, v20, v3, v20
	v_mul_f32_e32 v7, v6, v9
	v_fma_f32 v21, -v8, v7, v6
	v_fmac_f32_e32 v7, v21, v9
	v_fma_f32 v6, -v8, v7, v6
	v_div_scale_f32 v8, s[4:5], v2, v2, v19
	v_rcp_f32_e32 v21, v8
	v_div_fmas_f32 v6, v6, v9, v7
	v_div_fixup_f32 v3, v6, v3, v20
	v_and_b32_e32 v20, 0xffff0000, v123
	v_fma_f32 v6, -v8, v21, 1.0
	v_fmac_f32_e32 v21, v6, v21
	v_div_scale_f32 v6, vcc, v19, v2, v19
	v_mul_f32_e32 v7, v6, v21
	v_fma_f32 v9, -v8, v7, v6
	v_fmac_f32_e32 v7, v9, v21
	v_fma_f32 v6, -v8, v7, v6
	v_div_fmas_f32 v6, v6, v21, v7
	v_div_fixup_f32 v2, v6, v2, v19
	v_lshlrev_b32_e32 v19, 16, v123
	v_mul_f32_e32 v6, 0xbfb8aa3b, v19
	v_mul_f32_e32 v7, 0xbfb8aa3b, v20
	v_exp_f32_e32 v6, v6
	v_exp_f32_e32 v7, v7
	v_pk_mul_f32 v[2:3], v[4:5], v[2:3]
	v_pk_fma_f32 v[4:5], v[112:113], v[42:43], v[10:11] op_sel_hi:[0,1,1]
	v_pk_fma_f32 v[4:5], v[114:115], v[58:59], v[4:5] op_sel_hi:[0,1,1]
	v_pk_add_f32 v[6:7], v[6:7], 1.0 op_sel_hi:[1,0]
	v_lshlrev_b32_e32 v8, 16, v121
	v_div_scale_f32 v10, s[4:5], v7, v7, v20
	v_rcp_f32_e32 v11, v10
	v_and_b32_e32 v9, 0xffff0000, v121
	v_pk_fma_f32 v[4:5], v[110:111], v[8:9], v[4:5] op_sel_hi:[0,1,1]
	v_fma_f32 v8, -v10, v11, 1.0
	v_fmac_f32_e32 v11, v8, v11
	v_div_scale_f32 v8, vcc, v20, v7, v20
	v_mul_f32_e32 v9, v8, v11
	v_fma_f32 v21, -v10, v9, v8
	v_fmac_f32_e32 v9, v21, v11
	v_fma_f32 v8, -v10, v9, v8
	v_div_scale_f32 v10, s[4:5], v6, v6, v19
	v_rcp_f32_e32 v21, v10
	v_div_fmas_f32 v8, v8, v11, v9
	v_div_fixup_f32 v7, v8, v7, v20
	v_fma_f32 v8, -v10, v21, 1.0
	v_fmac_f32_e32 v21, v8, v21
	v_div_scale_f32 v8, vcc, v19, v6, v19
	v_mul_f32_e32 v9, v8, v21
	v_fma_f32 v11, -v10, v9, v8
	v_fmac_f32_e32 v9, v11, v21
	v_fma_f32 v8, -v10, v9, v8
	v_div_fmas_f32 v8, v8, v21, v9
	v_div_fixup_f32 v6, v8, v6, v19
	v_pk_mul_f32 v[4:5], v[4:5], v[6:7]
	v_cvt_pk_bf16_f32 v6, v2, v3
	v_and_b32_e32 v3, 0xffff0000, v6
	v_lshlrev_b32_e32 v2, 16, v6
	v_mul_f32_e32 v8, v3, v3
	s_waitcnt vmcnt(5)
	v_lshlrev_b32_e32 v10, 16, v118
	v_and_b32_e32 v11, 0xffff0000, v118
	v_fmac_f32_e32 v8, v2, v2
	v_mul_f32_e32 v2, 0xbfb8aa3b, v10
	v_mul_f32_e32 v3, 0xbfb8aa3b, v11
	v_exp_f32_e32 v2, v2
	v_exp_f32_e32 v3, v3
	v_cvt_pk_bf16_f32 v7, v4, v5
	v_lshlrev_b32_e32 v4, 16, v7
	v_and_b32_e32 v5, 0xffff0000, v7
	v_fmac_f32_e32 v8, v4, v4
	v_pk_add_f32 v[2:3], v[2:3], 1.0 op_sel_hi:[1,0]
	v_fmac_f32_e32 v8, v5, v5
	v_pk_fma_f32 v[4:5], v[112:113], v[44:45], v[12:13] op_sel_hi:[0,1,1]
	v_div_scale_f32 v12, s[4:5], v3, v3, v11
	v_rcp_f32_e32 v13, v12
	v_add_f32_e32 v18, v18, v8
	v_pk_fma_f32 v[4:5], v[114:115], v[60:61], v[4:5] op_sel_hi:[0,1,1]
	v_lshlrev_b32_e32 v8, 16, v116
	v_and_b32_e32 v9, 0xffff0000, v116
	v_pk_fma_f32 v[4:5], v[110:111], v[8:9], v[4:5] op_sel_hi:[0,1,1]
	v_fma_f32 v8, -v12, v13, 1.0
	v_fmac_f32_e32 v13, v8, v13
	v_div_scale_f32 v8, vcc, v11, v3, v11
	v_mul_f32_e32 v9, v8, v13
	v_fma_f32 v19, -v12, v9, v8
	v_fmac_f32_e32 v9, v19, v13
	v_fma_f32 v8, -v12, v9, v8
	v_div_scale_f32 v12, s[4:5], v2, v2, v10
	v_rcp_f32_e32 v19, v12
	v_div_fmas_f32 v8, v8, v13, v9
	v_div_fixup_f32 v3, v8, v3, v11
	v_and_b32_e32 v13, 0xffff0000, v119
	v_fma_f32 v8, -v12, v19, 1.0
	v_fmac_f32_e32 v19, v8, v19
	v_div_scale_f32 v8, vcc, v10, v2, v10
	v_mul_f32_e32 v9, v8, v19
	v_fma_f32 v11, -v12, v9, v8
	v_fmac_f32_e32 v9, v11, v19
	v_fma_f32 v8, -v12, v9, v8
	v_div_fmas_f32 v8, v8, v19, v9
	v_lshlrev_b32_e32 v12, 16, v119
	v_div_fixup_f32 v2, v8, v2, v10
	v_mul_f32_e32 v8, 0xbfb8aa3b, v12
	v_mul_f32_e32 v9, 0xbfb8aa3b, v13
	v_exp_f32_e32 v8, v8
	v_exp_f32_e32 v9, v9
	v_pk_mul_f32 v[2:3], v[4:5], v[2:3]
	v_pk_fma_f32 v[4:5], v[112:113], v[46:47], v[14:15] op_sel_hi:[0,1,1]
	v_pk_fma_f32 v[4:5], v[114:115], v[62:63], v[4:5] op_sel_hi:[0,1,1]
	v_pk_add_f32 v[8:9], v[8:9], 1.0 op_sel_hi:[1,0]
	v_lshlrev_b32_e32 v10, 16, v117
	v_div_scale_f32 v14, s[4:5], v9, v9, v13
	v_rcp_f32_e32 v15, v14
	v_and_b32_e32 v11, 0xffff0000, v117
	v_pk_fma_f32 v[4:5], v[110:111], v[10:11], v[4:5] op_sel_hi:[0,1,1]
	v_fma_f32 v10, -v14, v15, 1.0
	v_fmac_f32_e32 v15, v10, v15
	v_div_scale_f32 v10, vcc, v13, v9, v13
	v_mul_f32_e32 v11, v10, v15
	v_fma_f32 v19, -v14, v11, v10
	v_fmac_f32_e32 v11, v19, v15
	v_fma_f32 v10, -v14, v11, v10
	v_div_scale_f32 v14, s[4:5], v8, v8, v12
	v_rcp_f32_e32 v19, v14
	v_div_fmas_f32 v10, v10, v15, v11
	v_div_fixup_f32 v9, v10, v9, v13
	v_fma_f32 v10, -v14, v19, 1.0
	v_fmac_f32_e32 v19, v10, v19
	v_div_scale_f32 v10, vcc, v12, v8, v12
	v_mul_f32_e32 v11, v10, v19
	v_fma_f32 v13, -v14, v11, v10
	v_fmac_f32_e32 v11, v13, v19
	v_fma_f32 v10, -v14, v11, v10
	v_div_fmas_f32 v10, v10, v19, v11
	v_div_fixup_f32 v8, v10, v8, v12
	v_pk_mul_f32 v[4:5], v[4:5], v[8:9]
	v_cvt_pk_bf16_f32 v8, v2, v3
	v_and_b32_e32 v3, 0xffff0000, v8
	v_cvt_pk_bf16_f32 v9, v4, v5
	v_lshlrev_b32_e32 v2, 16, v8
	v_mul_f32_e32 v3, v3, v3
	v_lshlrev_b32_e32 v4, 16, v9
	v_fmac_f32_e32 v3, v2, v2
	v_and_b32_e32 v5, 0xffff0000, v9
	v_fmac_f32_e32 v3, v4, v4
	v_fmac_f32_e32 v3, v5, v5
	v_add_f32_e32 v2, v18, v3
	v_xor_b32_e32 v3, 32, v165
	v_add_u32_e32 v4, 64, v113
	v_cmp_lt_i32_e32 vcc, v3, v4
	global_store_dwordx2 v[16:17], v[0:1], off offset:80
	global_store_dwordx2 v[16:17], v[6:7], off offset:96
	global_store_dwordx2 v[16:17], v[8:9], off offset:112
	v_cndmask_b32_e32 v3, v165, v3, vcc
	v_lshlrev_b32_e32 v3, 2, v3
	ds_bpermute_b32 v3, v3, v2
	v_cmp_eq_u32_e32 vcc, 0, v111
	s_and_saveexec_b64 s[30:31], vcc
	s_cbranch_execz .LBB0_2184
	v_lshlrev_b64 v[0:1], 5, v[108:109]
	v_lshl_add_u64 v[0:1], s[18:19], 0, v[0:1]
	s_mov_b32 s7, s21
	v_lshl_add_u64 v[0:1], v[0:1], 0, s[6:7]
	s_waitcnt lgkmcnt(0)
	v_add_f32_e32 v2, v2, v3
	global_store_dword v[0:1], v2, off
	s_branch .LBB0_2184
